# K loops: raised issue priority (s_setprio 1) for the wave in a load segment, priority 0 in MFMA segments
# baseline (speedup 1.0000x reference)
; #define PG8_STAGE(bufoff, gbase, voff) do { _Pragma("unroll") for (int _i = 0; _i < 2; ++_i) \
;         __builtin_amdgcn_global_load_lds((const unsigned*)((const char*)(gbase) + (voff)[_i]), (PG8_LAS unsigned*)(lds + (bufoff) + ldsw + _i * 8192), 16, 0, 0); } while (0)
; #define PG8_LDA(dst, b, h) do { _Pragma("unroll") for (int m = 0; m < 4; ++m) _Pragma("unroll") for (int k = 0; k < 2; ++k) dst[m][k] = *(const PG8_LAS bf16x8*)(lds + PG8_SA(b, h) + aoff + m * 2048 + k * 1024); } while (0)
; #define PG8_LDB(dst, b, h) do { _Pragma("unroll") for (int n = 0; n < 2; ++n) _Pragma("unroll") for (int k = 0; k < 2; ++k) dst[n][k] = *(const PG8_LAS bf16x8*)(lds + PG8_SB(b, h) + boff + n * 2048 + k * 1024); } while (0)
; #define PG8_WAIT_V(n) asm volatile("s_waitcnt vmcnt(" #n ")" ::: "memory")
; #define PG8_WAIT_L(n) asm volatile("s_waitcnt lgkmcnt(" #n ")" ::: "memory")
; #define PG8_BAR __builtin_amdgcn_s_barrier()
; #define PG8_SCHED __builtin_amdgcn_sched_barrier(0)
; template <class Epi, class Sched, bool ALIGN_EPI = false, bool SP2 = false>
; __device__ __forceinline__ void gemm_phase(PG8_LAS unsigned char* lds, const Gemm g, const Sched& S, const Epi& E) {
;     ...
;         const char* nA = has_next ? (const char*)g.A + (size_t)nxt.pm * tA + (size_t)nxt.pn * pnA : cA; const char* nB = has_next ? (const char*)g.Bt + (size_t)nxt.pn * tB : cB;
; #pragma nounroll
;         for (int t = 0; t < nt; t += 2) {
;             const bool last = (t == nt - 2);
;             const char* a1 = cA + (size_t)(t + 1) * kstep;
;             const char* a2 = last ? nA : cA + (size_t)(t + 2) * kstep; const char* b2 = last ? nB : cB + (size_t)(t + 2) * kstep;
;             const char* a3 = a2 + kstep; const char* b3 = b2 + kstep;
;             if (last && has_next) S.a_ready(nxt);
;             if constexpr (SP2) {
;             PG8_LDB(B0, 0, 0); PG8_LDB(B1, 0, 1); PG8_SCHED; PG8_LDA(At, 0, 0); PG8_STAGE(PG8_SA(1, 1), a1 + hA, voffA);
;             PG8_WAIT_V(8); PG8_WAIT_L(0); PG8_BAR; PG8_MMA(0, 0, At, B0); PG8_MMA(0, 1, At, B1); PG8_BAR; PG8_SCHED;
;             PG8_LDA(At, 0, 1); PG8_STAGE(PG8_SB(0, 0), b2, voffB); PG8_STAGE(PG8_SB(0, 1), b2 + hB, voffB); PG8_STAGE(PG8_SA(0, 0), a2, voffA);
;             PG8_WAIT_V(8); PG8_WAIT_L(0); PG8_BAR; PG8_MMA(1, 0, At, B0); PG8_MMA(1, 1, At, B1); PG8_BAR; PG8_SCHED;
.LBB0_189:
	s_ashr_i32 s55, s54, 31
	s_lshl_b64 s[56:57], s[54:55], 20
	s_add_u32 s56, s69, s56
	s_addc_u32 s57, s70, s57
	s_and_b64 s[58:59], s[8:9], exec
	s_cselect_b32 s11, s57, s63
	s_cselect_b32 s33, s56, s62
	s_ashr_i32 s53, s52, 31
	s_lshl_b64 s[58:59], s[52:53], 20
	s_add_u32 s58, s71, s58
	s_addc_u32 s59, s72, s59
	s_and_b64 s[66:67], s[8:9], exec
	s_cselect_b32 s53, s59, s65
	s_cselect_b32 s55, s58, s64
	s_add_u32 s62, s62, 0x80080
	s_addc_u32 s63, s63, 0
	s_add_u32 s61, s64, 0x100
	v_mov_b32_e32 v2, 0
	s_addc_u32 s96, s65, 0
	s_mov_b32 s97, -2
	v_mov_b32_e32 v3, v2
	s_setprio 1
	ds_read_b128 v[130:133], v229
	ds_read_b128 v[134:137], v229 offset:1024
	ds_read_b128 v[138:141], v229 offset:2048
	ds_read_b128 v[142:145], v229 offset:3072
	ds_read_b128 v[146:149], v230
	ds_read_b128 v[150:153], v230 offset:1024
	ds_read_b128 v[154:157], v230 offset:2048
	ds_read_b128 v[158:161], v230 offset:3072
	s_add_u32 s64, s62, 0xfff80080
	s_addc_u32 s65, s63, -1
	s_cmp_eq_u32 s97, 28
	s_cselect_b32 s67, s11, s65
	s_cselect_b32 s66, s33, s64
	s_cselect_b32 s65, s53, s96
	s_cselect_b32 s64, s55, s61
	s_add_i32 m0, s74, 0xc000
	ds_read_b128 v[162:165], v231
	ds_read_b128 v[166:169], v231 offset:1024
	ds_read_b128 v[170:173], v231 offset:2048
	ds_read_b128 v[174:177], v231 offset:3072
	ds_read_b128 v[178:181], v231 offset:4096
	ds_read_b128 v[182:185], v231 offset:5120
	ds_read_b128 v[186:189], v231 offset:6144
	ds_read_b128 v[190:193], v231 offset:7168
	global_load_lds_dwordx4 v212, s[62:63]
	s_add_i32 m0, s74, 0xe000
	s_nop 0
	global_load_lds_dwordx4 v214, s[62:63]
	s_waitcnt vmcnt(8)
	s_waitcnt lgkmcnt(0)
	s_barrier
	s_setprio 0
	v_mfma_f32_16x16x32_bf16 v[126:129], v[130:133], v[162:165], 0
	v_mfma_f32_16x16x32_bf16 v[122:125], v[138:141], v[162:165], 0
	v_mfma_f32_16x16x32_bf16 v[110:113], v[130:133], v[170:173], 0
	v_mfma_f32_16x16x32_bf16 v[106:109], v[138:141], v[170:173], 0
	v_mfma_f32_16x16x32_bf16 v[94:97], v[130:133], v[178:181], 0
	v_mfma_f32_16x16x32_bf16 v[90:93], v[138:141], v[178:181], 0
	v_mfma_f32_16x16x32_bf16 v[78:81], v[130:133], v[186:189], 0
	v_mfma_f32_16x16x32_bf16 v[74:77], v[138:141], v[186:189], 0
	v_mfma_f32_16x16x32_bf16 v[126:129], v[134:137], v[166:169], v[126:129]
	v_mfma_f32_16x16x32_bf16 v[122:125], v[142:145], v[166:169], v[122:125]
	v_mfma_f32_16x16x32_bf16 v[110:113], v[134:137], v[174:177], v[110:113]
	v_mfma_f32_16x16x32_bf16 v[106:109], v[142:145], v[174:177], v[106:109]
	v_mfma_f32_16x16x32_bf16 v[94:97], v[134:137], v[182:185], v[94:97]
	v_mfma_f32_16x16x32_bf16 v[90:93], v[142:145], v[182:185], v[90:93]
	v_mfma_f32_16x16x32_bf16 v[78:81], v[134:137], v[190:193], v[78:81]
	v_mfma_f32_16x16x32_bf16 v[74:77], v[142:145], v[190:193], v[74:77]
	v_mfma_f32_16x16x32_bf16 v[118:121], v[146:149], v[162:165], 0
	v_mfma_f32_16x16x32_bf16 v[114:117], v[154:157], v[162:165], 0
	v_mfma_f32_16x16x32_bf16 v[102:105], v[146:149], v[170:173], 0
	v_mfma_f32_16x16x32_bf16 v[98:101], v[154:157], v[170:173], 0
	v_mfma_f32_16x16x32_bf16 v[86:89], v[146:149], v[178:181], 0
	v_mfma_f32_16x16x32_bf16 v[82:85], v[154:157], v[178:181], 0
	v_mfma_f32_16x16x32_bf16 v[70:73], v[146:149], v[186:189], 0
	v_mfma_f32_16x16x32_bf16 v[66:69], v[154:157], v[186:189], 0
	v_mfma_f32_16x16x32_bf16 v[118:121], v[150:153], v[166:169], v[118:121]
	v_mfma_f32_16x16x32_bf16 v[114:117], v[158:161], v[166:169], v[114:117]
	v_mfma_f32_16x16x32_bf16 v[102:105], v[150:153], v[174:177], v[102:105]
	v_mfma_f32_16x16x32_bf16 v[98:101], v[158:161], v[174:177], v[98:101]
	v_mfma_f32_16x16x32_bf16 v[86:89], v[150:153], v[182:185], v[86:89]
	v_mfma_f32_16x16x32_bf16 v[82:85], v[158:161], v[182:185], v[82:85]
	v_mfma_f32_16x16x32_bf16 v[70:73], v[150:153], v[190:193], v[70:73]
	v_mfma_f32_16x16x32_bf16 v[66:69], v[158:161], v[190:193], v[66:69]
	s_barrier
	s_setprio 1
	s_add_i32 vcc_lo, s84, s73
	s_add_u32 s34, s64, s38
	s_addc_u32 s35, s65, s39
	s_mov_b32 m0, vcc_lo
	ds_read_b128 v[162:165], v231 offset:16384
	ds_read_b128 v[166:169], v231 offset:17408
	ds_read_b128 v[170:173], v231 offset:18432
	ds_read_b128 v[174:177], v231 offset:19456
	ds_read_b128 v[178:181], v231 offset:20480
	ds_read_b128 v[182:185], v231 offset:21504
	ds_read_b128 v[186:189], v231 offset:22528
	ds_read_b128 v[190:193], v231 offset:23552
	global_load_lds_dwordx4 v196, s[64:65]
	s_add_i32 m0, vcc_lo, 0x2000
	s_add_u32 vcc_lo, s64, 0x80000
	s_addc_u32 vcc_hi, s65, 0
	s_add_i32 s86, s85, s73
	global_load_lds_dwordx4 v200, s[64:65]
	s_mov_b32 m0, s86
	s_nop 0
	global_load_lds_dwordx4 v196, vcc
	s_add_i32 m0, s86, 0x2000
	s_nop 0
	global_load_lds_dwordx4 v200, vcc
	s_add_u32 s98, s66, s38
	s_addc_u32 s99, s67, s39
	s_mov_b32 m0, s74
	s_nop 0
	global_load_lds_dwordx4 v194, s[66:67]
	s_mov_b32 m0, s75
	s_nop 0
	global_load_lds_dwordx4 v198, s[66:67]
	s_waitcnt vmcnt(8)
	s_waitcnt lgkmcnt(0)
	s_barrier
; #define PG8_STAGE(bufoff, gbase, voff) do { _Pragma("unroll") for (int _i = 0; _i < 2; ++_i) \
;         __builtin_amdgcn_global_load_lds((const unsigned*)((const char*)(gbase) + (voff)[_i]), (PG8_LAS unsigned*)(lds + (bufoff) + ldsw + _i * 8192), 16, 0, 0); } while (0)
; #define PG8_LDA(dst, b, h) do { _Pragma("unroll") for (int m = 0; m < 4; ++m) _Pragma("unroll") for (int k = 0; k < 2; ++k) dst[m][k] = *(const PG8_LAS bf16x8*)(lds + PG8_SA(b, h) + aoff + m * 2048 + k * 1024); } while (0)
; #define PG8_LDB(dst, b, h) do { _Pragma("unroll") for (int n = 0; n < 2; ++n) _Pragma("unroll") for (int k = 0; k < 2; ++k) dst[n][k] = *(const PG8_LAS bf16x8*)(lds + PG8_SB(b, h) + boff + n * 2048 + k * 1024); } while (0)
; #define PG8_MMA(ai, bj, At, Bt) do { __builtin_amdgcn_s_setprio(1); _Pragma("unroll") for (int m = 0; m < 4; ++m) _Pragma("unroll") for (int n = 0; n < 2; ++n) _Pragma("unroll") for (int k = 0; k < 2; ++k) \
;         acc[ai][bj][m][n] = __builtin_amdgcn_mfma_f32_16x16x32_bf16(Bt[n][k], At[m][k], acc[ai][bj][m][n], 0, 0, 0); __builtin_amdgcn_s_setprio(0); } while (0)
; #define PG8_WAIT_V(n) asm volatile("s_waitcnt vmcnt(" #n ")" ::: "memory")
; #define PG8_WAIT_L(n) asm volatile("s_waitcnt lgkmcnt(" #n ")" ::: "memory")
; #define PG8_BAR __builtin_amdgcn_s_barrier()
; #define PG8_SCHED __builtin_amdgcn_sched_barrier(0)
; template <class Epi, class Sched, bool ALIGN_EPI = false, bool SP2 = false>
; __device__ __forceinline__ void gemm_phase(PG8_LAS unsigned char* lds, const Gemm g, const Sched& S, const Epi& E) {
;     ...
;             PG8_WAIT_V(8); PG8_WAIT_L(0); PG8_BAR; PG8_MMA(1, 0, At, B0); PG8_MMA(1, 1, At, B1); PG8_BAR; PG8_SCHED;
;             PG8_LDB(B0, 1, 0); PG8_LDB(B1, 1, 1); PG8_SCHED; PG8_LDA(At, 1, 0); PG8_STAGE(PG8_SA(0, 1), a2 + hA, voffA);
;             PG8_WAIT_V(8); PG8_WAIT_L(0); PG8_BAR; PG8_MMA(0, 0, At, B0); PG8_MMA(0, 1, At, B1); PG8_BAR; PG8_SCHED;
	s_setprio 0
	v_mfma_f32_16x16x32_bf16 v[62:65], v[130:133], v[162:165], 0
	v_mfma_f32_16x16x32_bf16 v[58:61], v[138:141], v[162:165], 0
	v_mfma_f32_16x16x32_bf16 v[46:49], v[130:133], v[170:173], 0
	v_mfma_f32_16x16x32_bf16 v[42:45], v[138:141], v[170:173], 0
	v_mfma_f32_16x16x32_bf16 v[30:33], v[130:133], v[178:181], 0
	v_mfma_f32_16x16x32_bf16 v[26:29], v[138:141], v[178:181], 0
	v_mfma_f32_16x16x32_bf16 v[14:17], v[130:133], v[186:189], 0
	v_mfma_f32_16x16x32_bf16 v[10:13], v[138:141], v[186:189], 0
	v_mfma_f32_16x16x32_bf16 v[62:65], v[134:137], v[166:169], v[62:65]
	v_mfma_f32_16x16x32_bf16 v[58:61], v[142:145], v[166:169], v[58:61]
	v_mfma_f32_16x16x32_bf16 v[46:49], v[134:137], v[174:177], v[46:49]
	v_mfma_f32_16x16x32_bf16 v[42:45], v[142:145], v[174:177], v[42:45]
	v_mfma_f32_16x16x32_bf16 v[30:33], v[134:137], v[182:185], v[30:33]
	v_mfma_f32_16x16x32_bf16 v[26:29], v[142:145], v[182:185], v[26:29]
	v_mfma_f32_16x16x32_bf16 v[14:17], v[134:137], v[190:193], v[14:17]
	v_mfma_f32_16x16x32_bf16 v[10:13], v[142:145], v[190:193], v[10:13]
	v_mfma_f32_16x16x32_bf16 v[54:57], v[146:149], v[162:165], 0
	v_mfma_f32_16x16x32_bf16 v[50:53], v[154:157], v[162:165], 0
	v_mfma_f32_16x16x32_bf16 v[38:41], v[146:149], v[170:173], 0
	v_mfma_f32_16x16x32_bf16 v[34:37], v[154:157], v[170:173], 0
	v_mfma_f32_16x16x32_bf16 v[22:25], v[146:149], v[178:181], 0
	v_mfma_f32_16x16x32_bf16 v[18:21], v[154:157], v[178:181], 0
	v_mfma_f32_16x16x32_bf16 v[6:9], v[146:149], v[186:189], 0
	v_mfma_f32_16x16x32_bf16 v[2:5], v[154:157], v[186:189], 0
	v_mfma_f32_16x16x32_bf16 v[54:57], v[150:153], v[166:169], v[54:57]
	v_mfma_f32_16x16x32_bf16 v[50:53], v[158:161], v[166:169], v[50:53]
	v_mfma_f32_16x16x32_bf16 v[38:41], v[150:153], v[174:177], v[38:41]
	v_mfma_f32_16x16x32_bf16 v[34:37], v[158:161], v[174:177], v[34:37]
	v_mfma_f32_16x16x32_bf16 v[22:25], v[150:153], v[182:185], v[22:25]
	v_mfma_f32_16x16x32_bf16 v[18:21], v[158:161], v[182:185], v[18:21]
	v_mfma_f32_16x16x32_bf16 v[6:9], v[150:153], v[190:193], v[6:9]
	v_mfma_f32_16x16x32_bf16 v[2:5], v[158:161], v[190:193], v[2:5]
	s_barrier
	s_setprio 1
	s_add_i32 s86, 0, 0x18000
	s_add_i32 vcc_lo, 0, 0x1c000
	v_add_u32_e32 v142, s86, v223
	v_add_u32_e32 v158, vcc_lo, v223
	ds_read_b128 v[130:133], v142
	ds_read_b128 v[134:137], v142 offset:1024
	ds_read_b128 v[138:141], v142 offset:2048
	ds_read_b128 v[142:145], v142 offset:3072
	ds_read_b128 v[146:149], v158
	ds_read_b128 v[150:153], v158 offset:1024
	ds_read_b128 v[154:157], v158 offset:2048
	ds_read_b128 v[158:161], v158 offset:3072
	s_add_u32 s66, s66, 0x80000
	s_addc_u32 s67, s67, 0
	s_mov_b32 m0, s76
	ds_read_b128 v[162:165], v231 offset:32768
	ds_read_b128 v[166:169], v231 offset:33792
	ds_read_b128 v[170:173], v231 offset:34816
	ds_read_b128 v[174:177], v231 offset:35840
	ds_read_b128 v[178:181], v231 offset:36864
	ds_read_b128 v[182:185], v231 offset:37888
	ds_read_b128 v[186:189], v231 offset:38912
	ds_read_b128 v[190:193], v231 offset:39936
	global_load_lds_dwordx4 v194, s[66:67]
	s_mov_b32 m0, s77
	s_nop 0
	global_load_lds_dwordx4 v198, s[66:67]
	s_waitcnt vmcnt(8)
	s_waitcnt lgkmcnt(0)
	s_barrier
	s_setprio 0
	v_mfma_f32_16x16x32_bf16 v[126:129], v[130:133], v[162:165], v[126:129]
	v_mfma_f32_16x16x32_bf16 v[122:125], v[138:141], v[162:165], v[122:125]
	v_mfma_f32_16x16x32_bf16 v[110:113], v[130:133], v[170:173], v[110:113]
	v_mfma_f32_16x16x32_bf16 v[106:109], v[138:141], v[170:173], v[106:109]
	v_mfma_f32_16x16x32_bf16 v[94:97], v[130:133], v[178:181], v[94:97]
	v_mfma_f32_16x16x32_bf16 v[90:93], v[138:141], v[178:181], v[90:93]
	v_mfma_f32_16x16x32_bf16 v[78:81], v[130:133], v[186:189], v[78:81]
	v_mfma_f32_16x16x32_bf16 v[74:77], v[138:141], v[186:189], v[74:77]
	v_mfma_f32_16x16x32_bf16 v[126:129], v[134:137], v[166:169], v[126:129]
	v_mfma_f32_16x16x32_bf16 v[122:125], v[142:145], v[166:169], v[122:125]
	v_mfma_f32_16x16x32_bf16 v[110:113], v[134:137], v[174:177], v[110:113]
	v_mfma_f32_16x16x32_bf16 v[106:109], v[142:145], v[174:177], v[106:109]
	v_mfma_f32_16x16x32_bf16 v[94:97], v[134:137], v[182:185], v[94:97]
	v_mfma_f32_16x16x32_bf16 v[90:93], v[142:145], v[182:185], v[90:93]
	v_mfma_f32_16x16x32_bf16 v[78:81], v[134:137], v[190:193], v[78:81]
	v_mfma_f32_16x16x32_bf16 v[74:77], v[142:145], v[190:193], v[74:77]
	v_mfma_f32_16x16x32_bf16 v[118:121], v[146:149], v[162:165], v[118:121]
	v_mfma_f32_16x16x32_bf16 v[114:117], v[154:157], v[162:165], v[114:117]
	v_mfma_f32_16x16x32_bf16 v[102:105], v[146:149], v[170:173], v[102:105]
	v_mfma_f32_16x16x32_bf16 v[98:101], v[154:157], v[170:173], v[98:101]
	v_mfma_f32_16x16x32_bf16 v[86:89], v[146:149], v[178:181], v[86:89]
	v_mfma_f32_16x16x32_bf16 v[82:85], v[154:157], v[178:181], v[82:85]
	v_mfma_f32_16x16x32_bf16 v[70:73], v[146:149], v[186:189], v[70:73]
	v_mfma_f32_16x16x32_bf16 v[66:69], v[154:157], v[186:189], v[66:69]
	v_mfma_f32_16x16x32_bf16 v[118:121], v[150:153], v[166:169], v[118:121]
	v_mfma_f32_16x16x32_bf16 v[114:117], v[158:161], v[166:169], v[114:117]
	v_mfma_f32_16x16x32_bf16 v[102:105], v[150:153], v[174:177], v[102:105]
	v_mfma_f32_16x16x32_bf16 v[98:101], v[158:161], v[174:177], v[98:101]
	v_mfma_f32_16x16x32_bf16 v[86:89], v[150:153], v[182:185], v[86:89]
	v_mfma_f32_16x16x32_bf16 v[82:85], v[158:161], v[182:185], v[82:85]
	v_mfma_f32_16x16x32_bf16 v[70:73], v[150:153], v[190:193], v[70:73]
	v_mfma_f32_16x16x32_bf16 v[66:69], v[158:161], v[190:193], v[66:69]
	s_barrier
; #define PG8_STAGE(bufoff, gbase, voff) do { _Pragma("unroll") for (int _i = 0; _i < 2; ++_i) \
;         __builtin_amdgcn_global_load_lds((const unsigned*)((const char*)(gbase) + (voff)[_i]), (PG8_LAS unsigned*)(lds + (bufoff) + ldsw + _i * 8192), 16, 0, 0); } while (0)
; #define PG8_LDA(dst, b, h) do { _Pragma("unroll") for (int m = 0; m < 4; ++m) _Pragma("unroll") for (int k = 0; k < 2; ++k) dst[m][k] = *(const PG8_LAS bf16x8*)(lds + PG8_SA(b, h) + aoff + m * 2048 + k * 1024); } while (0)
; #define PG8_LDB(dst, b, h) do { _Pragma("unroll") for (int n = 0; n < 2; ++n) _Pragma("unroll") for (int k = 0; k < 2; ++k) dst[n][k] = *(const PG8_LAS bf16x8*)(lds + PG8_SB(b, h) + boff + n * 2048 + k * 1024); } while (0)
; #define PG8_MMA(ai, bj, At, Bt) do { __builtin_amdgcn_s_setprio(1); _Pragma("unroll") for (int m = 0; m < 4; ++m) _Pragma("unroll") for (int n = 0; n < 2; ++n) _Pragma("unroll") for (int k = 0; k < 2; ++k) \
;         acc[ai][bj][m][n] = __builtin_amdgcn_mfma_f32_16x16x32_bf16(Bt[n][k], At[m][k], acc[ai][bj][m][n], 0, 0, 0); __builtin_amdgcn_s_setprio(0); } while (0)
; #define PG8_WAIT_V(n) asm volatile("s_waitcnt vmcnt(" #n ")" ::: "memory")
; #define PG8_WAIT_L(n) asm volatile("s_waitcnt lgkmcnt(" #n ")" ::: "memory")
; #define PG8_BAR __builtin_amdgcn_s_barrier()
; #define PG8_SCHED __builtin_amdgcn_sched_barrier(0)
; template <class Epi, class Sched, bool ALIGN_EPI = false, bool SP2 = false>
; __device__ __forceinline__ void gemm_phase(PG8_LAS unsigned char* lds, const Gemm g, const Sched& S, const Epi& E) {
;     ...
;             PG8_LDB(B0, 0, 0); PG8_LDB(B1, 0, 1); PG8_SCHED; PG8_LDA(At, 0, 0); PG8_STAGE(PG8_SA(1, 1), a1 + hA, voffA);
;             PG8_WAIT_V(8); PG8_WAIT_L(0); PG8_BAR; PG8_MMA(0, 0, At, B0); PG8_MMA(0, 1, At, B1); PG8_BAR; PG8_SCHED;
;     ...
;             PG8_LDA(At, 1, 1); PG8_STAGE(PG8_SB(1, 0), b3, voffB); PG8_STAGE(PG8_SB(1, 1), b3 + hB, voffB); PG8_STAGE(PG8_SA(1, 0), a3, voffA);
;             PG8_WAIT_V(8); PG8_WAIT_L(0); PG8_BAR; PG8_MMA(1, 0, At, B0); PG8_MMA(1, 1, At, B1); PG8_BAR; PG8_SCHED;
	s_setprio 1
	s_add_i32 s66, s86, s73
	s_mov_b32 m0, s66
	ds_read_b128 v[162:165], v231 offset:49152
	ds_read_b128 v[166:169], v231 offset:50176
	ds_read_b128 v[170:173], v231 offset:51200
	ds_read_b128 v[174:177], v231 offset:52224
	ds_read_b128 v[178:181], v231 offset:53248
	ds_read_b128 v[182:185], v231 offset:54272
	ds_read_b128 v[186:189], v231 offset:55296
	ds_read_b128 v[190:193], v231 offset:56320
	global_load_lds_dwordx4 v196, s[34:35]
	s_add_i32 m0, s66, 0x2000
	s_add_u32 s64, s64, 0x80080
	s_addc_u32 s65, s65, 0
	s_add_i32 s66, vcc_lo, s73
	global_load_lds_dwordx4 v200, s[34:35]
	s_mov_b32 m0, s66
	s_nop 0
	global_load_lds_dwordx4 v196, s[64:65]
	s_add_i32 m0, s66, 0x2000
	s_nop 0
	global_load_lds_dwordx4 v200, s[64:65]
	s_mov_b32 m0, s81
	s_nop 0
	global_load_lds_dwordx4 v194, s[98:99]
	s_mov_b32 m0, s82
	s_nop 0
	global_load_lds_dwordx4 v198, s[98:99]
	s_waitcnt vmcnt(8)
	s_waitcnt lgkmcnt(0)
	s_barrier
	s_setprio 0
	v_mfma_f32_16x16x32_bf16 v[62:65], v[130:133], v[162:165], v[62:65]
	v_mfma_f32_16x16x32_bf16 v[58:61], v[138:141], v[162:165], v[58:61]
	v_mfma_f32_16x16x32_bf16 v[46:49], v[130:133], v[170:173], v[46:49]
	v_mfma_f32_16x16x32_bf16 v[42:45], v[138:141], v[170:173], v[42:45]
	v_mfma_f32_16x16x32_bf16 v[30:33], v[130:133], v[178:181], v[30:33]
	v_mfma_f32_16x16x32_bf16 v[26:29], v[138:141], v[178:181], v[26:29]
	v_mfma_f32_16x16x32_bf16 v[14:17], v[130:133], v[186:189], v[14:17]
	v_mfma_f32_16x16x32_bf16 v[10:13], v[138:141], v[186:189], v[10:13]
	v_mfma_f32_16x16x32_bf16 v[62:65], v[134:137], v[166:169], v[62:65]
	v_mfma_f32_16x16x32_bf16 v[58:61], v[142:145], v[166:169], v[58:61]
	v_mfma_f32_16x16x32_bf16 v[46:49], v[134:137], v[174:177], v[46:49]
	v_mfma_f32_16x16x32_bf16 v[42:45], v[142:145], v[174:177], v[42:45]
	v_mfma_f32_16x16x32_bf16 v[30:33], v[134:137], v[182:185], v[30:33]
	v_mfma_f32_16x16x32_bf16 v[26:29], v[142:145], v[182:185], v[26:29]
	v_mfma_f32_16x16x32_bf16 v[14:17], v[134:137], v[190:193], v[14:17]
	v_mfma_f32_16x16x32_bf16 v[10:13], v[142:145], v[190:193], v[10:13]
	v_mfma_f32_16x16x32_bf16 v[54:57], v[146:149], v[162:165], v[54:57]
	v_mfma_f32_16x16x32_bf16 v[50:53], v[154:157], v[162:165], v[50:53]
	v_mfma_f32_16x16x32_bf16 v[38:41], v[146:149], v[170:173], v[38:41]
	v_mfma_f32_16x16x32_bf16 v[34:37], v[154:157], v[170:173], v[34:37]
	v_mfma_f32_16x16x32_bf16 v[22:25], v[146:149], v[178:181], v[22:25]
	v_mfma_f32_16x16x32_bf16 v[18:21], v[154:157], v[178:181], v[18:21]
	v_mfma_f32_16x16x32_bf16 v[6:9], v[146:149], v[186:189], v[6:9]
	v_mfma_f32_16x16x32_bf16 v[2:5], v[154:157], v[186:189], v[2:5]
	v_mfma_f32_16x16x32_bf16 v[54:57], v[150:153], v[166:169], v[54:57]
	v_mfma_f32_16x16x32_bf16 v[50:53], v[158:161], v[166:169], v[50:53]
	v_mfma_f32_16x16x32_bf16 v[38:41], v[150:153], v[174:177], v[38:41]
	v_mfma_f32_16x16x32_bf16 v[34:37], v[158:161], v[174:177], v[34:37]
	v_mfma_f32_16x16x32_bf16 v[22:25], v[150:153], v[182:185], v[22:25]
	v_mfma_f32_16x16x32_bf16 v[18:21], v[158:161], v[182:185], v[18:21]
	v_mfma_f32_16x16x32_bf16 v[6:9], v[150:153], v[190:193], v[6:9]
	v_mfma_f32_16x16x32_bf16 v[2:5], v[158:161], v[190:193], v[2:5]
	s_barrier
	s_add_i32 s97, s97, 2
	s_add_u32 s62, s62, 0x100
	s_addc_u32 s63, s63, 0
	s_add_u32 s61, s61, 0x100
	s_addc_u32 s96, s96, 0
	s_cmp_gt_u32 s97, 29
.LBB0_190:
	s_setprio 1
	ds_read_b128 v[130:133], v229
	ds_read_b128 v[134:137], v229 offset:1024
	ds_read_b128 v[138:141], v229 offset:2048
	ds_read_b128 v[142:145], v229 offset:3072
	ds_read_b128 v[146:149], v230
	ds_read_b128 v[150:153], v230 offset:1024
	ds_read_b128 v[154:157], v230 offset:2048
	ds_read_b128 v[158:161], v230 offset:3072
	s_add_u32 s64, s62, 0xfff80080
	s_addc_u32 s65, s63, -1
	s_cmp_eq_u32 s97, 28
	s_cselect_b32 s67, s11, s65
	s_cselect_b32 s66, s33, s64
	s_cselect_b32 s65, s53, s96
	s_cselect_b32 s64, s55, s61
	s_add_i32 m0, s74, 0xc000
	ds_read_b128 v[162:165], v231
	ds_read_b128 v[166:169], v231 offset:1024
	ds_read_b128 v[170:173], v231 offset:2048
	ds_read_b128 v[174:177], v231 offset:3072
	ds_read_b128 v[178:181], v231 offset:4096
	ds_read_b128 v[182:185], v231 offset:5120
	ds_read_b128 v[186:189], v231 offset:6144
	ds_read_b128 v[190:193], v231 offset:7168
	global_load_lds_dwordx4 v212, s[62:63]
	s_add_i32 m0, s74, 0xe000
	s_nop 0
	global_load_lds_dwordx4 v214, s[62:63]
	s_waitcnt vmcnt(8)
	s_waitcnt lgkmcnt(0)
	s_barrier
	s_setprio 0
	v_mfma_f32_16x16x32_bf16 v[126:129], v[130:133], v[162:165], v[126:129]
	v_mfma_f32_16x16x32_bf16 v[122:125], v[138:141], v[162:165], v[122:125]
	v_mfma_f32_16x16x32_bf16 v[110:113], v[130:133], v[170:173], v[110:113]
	v_mfma_f32_16x16x32_bf16 v[106:109], v[138:141], v[170:173], v[106:109]
	v_mfma_f32_16x16x32_bf16 v[94:97], v[130:133], v[178:181], v[94:97]
	v_mfma_f32_16x16x32_bf16 v[90:93], v[138:141], v[178:181], v[90:93]
	v_mfma_f32_16x16x32_bf16 v[78:81], v[130:133], v[186:189], v[78:81]
	v_mfma_f32_16x16x32_bf16 v[74:77], v[138:141], v[186:189], v[74:77]
	v_mfma_f32_16x16x32_bf16 v[126:129], v[134:137], v[166:169], v[126:129]
	v_mfma_f32_16x16x32_bf16 v[122:125], v[142:145], v[166:169], v[122:125]
	v_mfma_f32_16x16x32_bf16 v[110:113], v[134:137], v[174:177], v[110:113]
	v_mfma_f32_16x16x32_bf16 v[106:109], v[142:145], v[174:177], v[106:109]
	v_mfma_f32_16x16x32_bf16 v[94:97], v[134:137], v[182:185], v[94:97]
	v_mfma_f32_16x16x32_bf16 v[90:93], v[142:145], v[182:185], v[90:93]
	v_mfma_f32_16x16x32_bf16 v[78:81], v[134:137], v[190:193], v[78:81]
	v_mfma_f32_16x16x32_bf16 v[74:77], v[142:145], v[190:193], v[74:77]
	v_mfma_f32_16x16x32_bf16 v[118:121], v[146:149], v[162:165], v[118:121]
	v_mfma_f32_16x16x32_bf16 v[114:117], v[154:157], v[162:165], v[114:117]
	v_mfma_f32_16x16x32_bf16 v[102:105], v[146:149], v[170:173], v[102:105]
	v_mfma_f32_16x16x32_bf16 v[98:101], v[154:157], v[170:173], v[98:101]
	v_mfma_f32_16x16x32_bf16 v[86:89], v[146:149], v[178:181], v[86:89]
	v_mfma_f32_16x16x32_bf16 v[82:85], v[154:157], v[178:181], v[82:85]
	v_mfma_f32_16x16x32_bf16 v[70:73], v[146:149], v[186:189], v[70:73]
	v_mfma_f32_16x16x32_bf16 v[66:69], v[154:157], v[186:189], v[66:69]
	v_mfma_f32_16x16x32_bf16 v[118:121], v[150:153], v[166:169], v[118:121]
	v_mfma_f32_16x16x32_bf16 v[114:117], v[158:161], v[166:169], v[114:117]
	v_mfma_f32_16x16x32_bf16 v[102:105], v[150:153], v[174:177], v[102:105]
	v_mfma_f32_16x16x32_bf16 v[98:101], v[158:161], v[174:177], v[98:101]
	v_mfma_f32_16x16x32_bf16 v[86:89], v[150:153], v[182:185], v[86:89]
	v_mfma_f32_16x16x32_bf16 v[82:85], v[158:161], v[182:185], v[82:85]
	v_mfma_f32_16x16x32_bf16 v[70:73], v[150:153], v[190:193], v[70:73]
	v_mfma_f32_16x16x32_bf16 v[66:69], v[158:161], v[190:193], v[66:69]
	s_barrier
; #define PG8_STAGE(bufoff, gbase, voff) do { _Pragma("unroll") for (int _i = 0; _i < 2; ++_i) \
;         __builtin_amdgcn_global_load_lds((const unsigned*)((const char*)(gbase) + (voff)[_i]), (PG8_LAS unsigned*)(lds + (bufoff) + ldsw + _i * 8192), 16, 0, 0); } while (0)
; #define PG8_LDA(dst, b, h) do { _Pragma("unroll") for (int m = 0; m < 4; ++m) _Pragma("unroll") for (int k = 0; k < 2; ++k) dst[m][k] = *(const PG8_LAS bf16x8*)(lds + PG8_SA(b, h) + aoff + m * 2048 + k * 1024); } while (0)
; #define PG8_LDB(dst, b, h) do { _Pragma("unroll") for (int n = 0; n < 2; ++n) _Pragma("unroll") for (int k = 0; k < 2; ++k) dst[n][k] = *(const PG8_LAS bf16x8*)(lds + PG8_SB(b, h) + boff + n * 2048 + k * 1024); } while (0)
; #define PG8_MMA(ai, bj, At, Bt) do { __builtin_amdgcn_s_setprio(1); _Pragma("unroll") for (int m = 0; m < 4; ++m) _Pragma("unroll") for (int n = 0; n < 2; ++n) _Pragma("unroll") for (int k = 0; k < 2; ++k) \
;         acc[ai][bj][m][n] = __builtin_amdgcn_mfma_f32_16x16x32_bf16(Bt[n][k], At[m][k], acc[ai][bj][m][n], 0, 0, 0); __builtin_amdgcn_s_setprio(0); } while (0)
; #define PG8_WAIT_V(n) asm volatile("s_waitcnt vmcnt(" #n ")" ::: "memory")
; #define PG8_WAIT_L(n) asm volatile("s_waitcnt lgkmcnt(" #n ")" ::: "memory")
; #define PG8_BAR __builtin_amdgcn_s_barrier()
; #define PG8_SCHED __builtin_amdgcn_sched_barrier(0)
; template <class Epi, class Sched, bool ALIGN_EPI = false, bool SP2 = false>
; __device__ __forceinline__ void gemm_phase(PG8_LAS unsigned char* lds, const Gemm g, const Sched& S, const Epi& E) {
;     ...
;             PG8_LDA(At, 0, 1); PG8_STAGE(PG8_SB(0, 0), b2, voffB); PG8_STAGE(PG8_SB(0, 1), b2 + hB, voffB); PG8_STAGE(PG8_SA(0, 0), a2, voffA);
;             PG8_WAIT_V(8); PG8_WAIT_L(0); PG8_BAR; PG8_MMA(1, 0, At, B0); PG8_MMA(1, 1, At, B1); PG8_BAR; PG8_SCHED;
;             PG8_LDB(B0, 1, 0); PG8_LDB(B1, 1, 1); PG8_SCHED; PG8_LDA(At, 1, 0); PG8_STAGE(PG8_SA(0, 1), a2 + hA, voffA);
	s_setprio 1
	s_add_i32 vcc_lo, s84, s73
	s_add_u32 s34, s64, s38
	s_addc_u32 s35, s65, s39
	s_mov_b32 m0, vcc_lo
	ds_read_b128 v[162:165], v231 offset:16384
	ds_read_b128 v[166:169], v231 offset:17408
	ds_read_b128 v[170:173], v231 offset:18432
	ds_read_b128 v[174:177], v231 offset:19456
	ds_read_b128 v[178:181], v231 offset:20480
	ds_read_b128 v[182:185], v231 offset:21504
	ds_read_b128 v[186:189], v231 offset:22528
	ds_read_b128 v[190:193], v231 offset:23552
	global_load_lds_dwordx4 v196, s[64:65]
	s_add_i32 m0, vcc_lo, 0x2000
	s_add_u32 vcc_lo, s64, 0x80000
	s_addc_u32 vcc_hi, s65, 0
	s_add_i32 s86, s85, s73
	global_load_lds_dwordx4 v200, s[64:65]
	s_mov_b32 m0, s86
	s_nop 0
	global_load_lds_dwordx4 v196, vcc
	s_add_i32 m0, s86, 0x2000
	s_nop 0
	global_load_lds_dwordx4 v200, vcc
	s_add_u32 s98, s66, s38
	s_addc_u32 s99, s67, s39
	s_mov_b32 m0, s74
	s_nop 0
	global_load_lds_dwordx4 v194, s[66:67]
	s_mov_b32 m0, s75
	s_nop 0
	global_load_lds_dwordx4 v198, s[66:67]
	s_waitcnt vmcnt(8)
	s_waitcnt lgkmcnt(0)
	s_barrier
	s_setprio 0
	v_mfma_f32_16x16x32_bf16 v[62:65], v[130:133], v[162:165], v[62:65]
	v_mfma_f32_16x16x32_bf16 v[58:61], v[138:141], v[162:165], v[58:61]
	v_mfma_f32_16x16x32_bf16 v[46:49], v[130:133], v[170:173], v[46:49]
	v_mfma_f32_16x16x32_bf16 v[42:45], v[138:141], v[170:173], v[42:45]
	v_mfma_f32_16x16x32_bf16 v[30:33], v[130:133], v[178:181], v[30:33]
	v_mfma_f32_16x16x32_bf16 v[26:29], v[138:141], v[178:181], v[26:29]
	v_mfma_f32_16x16x32_bf16 v[14:17], v[130:133], v[186:189], v[14:17]
	v_mfma_f32_16x16x32_bf16 v[10:13], v[138:141], v[186:189], v[10:13]
	v_mfma_f32_16x16x32_bf16 v[62:65], v[134:137], v[166:169], v[62:65]
	v_mfma_f32_16x16x32_bf16 v[58:61], v[142:145], v[166:169], v[58:61]
	v_mfma_f32_16x16x32_bf16 v[46:49], v[134:137], v[174:177], v[46:49]
	v_mfma_f32_16x16x32_bf16 v[42:45], v[142:145], v[174:177], v[42:45]
	v_mfma_f32_16x16x32_bf16 v[30:33], v[134:137], v[182:185], v[30:33]
	v_mfma_f32_16x16x32_bf16 v[26:29], v[142:145], v[182:185], v[26:29]
	v_mfma_f32_16x16x32_bf16 v[14:17], v[134:137], v[190:193], v[14:17]
	v_mfma_f32_16x16x32_bf16 v[10:13], v[142:145], v[190:193], v[10:13]
	v_mfma_f32_16x16x32_bf16 v[54:57], v[146:149], v[162:165], v[54:57]
	v_mfma_f32_16x16x32_bf16 v[50:53], v[154:157], v[162:165], v[50:53]
	v_mfma_f32_16x16x32_bf16 v[38:41], v[146:149], v[170:173], v[38:41]
	v_mfma_f32_16x16x32_bf16 v[34:37], v[154:157], v[170:173], v[34:37]
	v_mfma_f32_16x16x32_bf16 v[22:25], v[146:149], v[178:181], v[22:25]
	v_mfma_f32_16x16x32_bf16 v[18:21], v[154:157], v[178:181], v[18:21]
	v_mfma_f32_16x16x32_bf16 v[6:9], v[146:149], v[186:189], v[6:9]
	v_mfma_f32_16x16x32_bf16 v[2:5], v[154:157], v[186:189], v[2:5]
	v_mfma_f32_16x16x32_bf16 v[54:57], v[150:153], v[166:169], v[54:57]
	v_mfma_f32_16x16x32_bf16 v[50:53], v[158:161], v[166:169], v[50:53]
	v_mfma_f32_16x16x32_bf16 v[38:41], v[150:153], v[174:177], v[38:41]
	v_mfma_f32_16x16x32_bf16 v[34:37], v[158:161], v[174:177], v[34:37]
	v_mfma_f32_16x16x32_bf16 v[22:25], v[150:153], v[182:185], v[22:25]
	v_mfma_f32_16x16x32_bf16 v[18:21], v[158:161], v[182:185], v[18:21]
	v_mfma_f32_16x16x32_bf16 v[6:9], v[150:153], v[190:193], v[6:9]
	v_mfma_f32_16x16x32_bf16 v[2:5], v[158:161], v[190:193], v[2:5]
	s_barrier
	s_setprio 1
	s_add_i32 s86, 0, 0x18000
	s_add_i32 vcc_lo, 0, 0x1c000
	v_add_u32_e32 v142, s86, v223
	v_add_u32_e32 v158, vcc_lo, v223
	ds_read_b128 v[130:133], v142
	ds_read_b128 v[134:137], v142 offset:1024
	ds_read_b128 v[138:141], v142 offset:2048
	ds_read_b128 v[142:145], v142 offset:3072
	ds_read_b128 v[146:149], v158
	ds_read_b128 v[150:153], v158 offset:1024
	ds_read_b128 v[154:157], v158 offset:2048
	ds_read_b128 v[158:161], v158 offset:3072
	s_add_u32 s66, s66, 0x80000
	s_addc_u32 s67, s67, 0
	s_mov_b32 m0, s76
	ds_read_b128 v[162:165], v231 offset:32768
	ds_read_b128 v[166:169], v231 offset:33792
	ds_read_b128 v[170:173], v231 offset:34816
	ds_read_b128 v[174:177], v231 offset:35840
	ds_read_b128 v[178:181], v231 offset:36864
	ds_read_b128 v[182:185], v231 offset:37888
	ds_read_b128 v[186:189], v231 offset:38912
	ds_read_b128 v[190:193], v231 offset:39936
	global_load_lds_dwordx4 v194, s[66:67]
	s_mov_b32 m0, s77
	s_nop 0
	global_load_lds_dwordx4 v198, s[66:67]
	s_waitcnt vmcnt(8)
	s_waitcnt lgkmcnt(0)
	s_barrier
; #define PG8_STAGE(bufoff, gbase, voff) do { _Pragma("unroll") for (int _i = 0; _i < 2; ++_i) \
;         __builtin_amdgcn_global_load_lds((const unsigned*)((const char*)(gbase) + (voff)[_i]), (PG8_LAS unsigned*)(lds + (bufoff) + ldsw + _i * 8192), 16, 0, 0); } while (0)
; #define PG8_LDA(dst, b, h) do { _Pragma("unroll") for (int m = 0; m < 4; ++m) _Pragma("unroll") for (int k = 0; k < 2; ++k) dst[m][k] = *(const PG8_LAS bf16x8*)(lds + PG8_SA(b, h) + aoff + m * 2048 + k * 1024); } while (0)
; #define PG8_LDB(dst, b, h) do { _Pragma("unroll") for (int n = 0; n < 2; ++n) _Pragma("unroll") for (int k = 0; k < 2; ++k) dst[n][k] = *(const PG8_LAS bf16x8*)(lds + PG8_SB(b, h) + boff + n * 2048 + k * 1024); } while (0)
; #define PG8_MMA(ai, bj, At, Bt) do { __builtin_amdgcn_s_setprio(1); _Pragma("unroll") for (int m = 0; m < 4; ++m) _Pragma("unroll") for (int n = 0; n < 2; ++n) _Pragma("unroll") for (int k = 0; k < 2; ++k) \
;         acc[ai][bj][m][n] = __builtin_amdgcn_mfma_f32_16x16x32_bf16(Bt[n][k], At[m][k], acc[ai][bj][m][n], 0, 0, 0); __builtin_amdgcn_s_setprio(0); } while (0)
; #define PG8_WAIT_V(n) asm volatile("s_waitcnt vmcnt(" #n ")" ::: "memory")
; #define PG8_WAIT_L(n) asm volatile("s_waitcnt lgkmcnt(" #n ")" ::: "memory")
; #define PG8_BAR __builtin_amdgcn_s_barrier()
; #define PG8_SCHED __builtin_amdgcn_sched_barrier(0)
; template <class Epi, class Sched, bool ALIGN_EPI = false, bool SP2 = false>
; __device__ __forceinline__ void gemm_phase(PG8_LAS unsigned char* lds, const Gemm g, const Sched& S, const Epi& E) {
;     ...
;             PG8_LDB(B0, 1, 0); PG8_LDB(B1, 1, 1); PG8_SCHED; PG8_LDA(At, 1, 0); PG8_STAGE(PG8_SA(0, 1), a2 + hA, voffA);
;             PG8_WAIT_V(8); PG8_WAIT_L(0); PG8_BAR; PG8_MMA(0, 0, At, B0); PG8_MMA(0, 1, At, B1); PG8_BAR; PG8_SCHED;
;             PG8_LDA(At, 1, 1); PG8_STAGE(PG8_SB(1, 0), b3, voffB); PG8_STAGE(PG8_SB(1, 1), b3 + hB, voffB); PG8_STAGE(PG8_SA(1, 0), a3, voffA);
;             PG8_WAIT_V(8); PG8_WAIT_L(0); PG8_BAR; PG8_MMA(1, 0, At, B0); PG8_MMA(1, 1, At, B1); PG8_BAR; PG8_SCHED;
	s_setprio 0
	v_mfma_f32_16x16x32_bf16 v[126:129], v[130:133], v[162:165], v[126:129]
	v_mfma_f32_16x16x32_bf16 v[122:125], v[138:141], v[162:165], v[122:125]
	v_mfma_f32_16x16x32_bf16 v[110:113], v[130:133], v[170:173], v[110:113]
	v_mfma_f32_16x16x32_bf16 v[106:109], v[138:141], v[170:173], v[106:109]
	v_mfma_f32_16x16x32_bf16 v[94:97], v[130:133], v[178:181], v[94:97]
	v_mfma_f32_16x16x32_bf16 v[90:93], v[138:141], v[178:181], v[90:93]
	v_mfma_f32_16x16x32_bf16 v[78:81], v[130:133], v[186:189], v[78:81]
	v_mfma_f32_16x16x32_bf16 v[74:77], v[138:141], v[186:189], v[74:77]
	v_mfma_f32_16x16x32_bf16 v[126:129], v[134:137], v[166:169], v[126:129]
	v_mfma_f32_16x16x32_bf16 v[122:125], v[142:145], v[166:169], v[122:125]
	v_mfma_f32_16x16x32_bf16 v[110:113], v[134:137], v[174:177], v[110:113]
	v_mfma_f32_16x16x32_bf16 v[106:109], v[142:145], v[174:177], v[106:109]
	v_mfma_f32_16x16x32_bf16 v[94:97], v[134:137], v[182:185], v[94:97]
	v_mfma_f32_16x16x32_bf16 v[90:93], v[142:145], v[182:185], v[90:93]
	v_mfma_f32_16x16x32_bf16 v[78:81], v[134:137], v[190:193], v[78:81]
	v_mfma_f32_16x16x32_bf16 v[74:77], v[142:145], v[190:193], v[74:77]
	v_mfma_f32_16x16x32_bf16 v[118:121], v[146:149], v[162:165], v[118:121]
	v_mfma_f32_16x16x32_bf16 v[114:117], v[154:157], v[162:165], v[114:117]
	v_mfma_f32_16x16x32_bf16 v[102:105], v[146:149], v[170:173], v[102:105]
	v_mfma_f32_16x16x32_bf16 v[98:101], v[154:157], v[170:173], v[98:101]
	v_mfma_f32_16x16x32_bf16 v[86:89], v[146:149], v[178:181], v[86:89]
	v_mfma_f32_16x16x32_bf16 v[82:85], v[154:157], v[178:181], v[82:85]
	v_mfma_f32_16x16x32_bf16 v[70:73], v[146:149], v[186:189], v[70:73]
	v_mfma_f32_16x16x32_bf16 v[66:69], v[154:157], v[186:189], v[66:69]
	v_mfma_f32_16x16x32_bf16 v[118:121], v[150:153], v[166:169], v[118:121]
	v_mfma_f32_16x16x32_bf16 v[114:117], v[158:161], v[166:169], v[114:117]
	v_mfma_f32_16x16x32_bf16 v[102:105], v[150:153], v[174:177], v[102:105]
	v_mfma_f32_16x16x32_bf16 v[98:101], v[158:161], v[174:177], v[98:101]
	v_mfma_f32_16x16x32_bf16 v[86:89], v[150:153], v[182:185], v[86:89]
	v_mfma_f32_16x16x32_bf16 v[82:85], v[158:161], v[182:185], v[82:85]
	v_mfma_f32_16x16x32_bf16 v[70:73], v[150:153], v[190:193], v[70:73]
	v_mfma_f32_16x16x32_bf16 v[66:69], v[158:161], v[190:193], v[66:69]
	s_barrier
	s_setprio 1
	s_add_i32 s66, s86, s73
	s_mov_b32 m0, s66
	ds_read_b128 v[162:165], v231 offset:49152
	ds_read_b128 v[166:169], v231 offset:50176
	ds_read_b128 v[170:173], v231 offset:51200
	ds_read_b128 v[174:177], v231 offset:52224
	ds_read_b128 v[178:181], v231 offset:53248
	ds_read_b128 v[182:185], v231 offset:54272
	ds_read_b128 v[186:189], v231 offset:55296
	ds_read_b128 v[190:193], v231 offset:56320
	global_load_lds_dwordx4 v196, s[34:35]
	s_add_i32 m0, s66, 0x2000
	s_add_u32 s64, s64, 0x80080
	s_addc_u32 s65, s65, 0
	s_add_i32 s66, vcc_lo, s73
	global_load_lds_dwordx4 v200, s[34:35]
	s_mov_b32 m0, s66
	s_nop 0
	global_load_lds_dwordx4 v196, s[64:65]
	s_add_i32 m0, s66, 0x2000
	s_nop 0
	global_load_lds_dwordx4 v200, s[64:65]
	s_mov_b32 m0, s81
	s_nop 0
	global_load_lds_dwordx4 v194, s[98:99]
	s_mov_b32 m0, s82
	s_nop 0
	global_load_lds_dwordx4 v198, s[98:99]
	s_waitcnt vmcnt(8)
	s_waitcnt lgkmcnt(0)
	s_barrier
	s_setprio 0
	v_mfma_f32_16x16x32_bf16 v[62:65], v[130:133], v[162:165], v[62:65]
	v_mfma_f32_16x16x32_bf16 v[58:61], v[138:141], v[162:165], v[58:61]
	v_mfma_f32_16x16x32_bf16 v[46:49], v[130:133], v[170:173], v[46:49]
	v_mfma_f32_16x16x32_bf16 v[42:45], v[138:141], v[170:173], v[42:45]
	v_mfma_f32_16x16x32_bf16 v[30:33], v[130:133], v[178:181], v[30:33]
	v_mfma_f32_16x16x32_bf16 v[26:29], v[138:141], v[178:181], v[26:29]
	v_mfma_f32_16x16x32_bf16 v[14:17], v[130:133], v[186:189], v[14:17]
	v_mfma_f32_16x16x32_bf16 v[10:13], v[138:141], v[186:189], v[10:13]
	v_mfma_f32_16x16x32_bf16 v[62:65], v[134:137], v[166:169], v[62:65]
	v_mfma_f32_16x16x32_bf16 v[58:61], v[142:145], v[166:169], v[58:61]
	v_mfma_f32_16x16x32_bf16 v[46:49], v[134:137], v[174:177], v[46:49]
	v_mfma_f32_16x16x32_bf16 v[42:45], v[142:145], v[174:177], v[42:45]
	v_mfma_f32_16x16x32_bf16 v[30:33], v[134:137], v[182:185], v[30:33]
	v_mfma_f32_16x16x32_bf16 v[26:29], v[142:145], v[182:185], v[26:29]
	v_mfma_f32_16x16x32_bf16 v[14:17], v[134:137], v[190:193], v[14:17]
	v_mfma_f32_16x16x32_bf16 v[10:13], v[142:145], v[190:193], v[10:13]
	v_mfma_f32_16x16x32_bf16 v[54:57], v[146:149], v[162:165], v[54:57]
	v_mfma_f32_16x16x32_bf16 v[50:53], v[154:157], v[162:165], v[50:53]
	v_mfma_f32_16x16x32_bf16 v[38:41], v[146:149], v[170:173], v[38:41]
	v_mfma_f32_16x16x32_bf16 v[34:37], v[154:157], v[170:173], v[34:37]
	v_mfma_f32_16x16x32_bf16 v[22:25], v[146:149], v[178:181], v[22:25]
	v_mfma_f32_16x16x32_bf16 v[18:21], v[154:157], v[178:181], v[18:21]
	v_mfma_f32_16x16x32_bf16 v[6:9], v[146:149], v[186:189], v[6:9]
	v_mfma_f32_16x16x32_bf16 v[2:5], v[154:157], v[186:189], v[2:5]
	v_mfma_f32_16x16x32_bf16 v[54:57], v[150:153], v[166:169], v[54:57]
	v_mfma_f32_16x16x32_bf16 v[50:53], v[158:161], v[166:169], v[50:53]
	v_mfma_f32_16x16x32_bf16 v[38:41], v[150:153], v[174:177], v[38:41]
	v_mfma_f32_16x16x32_bf16 v[34:37], v[158:161], v[174:177], v[34:37]
	v_mfma_f32_16x16x32_bf16 v[22:25], v[150:153], v[182:185], v[22:25]
	v_mfma_f32_16x16x32_bf16 v[18:21], v[158:161], v[182:185], v[18:21]
	v_mfma_f32_16x16x32_bf16 v[6:9], v[150:153], v[190:193], v[6:9]
	v_mfma_f32_16x16x32_bf16 v[2:5], v[158:161], v[190:193], v[2:5]
	s_barrier
	s_add_i32 s97, s97, 2
	s_add_u32 s62, s62, 0x100
	s_addc_u32 s63, s63, 0
	s_add_u32 s61, s61, 0x100
	s_addc_u32 s96, s96, 0
	s_cmp_gt_u32 s97, 29
	s_cbranch_scc0 .LBB0_190
	s_and_b64 vcc, exec, s[40:41]
	s_cbranch_vccz .LBB0_211
	s_barrier
	v_lshl_add_u32 v220, s60, 8, v1
	s_cmp_gt_i32 s10, 15
	s_mov_b64 s[60:61], -1
	s_cbranch_scc1 .LBB0_212

; #define PG8_STAGE(bufoff, gbase, voff) do { _Pragma("unroll") for (int _i = 0; _i < 2; ++_i) \
;         __builtin_amdgcn_global_load_lds((const unsigned*)((const char*)(gbase) + (voff)[_i]), (PG8_LAS unsigned*)(lds + (bufoff) + ldsw + _i * 8192), 16, 0, 0); } while (0)
; #define PG8_LDA(dst, b, h) do { _Pragma("unroll") for (int m = 0; m < 4; ++m) _Pragma("unroll") for (int k = 0; k < 2; ++k) dst[m][k] = *(const PG8_LAS bf16x8*)(lds + PG8_SA(b, h) + aoff + m * 2048 + k * 1024); } while (0)
; #define PG8_LDB(dst, b, h) do { _Pragma("unroll") for (int n = 0; n < 2; ++n) _Pragma("unroll") for (int k = 0; k < 2; ++k) dst[n][k] = *(const PG8_LAS bf16x8*)(lds + PG8_SB(b, h) + boff + n * 2048 + k * 1024); } while (0)
; #define PG8_WAIT_V(n) asm volatile("s_waitcnt vmcnt(" #n ")" ::: "memory")
; #define PG8_WAIT_L(n) asm volatile("s_waitcnt lgkmcnt(" #n ")" ::: "memory")
; #define PG8_BAR __builtin_amdgcn_s_barrier()
; #define PG8_SCHED __builtin_amdgcn_sched_barrier(0)
; template <class Epi, class Sched, bool ALIGN_EPI = false, bool SP2 = false>
; __device__ __forceinline__ void gemm_phase(PG8_LAS unsigned char* lds, const Gemm g, const Sched& S, const Epi& E) {
;     ...
;         const char* nA = has_next ? (const char*)g.A + (size_t)nxt.pm * tA + (size_t)nxt.pn * pnA : cA; const char* nB = has_next ? (const char*)g.Bt + (size_t)nxt.pn * tB : cB;
; #pragma nounroll
;         for (int t = 0; t < nt; t += 2) {
;             const bool last = (t == nt - 2);
;             const char* a1 = cA + (size_t)(t + 1) * kstep;
;             const char* a2 = last ? nA : cA + (size_t)(t + 2) * kstep; const char* b2 = last ? nB : cB + (size_t)(t + 2) * kstep;
;             const char* a3 = a2 + kstep; const char* b3 = b2 + kstep;
;             if (last && has_next) S.a_ready(nxt);
;             if constexpr (SP2) {
;             PG8_LDB(B0, 0, 0); PG8_LDB(B1, 0, 1); PG8_SCHED; PG8_LDA(At, 0, 0); PG8_STAGE(PG8_SA(1, 1), a1 + hA, voffA);
;             PG8_WAIT_V(8); PG8_WAIT_L(0); PG8_BAR; PG8_MMA(0, 0, At, B0); PG8_MMA(0, 1, At, B1); PG8_BAR; PG8_SCHED;
;             PG8_LDA(At, 0, 1); PG8_STAGE(PG8_SB(0, 0), b2, voffB); PG8_STAGE(PG8_SB(0, 1), b2 + hB, voffB); PG8_STAGE(PG8_SA(0, 0), a2, voffA);
;             PG8_WAIT_V(8); PG8_WAIT_L(0); PG8_BAR; PG8_MMA(1, 0, At, B0); PG8_MMA(1, 1, At, B1); PG8_BAR; PG8_SCHED;
.LBB0_867:
	s_ashr_i32 s23, s22, 31
	s_lshl_b64 s[24:25], s[22:23], 19
	s_add_u32 s24, s33, s24
	s_addc_u32 s25, s48, s25
	s_and_b64 s[38:39], s[4:5], exec
	s_cselect_b32 s23, s25, s43
	s_cselect_b32 s67, s24, s42
	s_ashr_i32 s21, s20, 31
	s_lshl_b64 s[38:39], s[20:21], 19
	s_add_u32 s38, s49, s38
	s_addc_u32 s39, s51, s39
	s_and_b64 s[46:47], s[4:5], exec
	s_cselect_b32 s21, s39, s45
	s_cselect_b32 s69, s38, s44
	s_add_u32 s42, s42, 0x40080
	s_addc_u32 s43, s43, 0
	s_add_u32 s70, s44, 0x100
	v_mov_b32_e32 v2, 0
	s_addc_u32 s71, s45, 0
	s_mov_b32 s72, -2
	v_mov_b32_e32 v3, v2
	s_setprio 1
	ds_read_b128 v[146:149], v156
	ds_read_b128 v[150:153], v156 offset:1024
	ds_read_b128 v[160:163], v156 offset:2048
	ds_read_b128 v[164:167], v156 offset:3072
	ds_read_b128 v[168:171], v157
	ds_read_b128 v[172:175], v157 offset:1024
	ds_read_b128 v[176:179], v157 offset:2048
	ds_read_b128 v[180:183], v157 offset:3072
	s_add_u32 s18, s42, 0xfffc0080
	s_addc_u32 s19, s43, -1
	s_cmp_eq_u32 s72, 12
	s_cselect_b32 s47, s23, s19
	s_cselect_b32 s46, s67, s18
	s_cselect_b32 s45, s21, s71
	s_cselect_b32 s44, s69, s70
	s_add_i32 m0, s41, 0xc000
	ds_read_b128 v[184:187], v158
	ds_read_b128 v[188:191], v158 offset:1024
	ds_read_b128 v[192:195], v158 offset:2048
	ds_read_b128 v[196:199], v158 offset:3072
	ds_read_b128 v[200:203], v158 offset:4096
	ds_read_b128 v[204:207], v158 offset:5120
	ds_read_b128 v[208:211], v158 offset:6144
	ds_read_b128 v[212:215], v158 offset:7168
	global_load_lds_dwordx4 v138, s[42:43]
	s_add_i32 m0, s41, 0xe000
	s_nop 0
	global_load_lds_dwordx4 v140, s[42:43]
	s_waitcnt vmcnt(8)
	s_waitcnt lgkmcnt(0)
	s_barrier
	s_setprio 0
	v_mfma_f32_16x16x32_bf16 v[126:129], v[146:149], v[184:187], 0
	v_mfma_f32_16x16x32_bf16 v[122:125], v[160:163], v[184:187], 0
	v_mfma_f32_16x16x32_bf16 v[114:117], v[146:149], v[192:195], 0
	v_mfma_f32_16x16x32_bf16 v[106:109], v[160:163], v[192:195], 0
	v_mfma_f32_16x16x32_bf16 v[98:101], v[146:149], v[200:203], 0
	v_mfma_f32_16x16x32_bf16 v[90:93], v[160:163], v[200:203], 0
	v_mfma_f32_16x16x32_bf16 v[82:85], v[146:149], v[208:211], 0
	v_mfma_f32_16x16x32_bf16 v[74:77], v[160:163], v[208:211], 0
	v_mfma_f32_16x16x32_bf16 v[126:129], v[150:153], v[188:191], v[126:129]
	v_mfma_f32_16x16x32_bf16 v[122:125], v[164:167], v[188:191], v[122:125]
	v_mfma_f32_16x16x32_bf16 v[114:117], v[150:153], v[196:199], v[114:117]
	v_mfma_f32_16x16x32_bf16 v[106:109], v[164:167], v[196:199], v[106:109]
	v_mfma_f32_16x16x32_bf16 v[98:101], v[150:153], v[204:207], v[98:101]
	v_mfma_f32_16x16x32_bf16 v[90:93], v[164:167], v[204:207], v[90:93]
	v_mfma_f32_16x16x32_bf16 v[82:85], v[150:153], v[212:215], v[82:85]
	v_mfma_f32_16x16x32_bf16 v[74:77], v[164:167], v[212:215], v[74:77]
	v_mfma_f32_16x16x32_bf16 v[118:121], v[168:171], v[184:187], 0
	v_mfma_f32_16x16x32_bf16 v[110:113], v[176:179], v[184:187], 0
	v_mfma_f32_16x16x32_bf16 v[102:105], v[168:171], v[192:195], 0
	v_mfma_f32_16x16x32_bf16 v[94:97], v[176:179], v[192:195], 0
	v_mfma_f32_16x16x32_bf16 v[86:89], v[168:171], v[200:203], 0
	v_mfma_f32_16x16x32_bf16 v[78:81], v[176:179], v[200:203], 0
	v_mfma_f32_16x16x32_bf16 v[70:73], v[168:171], v[208:211], 0
	v_mfma_f32_16x16x32_bf16 v[66:69], v[176:179], v[208:211], 0
	v_mfma_f32_16x16x32_bf16 v[118:121], v[172:175], v[188:191], v[118:121]
	v_mfma_f32_16x16x32_bf16 v[110:113], v[180:183], v[188:191], v[110:113]
	v_mfma_f32_16x16x32_bf16 v[102:105], v[172:175], v[196:199], v[102:105]
	v_mfma_f32_16x16x32_bf16 v[94:97], v[180:183], v[196:199], v[94:97]
	v_mfma_f32_16x16x32_bf16 v[86:89], v[172:175], v[204:207], v[86:89]
	v_mfma_f32_16x16x32_bf16 v[78:81], v[180:183], v[204:207], v[78:81]
	v_mfma_f32_16x16x32_bf16 v[70:73], v[172:175], v[212:215], v[70:73]
	v_mfma_f32_16x16x32_bf16 v[66:69], v[180:183], v[212:215], v[66:69]
	s_barrier
	s_setprio 1
	s_add_i32 s18, s64, s52
	s_add_u32 s78, s44, s8
	s_addc_u32 s79, s45, s9
	s_mov_b32 m0, s18
	ds_read_b128 v[184:187], v158 offset:16384
	ds_read_b128 v[188:191], v158 offset:17408
	ds_read_b128 v[192:195], v158 offset:18432
	ds_read_b128 v[196:199], v158 offset:19456
	ds_read_b128 v[200:203], v158 offset:20480
	ds_read_b128 v[204:207], v158 offset:21504
	ds_read_b128 v[208:211], v158 offset:22528
	ds_read_b128 v[212:215], v158 offset:23552
	global_load_lds_dwordx4 v134, s[44:45]
	s_add_i32 m0, s18, 0x2000
	s_add_u32 s74, s44, 0x40000
	s_addc_u32 s75, s45, 0
	s_add_i32 s18, s65, s52
	global_load_lds_dwordx4 v130, s[44:45]
	s_mov_b32 m0, s18
	s_nop 0
	global_load_lds_dwordx4 v134, s[74:75]
	s_add_i32 m0, s18, 0x2000
	s_nop 0
	global_load_lds_dwordx4 v130, s[74:75]
	s_add_u32 s80, s46, s8
	s_addc_u32 s81, s47, s9
	s_mov_b32 m0, s41
	s_nop 0
	global_load_lds_dwordx4 v136, s[46:47]
	s_mov_b32 m0, s53
	s_nop 0
	global_load_lds_dwordx4 v132, s[46:47]
	s_waitcnt vmcnt(8)
	s_waitcnt lgkmcnt(0)
	s_barrier
; #define PG8_STAGE(bufoff, gbase, voff) do { _Pragma("unroll") for (int _i = 0; _i < 2; ++_i) \
;         __builtin_amdgcn_global_load_lds((const unsigned*)((const char*)(gbase) + (voff)[_i]), (PG8_LAS unsigned*)(lds + (bufoff) + ldsw + _i * 8192), 16, 0, 0); } while (0)
; #define PG8_LDA(dst, b, h) do { _Pragma("unroll") for (int m = 0; m < 4; ++m) _Pragma("unroll") for (int k = 0; k < 2; ++k) dst[m][k] = *(const PG8_LAS bf16x8*)(lds + PG8_SA(b, h) + aoff + m * 2048 + k * 1024); } while (0)
; #define PG8_LDB(dst, b, h) do { _Pragma("unroll") for (int n = 0; n < 2; ++n) _Pragma("unroll") for (int k = 0; k < 2; ++k) dst[n][k] = *(const PG8_LAS bf16x8*)(lds + PG8_SB(b, h) + boff + n * 2048 + k * 1024); } while (0)
; #define PG8_MMA(ai, bj, At, Bt) do { __builtin_amdgcn_s_setprio(1); _Pragma("unroll") for (int m = 0; m < 4; ++m) _Pragma("unroll") for (int n = 0; n < 2; ++n) _Pragma("unroll") for (int k = 0; k < 2; ++k) \
;         acc[ai][bj][m][n] = __builtin_amdgcn_mfma_f32_16x16x32_bf16(Bt[n][k], At[m][k], acc[ai][bj][m][n], 0, 0, 0); __builtin_amdgcn_s_setprio(0); } while (0)
; #define PG8_WAIT_V(n) asm volatile("s_waitcnt vmcnt(" #n ")" ::: "memory")
; #define PG8_WAIT_L(n) asm volatile("s_waitcnt lgkmcnt(" #n ")" ::: "memory")
; #define PG8_BAR __builtin_amdgcn_s_barrier()
; #define PG8_SCHED __builtin_amdgcn_sched_barrier(0)
; template <class Epi, class Sched, bool ALIGN_EPI = false, bool SP2 = false>
; __device__ __forceinline__ void gemm_phase(PG8_LAS unsigned char* lds, const Gemm g, const Sched& S, const Epi& E) {
;     ...
;             PG8_WAIT_V(8); PG8_WAIT_L(0); PG8_BAR; PG8_MMA(1, 0, At, B0); PG8_MMA(1, 1, At, B1); PG8_BAR; PG8_SCHED;
;             PG8_LDB(B0, 1, 0); PG8_LDB(B1, 1, 1); PG8_SCHED; PG8_LDA(At, 1, 0); PG8_STAGE(PG8_SA(0, 1), a2 + hA, voffA);
;             PG8_WAIT_V(8); PG8_WAIT_L(0); PG8_BAR; PG8_MMA(0, 0, At, B0); PG8_MMA(0, 1, At, B1); PG8_BAR; PG8_SCHED;
	s_setprio 0
	v_mfma_f32_16x16x32_bf16 v[62:65], v[146:149], v[184:187], 0
	v_mfma_f32_16x16x32_bf16 v[58:61], v[160:163], v[184:187], 0
	v_mfma_f32_16x16x32_bf16 v[50:53], v[146:149], v[192:195], 0
	v_mfma_f32_16x16x32_bf16 v[42:45], v[160:163], v[192:195], 0
	v_mfma_f32_16x16x32_bf16 v[34:37], v[146:149], v[200:203], 0
	v_mfma_f32_16x16x32_bf16 v[26:29], v[160:163], v[200:203], 0
	v_mfma_f32_16x16x32_bf16 v[18:21], v[146:149], v[208:211], 0
	v_mfma_f32_16x16x32_bf16 v[10:13], v[160:163], v[208:211], 0
	v_mfma_f32_16x16x32_bf16 v[62:65], v[150:153], v[188:191], v[62:65]
	v_mfma_f32_16x16x32_bf16 v[58:61], v[164:167], v[188:191], v[58:61]
	v_mfma_f32_16x16x32_bf16 v[50:53], v[150:153], v[196:199], v[50:53]
	v_mfma_f32_16x16x32_bf16 v[42:45], v[164:167], v[196:199], v[42:45]
	v_mfma_f32_16x16x32_bf16 v[34:37], v[150:153], v[204:207], v[34:37]
	v_mfma_f32_16x16x32_bf16 v[26:29], v[164:167], v[204:207], v[26:29]
	v_mfma_f32_16x16x32_bf16 v[18:21], v[150:153], v[212:215], v[18:21]
	v_mfma_f32_16x16x32_bf16 v[10:13], v[164:167], v[212:215], v[10:13]
	v_mfma_f32_16x16x32_bf16 v[54:57], v[168:171], v[184:187], 0
	v_mfma_f32_16x16x32_bf16 v[46:49], v[176:179], v[184:187], 0
	v_mfma_f32_16x16x32_bf16 v[38:41], v[168:171], v[192:195], 0
	v_mfma_f32_16x16x32_bf16 v[30:33], v[176:179], v[192:195], 0
	v_mfma_f32_16x16x32_bf16 v[22:25], v[168:171], v[200:203], 0
	v_mfma_f32_16x16x32_bf16 v[14:17], v[176:179], v[200:203], 0
	v_mfma_f32_16x16x32_bf16 v[6:9], v[168:171], v[208:211], 0
	v_mfma_f32_16x16x32_bf16 v[2:5], v[176:179], v[208:211], 0
	v_mfma_f32_16x16x32_bf16 v[54:57], v[172:175], v[188:191], v[54:57]
	v_mfma_f32_16x16x32_bf16 v[46:49], v[180:183], v[188:191], v[46:49]
	v_mfma_f32_16x16x32_bf16 v[38:41], v[172:175], v[196:199], v[38:41]
	v_mfma_f32_16x16x32_bf16 v[30:33], v[180:183], v[196:199], v[30:33]
	v_mfma_f32_16x16x32_bf16 v[22:25], v[172:175], v[204:207], v[22:25]
	v_mfma_f32_16x16x32_bf16 v[14:17], v[180:183], v[204:207], v[14:17]
	v_mfma_f32_16x16x32_bf16 v[6:9], v[172:175], v[212:215], v[6:9]
	v_mfma_f32_16x16x32_bf16 v[2:5], v[180:183], v[212:215], v[2:5]
	s_barrier
	s_setprio 1
	s_add_i32 s18, 0, 0x18000
	v_add_u32_e32 v159, s18, v154
	s_add_i32 s19, 0, 0x1c000
	ds_read_b128 v[146:149], v159
	ds_read_b128 v[150:153], v159 offset:1024
	ds_read_b128 v[160:163], v159 offset:2048
	ds_read_b128 v[164:167], v159 offset:3072
	v_add_u32_e32 v159, s19, v154
	ds_read_b128 v[168:171], v159
	ds_read_b128 v[172:175], v159 offset:1024
	ds_read_b128 v[176:179], v159 offset:2048
	ds_read_b128 v[180:183], v159 offset:3072
	s_add_u32 s46, s46, 0x40000
	s_addc_u32 s47, s47, 0
	s_mov_b32 m0, s58
	ds_read_b128 v[184:187], v158 offset:32768
	ds_read_b128 v[188:191], v158 offset:33792
	ds_read_b128 v[192:195], v158 offset:34816
	ds_read_b128 v[196:199], v158 offset:35840
	ds_read_b128 v[200:203], v158 offset:36864
	ds_read_b128 v[204:207], v158 offset:37888
	ds_read_b128 v[208:211], v158 offset:38912
	ds_read_b128 v[212:215], v158 offset:39936
	global_load_lds_dwordx4 v136, s[46:47]
	s_mov_b32 m0, s59
	s_nop 0
	global_load_lds_dwordx4 v132, s[46:47]
	s_waitcnt vmcnt(8)
	s_waitcnt lgkmcnt(0)
	s_barrier
	s_setprio 0
	v_mfma_f32_16x16x32_bf16 v[126:129], v[146:149], v[184:187], v[126:129]
	v_mfma_f32_16x16x32_bf16 v[122:125], v[160:163], v[184:187], v[122:125]
	v_mfma_f32_16x16x32_bf16 v[114:117], v[146:149], v[192:195], v[114:117]
	v_mfma_f32_16x16x32_bf16 v[106:109], v[160:163], v[192:195], v[106:109]
	v_mfma_f32_16x16x32_bf16 v[98:101], v[146:149], v[200:203], v[98:101]
	v_mfma_f32_16x16x32_bf16 v[90:93], v[160:163], v[200:203], v[90:93]
	v_mfma_f32_16x16x32_bf16 v[82:85], v[146:149], v[208:211], v[82:85]
	v_mfma_f32_16x16x32_bf16 v[74:77], v[160:163], v[208:211], v[74:77]
	v_mfma_f32_16x16x32_bf16 v[126:129], v[150:153], v[188:191], v[126:129]
	v_mfma_f32_16x16x32_bf16 v[122:125], v[164:167], v[188:191], v[122:125]
	v_mfma_f32_16x16x32_bf16 v[114:117], v[150:153], v[196:199], v[114:117]
	v_mfma_f32_16x16x32_bf16 v[106:109], v[164:167], v[196:199], v[106:109]
	v_mfma_f32_16x16x32_bf16 v[98:101], v[150:153], v[204:207], v[98:101]
	v_mfma_f32_16x16x32_bf16 v[90:93], v[164:167], v[204:207], v[90:93]
	v_mfma_f32_16x16x32_bf16 v[82:85], v[150:153], v[212:215], v[82:85]
	v_mfma_f32_16x16x32_bf16 v[74:77], v[164:167], v[212:215], v[74:77]
	v_mfma_f32_16x16x32_bf16 v[118:121], v[168:171], v[184:187], v[118:121]
	v_mfma_f32_16x16x32_bf16 v[110:113], v[176:179], v[184:187], v[110:113]
	v_mfma_f32_16x16x32_bf16 v[102:105], v[168:171], v[192:195], v[102:105]
	v_mfma_f32_16x16x32_bf16 v[94:97], v[176:179], v[192:195], v[94:97]
	v_mfma_f32_16x16x32_bf16 v[86:89], v[168:171], v[200:203], v[86:89]
	v_mfma_f32_16x16x32_bf16 v[78:81], v[176:179], v[200:203], v[78:81]
	v_mfma_f32_16x16x32_bf16 v[70:73], v[168:171], v[208:211], v[70:73]
	v_mfma_f32_16x16x32_bf16 v[66:69], v[176:179], v[208:211], v[66:69]
	v_mfma_f32_16x16x32_bf16 v[118:121], v[172:175], v[188:191], v[118:121]
	v_mfma_f32_16x16x32_bf16 v[110:113], v[180:183], v[188:191], v[110:113]
	v_mfma_f32_16x16x32_bf16 v[102:105], v[172:175], v[196:199], v[102:105]
	v_mfma_f32_16x16x32_bf16 v[94:97], v[180:183], v[196:199], v[94:97]
	v_mfma_f32_16x16x32_bf16 v[86:89], v[172:175], v[204:207], v[86:89]
	v_mfma_f32_16x16x32_bf16 v[78:81], v[180:183], v[204:207], v[78:81]
	v_mfma_f32_16x16x32_bf16 v[70:73], v[172:175], v[212:215], v[70:73]
	v_mfma_f32_16x16x32_bf16 v[66:69], v[180:183], v[212:215], v[66:69]
	s_barrier
; #define PG8_STAGE(bufoff, gbase, voff) do { _Pragma("unroll") for (int _i = 0; _i < 2; ++_i) \
;         __builtin_amdgcn_global_load_lds((const unsigned*)((const char*)(gbase) + (voff)[_i]), (PG8_LAS unsigned*)(lds + (bufoff) + ldsw + _i * 8192), 16, 0, 0); } while (0)
; #define PG8_LDA(dst, b, h) do { _Pragma("unroll") for (int m = 0; m < 4; ++m) _Pragma("unroll") for (int k = 0; k < 2; ++k) dst[m][k] = *(const PG8_LAS bf16x8*)(lds + PG8_SA(b, h) + aoff + m * 2048 + k * 1024); } while (0)
; #define PG8_LDB(dst, b, h) do { _Pragma("unroll") for (int n = 0; n < 2; ++n) _Pragma("unroll") for (int k = 0; k < 2; ++k) dst[n][k] = *(const PG8_LAS bf16x8*)(lds + PG8_SB(b, h) + boff + n * 2048 + k * 1024); } while (0)
; #define PG8_MMA(ai, bj, At, Bt) do { __builtin_amdgcn_s_setprio(1); _Pragma("unroll") for (int m = 0; m < 4; ++m) _Pragma("unroll") for (int n = 0; n < 2; ++n) _Pragma("unroll") for (int k = 0; k < 2; ++k) \
;         acc[ai][bj][m][n] = __builtin_amdgcn_mfma_f32_16x16x32_bf16(Bt[n][k], At[m][k], acc[ai][bj][m][n], 0, 0, 0); __builtin_amdgcn_s_setprio(0); } while (0)
; #define PG8_WAIT_V(n) asm volatile("s_waitcnt vmcnt(" #n ")" ::: "memory")
; #define PG8_WAIT_L(n) asm volatile("s_waitcnt lgkmcnt(" #n ")" ::: "memory")
; #define PG8_BAR __builtin_amdgcn_s_barrier()
; #define PG8_SCHED __builtin_amdgcn_sched_barrier(0)
; template <class Epi, class Sched, bool ALIGN_EPI = false, bool SP2 = false>
; __device__ __forceinline__ void gemm_phase(PG8_LAS unsigned char* lds, const Gemm g, const Sched& S, const Epi& E) {
;     ...
;             PG8_LDB(B0, 0, 0); PG8_LDB(B1, 0, 1); PG8_SCHED; PG8_LDA(At, 0, 0); PG8_STAGE(PG8_SA(1, 1), a1 + hA, voffA);
;             PG8_WAIT_V(8); PG8_WAIT_L(0); PG8_BAR; PG8_MMA(0, 0, At, B0); PG8_MMA(0, 1, At, B1); PG8_BAR; PG8_SCHED;
;     ...
;             PG8_LDA(At, 1, 1); PG8_STAGE(PG8_SB(1, 0), b3, voffB); PG8_STAGE(PG8_SB(1, 1), b3 + hB, voffB); PG8_STAGE(PG8_SA(1, 0), a3, voffA);
;             PG8_WAIT_V(8); PG8_WAIT_L(0); PG8_BAR; PG8_MMA(1, 0, At, B0); PG8_MMA(1, 1, At, B1); PG8_BAR; PG8_SCHED;
	s_setprio 1
	s_add_i32 s18, s18, s52
	s_mov_b32 m0, s18
	ds_read_b128 v[184:187], v158 offset:49152
	ds_read_b128 v[188:191], v158 offset:50176
	ds_read_b128 v[192:195], v158 offset:51200
	ds_read_b128 v[196:199], v158 offset:52224
	ds_read_b128 v[200:203], v158 offset:53248
	ds_read_b128 v[204:207], v158 offset:54272
	ds_read_b128 v[208:211], v158 offset:55296
	ds_read_b128 v[212:215], v158 offset:56320
	global_load_lds_dwordx4 v134, s[78:79]
	s_add_i32 m0, s18, 0x2000
	s_add_u32 s44, s44, 0x40080
	s_addc_u32 s45, s45, 0
	s_add_i32 s18, s19, s52
	global_load_lds_dwordx4 v130, s[78:79]
	s_mov_b32 m0, s18
	s_nop 0
	global_load_lds_dwordx4 v134, s[44:45]
	s_add_i32 m0, s18, 0x2000
	s_nop 0
	global_load_lds_dwordx4 v130, s[44:45]
	s_mov_b32 m0, s60
	s_nop 0
	global_load_lds_dwordx4 v136, s[80:81]
	s_mov_b32 m0, s61
	s_nop 0
	global_load_lds_dwordx4 v132, s[80:81]
	s_waitcnt vmcnt(8)
	s_waitcnt lgkmcnt(0)
	s_barrier
	s_setprio 0
	v_mfma_f32_16x16x32_bf16 v[62:65], v[146:149], v[184:187], v[62:65]
	v_mfma_f32_16x16x32_bf16 v[58:61], v[160:163], v[184:187], v[58:61]
	v_mfma_f32_16x16x32_bf16 v[50:53], v[146:149], v[192:195], v[50:53]
	v_mfma_f32_16x16x32_bf16 v[42:45], v[160:163], v[192:195], v[42:45]
	v_mfma_f32_16x16x32_bf16 v[34:37], v[146:149], v[200:203], v[34:37]
	v_mfma_f32_16x16x32_bf16 v[26:29], v[160:163], v[200:203], v[26:29]
	v_mfma_f32_16x16x32_bf16 v[18:21], v[146:149], v[208:211], v[18:21]
	v_mfma_f32_16x16x32_bf16 v[10:13], v[160:163], v[208:211], v[10:13]
	v_mfma_f32_16x16x32_bf16 v[62:65], v[150:153], v[188:191], v[62:65]
	v_mfma_f32_16x16x32_bf16 v[58:61], v[164:167], v[188:191], v[58:61]
	v_mfma_f32_16x16x32_bf16 v[50:53], v[150:153], v[196:199], v[50:53]
	v_mfma_f32_16x16x32_bf16 v[42:45], v[164:167], v[196:199], v[42:45]
	v_mfma_f32_16x16x32_bf16 v[34:37], v[150:153], v[204:207], v[34:37]
	v_mfma_f32_16x16x32_bf16 v[26:29], v[164:167], v[204:207], v[26:29]
	v_mfma_f32_16x16x32_bf16 v[18:21], v[150:153], v[212:215], v[18:21]
	v_mfma_f32_16x16x32_bf16 v[10:13], v[164:167], v[212:215], v[10:13]
	v_mfma_f32_16x16x32_bf16 v[54:57], v[168:171], v[184:187], v[54:57]
	v_mfma_f32_16x16x32_bf16 v[46:49], v[176:179], v[184:187], v[46:49]
	v_mfma_f32_16x16x32_bf16 v[38:41], v[168:171], v[192:195], v[38:41]
	v_mfma_f32_16x16x32_bf16 v[30:33], v[176:179], v[192:195], v[30:33]
	v_mfma_f32_16x16x32_bf16 v[22:25], v[168:171], v[200:203], v[22:25]
	v_mfma_f32_16x16x32_bf16 v[14:17], v[176:179], v[200:203], v[14:17]
	v_mfma_f32_16x16x32_bf16 v[6:9], v[168:171], v[208:211], v[6:9]
	v_mfma_f32_16x16x32_bf16 v[2:5], v[176:179], v[208:211], v[2:5]
	v_mfma_f32_16x16x32_bf16 v[54:57], v[172:175], v[188:191], v[54:57]
	v_mfma_f32_16x16x32_bf16 v[46:49], v[180:183], v[188:191], v[46:49]
	v_mfma_f32_16x16x32_bf16 v[38:41], v[172:175], v[196:199], v[38:41]
	v_mfma_f32_16x16x32_bf16 v[30:33], v[180:183], v[196:199], v[30:33]
	v_mfma_f32_16x16x32_bf16 v[22:25], v[172:175], v[204:207], v[22:25]
	v_mfma_f32_16x16x32_bf16 v[14:17], v[180:183], v[204:207], v[14:17]
	v_mfma_f32_16x16x32_bf16 v[6:9], v[172:175], v[212:215], v[6:9]
	v_mfma_f32_16x16x32_bf16 v[2:5], v[180:183], v[212:215], v[2:5]
	s_barrier
	s_add_i32 s72, s72, 2
	s_add_u32 s42, s42, 0x100
	s_addc_u32 s43, s43, 0
	s_add_u32 s70, s70, 0x100
	s_addc_u32 s71, s71, 0
	s_cmp_gt_u32 s72, 13
.LBB0_868:
	s_setprio 1
	ds_read_b128 v[146:149], v156
	ds_read_b128 v[150:153], v156 offset:1024
	ds_read_b128 v[160:163], v156 offset:2048
	ds_read_b128 v[164:167], v156 offset:3072
	ds_read_b128 v[168:171], v157
	ds_read_b128 v[172:175], v157 offset:1024
	ds_read_b128 v[176:179], v157 offset:2048
	ds_read_b128 v[180:183], v157 offset:3072
	s_add_u32 s18, s42, 0xfffc0080
	s_addc_u32 s19, s43, -1
	s_cmp_eq_u32 s72, 12
	s_cselect_b32 s47, s23, s19
	s_cselect_b32 s46, s67, s18
	s_cselect_b32 s45, s21, s71
	s_cselect_b32 s44, s69, s70
	s_add_i32 m0, s41, 0xc000
	ds_read_b128 v[184:187], v158
	ds_read_b128 v[188:191], v158 offset:1024
	ds_read_b128 v[192:195], v158 offset:2048
	ds_read_b128 v[196:199], v158 offset:3072
	ds_read_b128 v[200:203], v158 offset:4096
	ds_read_b128 v[204:207], v158 offset:5120
	ds_read_b128 v[208:211], v158 offset:6144
	ds_read_b128 v[212:215], v158 offset:7168
	global_load_lds_dwordx4 v138, s[42:43]
	s_add_i32 m0, s41, 0xe000
	s_nop 0
	global_load_lds_dwordx4 v140, s[42:43]
	s_waitcnt vmcnt(8)
	s_waitcnt lgkmcnt(0)
	s_barrier
	s_setprio 0
	v_mfma_f32_16x16x32_bf16 v[126:129], v[146:149], v[184:187], v[126:129]
	v_mfma_f32_16x16x32_bf16 v[122:125], v[160:163], v[184:187], v[122:125]
	v_mfma_f32_16x16x32_bf16 v[114:117], v[146:149], v[192:195], v[114:117]
	v_mfma_f32_16x16x32_bf16 v[106:109], v[160:163], v[192:195], v[106:109]
	v_mfma_f32_16x16x32_bf16 v[98:101], v[146:149], v[200:203], v[98:101]
	v_mfma_f32_16x16x32_bf16 v[90:93], v[160:163], v[200:203], v[90:93]
	v_mfma_f32_16x16x32_bf16 v[82:85], v[146:149], v[208:211], v[82:85]
	v_mfma_f32_16x16x32_bf16 v[74:77], v[160:163], v[208:211], v[74:77]
	v_mfma_f32_16x16x32_bf16 v[126:129], v[150:153], v[188:191], v[126:129]
	v_mfma_f32_16x16x32_bf16 v[122:125], v[164:167], v[188:191], v[122:125]
	v_mfma_f32_16x16x32_bf16 v[114:117], v[150:153], v[196:199], v[114:117]
	v_mfma_f32_16x16x32_bf16 v[106:109], v[164:167], v[196:199], v[106:109]
	v_mfma_f32_16x16x32_bf16 v[98:101], v[150:153], v[204:207], v[98:101]
	v_mfma_f32_16x16x32_bf16 v[90:93], v[164:167], v[204:207], v[90:93]
	v_mfma_f32_16x16x32_bf16 v[82:85], v[150:153], v[212:215], v[82:85]
	v_mfma_f32_16x16x32_bf16 v[74:77], v[164:167], v[212:215], v[74:77]
	v_mfma_f32_16x16x32_bf16 v[118:121], v[168:171], v[184:187], v[118:121]
	v_mfma_f32_16x16x32_bf16 v[110:113], v[176:179], v[184:187], v[110:113]
	v_mfma_f32_16x16x32_bf16 v[102:105], v[168:171], v[192:195], v[102:105]
	v_mfma_f32_16x16x32_bf16 v[94:97], v[176:179], v[192:195], v[94:97]
	v_mfma_f32_16x16x32_bf16 v[86:89], v[168:171], v[200:203], v[86:89]
	v_mfma_f32_16x16x32_bf16 v[78:81], v[176:179], v[200:203], v[78:81]
	v_mfma_f32_16x16x32_bf16 v[70:73], v[168:171], v[208:211], v[70:73]
	v_mfma_f32_16x16x32_bf16 v[66:69], v[176:179], v[208:211], v[66:69]
	v_mfma_f32_16x16x32_bf16 v[118:121], v[172:175], v[188:191], v[118:121]
	v_mfma_f32_16x16x32_bf16 v[110:113], v[180:183], v[188:191], v[110:113]
	v_mfma_f32_16x16x32_bf16 v[102:105], v[172:175], v[196:199], v[102:105]
	v_mfma_f32_16x16x32_bf16 v[94:97], v[180:183], v[196:199], v[94:97]
	v_mfma_f32_16x16x32_bf16 v[86:89], v[172:175], v[204:207], v[86:89]
	v_mfma_f32_16x16x32_bf16 v[78:81], v[180:183], v[204:207], v[78:81]
	v_mfma_f32_16x16x32_bf16 v[70:73], v[172:175], v[212:215], v[70:73]
	v_mfma_f32_16x16x32_bf16 v[66:69], v[180:183], v[212:215], v[66:69]
	s_barrier
; #define PG8_STAGE(bufoff, gbase, voff) do { _Pragma("unroll") for (int _i = 0; _i < 2; ++_i) \
;         __builtin_amdgcn_global_load_lds((const unsigned*)((const char*)(gbase) + (voff)[_i]), (PG8_LAS unsigned*)(lds + (bufoff) + ldsw + _i * 8192), 16, 0, 0); } while (0)
; #define PG8_LDA(dst, b, h) do { _Pragma("unroll") for (int m = 0; m < 4; ++m) _Pragma("unroll") for (int k = 0; k < 2; ++k) dst[m][k] = *(const PG8_LAS bf16x8*)(lds + PG8_SA(b, h) + aoff + m * 2048 + k * 1024); } while (0)
; #define PG8_LDB(dst, b, h) do { _Pragma("unroll") for (int n = 0; n < 2; ++n) _Pragma("unroll") for (int k = 0; k < 2; ++k) dst[n][k] = *(const PG8_LAS bf16x8*)(lds + PG8_SB(b, h) + boff + n * 2048 + k * 1024); } while (0)
; #define PG8_MMA(ai, bj, At, Bt) do { __builtin_amdgcn_s_setprio(1); _Pragma("unroll") for (int m = 0; m < 4; ++m) _Pragma("unroll") for (int n = 0; n < 2; ++n) _Pragma("unroll") for (int k = 0; k < 2; ++k) \
;         acc[ai][bj][m][n] = __builtin_amdgcn_mfma_f32_16x16x32_bf16(Bt[n][k], At[m][k], acc[ai][bj][m][n], 0, 0, 0); __builtin_amdgcn_s_setprio(0); } while (0)
; #define PG8_WAIT_V(n) asm volatile("s_waitcnt vmcnt(" #n ")" ::: "memory")
; #define PG8_WAIT_L(n) asm volatile("s_waitcnt lgkmcnt(" #n ")" ::: "memory")
; #define PG8_BAR __builtin_amdgcn_s_barrier()
; #define PG8_SCHED __builtin_amdgcn_sched_barrier(0)
; template <class Epi, class Sched, bool ALIGN_EPI = false, bool SP2 = false>
; __device__ __forceinline__ void gemm_phase(PG8_LAS unsigned char* lds, const Gemm g, const Sched& S, const Epi& E) {
;     ...
;             PG8_LDA(At, 0, 1); PG8_STAGE(PG8_SB(0, 0), b2, voffB); PG8_STAGE(PG8_SB(0, 1), b2 + hB, voffB); PG8_STAGE(PG8_SA(0, 0), a2, voffA);
;             PG8_WAIT_V(8); PG8_WAIT_L(0); PG8_BAR; PG8_MMA(1, 0, At, B0); PG8_MMA(1, 1, At, B1); PG8_BAR; PG8_SCHED;
;             PG8_LDB(B0, 1, 0); PG8_LDB(B1, 1, 1); PG8_SCHED; PG8_LDA(At, 1, 0); PG8_STAGE(PG8_SA(0, 1), a2 + hA, voffA);
	s_setprio 1
	s_add_i32 s18, s64, s52
	s_add_u32 s78, s44, s8
	s_addc_u32 s79, s45, s9
	s_mov_b32 m0, s18
	ds_read_b128 v[184:187], v158 offset:16384
	ds_read_b128 v[188:191], v158 offset:17408
	ds_read_b128 v[192:195], v158 offset:18432
	ds_read_b128 v[196:199], v158 offset:19456
	ds_read_b128 v[200:203], v158 offset:20480
	ds_read_b128 v[204:207], v158 offset:21504
	ds_read_b128 v[208:211], v158 offset:22528
	ds_read_b128 v[212:215], v158 offset:23552
	global_load_lds_dwordx4 v134, s[44:45]
	s_add_i32 m0, s18, 0x2000
	s_add_u32 s74, s44, 0x40000
	s_addc_u32 s75, s45, 0
	s_add_i32 s18, s65, s52
	global_load_lds_dwordx4 v130, s[44:45]
	s_mov_b32 m0, s18
	s_nop 0
	global_load_lds_dwordx4 v134, s[74:75]
	s_add_i32 m0, s18, 0x2000
	s_nop 0
	global_load_lds_dwordx4 v130, s[74:75]
	s_add_u32 s80, s46, s8
	s_addc_u32 s81, s47, s9
	s_mov_b32 m0, s41
	s_nop 0
	global_load_lds_dwordx4 v136, s[46:47]
	s_mov_b32 m0, s53
	s_nop 0
	global_load_lds_dwordx4 v132, s[46:47]
	s_waitcnt vmcnt(8)
	s_waitcnt lgkmcnt(0)
	s_barrier
	s_setprio 0
	v_mfma_f32_16x16x32_bf16 v[62:65], v[146:149], v[184:187], v[62:65]
	v_mfma_f32_16x16x32_bf16 v[58:61], v[160:163], v[184:187], v[58:61]
	v_mfma_f32_16x16x32_bf16 v[50:53], v[146:149], v[192:195], v[50:53]
	v_mfma_f32_16x16x32_bf16 v[42:45], v[160:163], v[192:195], v[42:45]
	v_mfma_f32_16x16x32_bf16 v[34:37], v[146:149], v[200:203], v[34:37]
	v_mfma_f32_16x16x32_bf16 v[26:29], v[160:163], v[200:203], v[26:29]
	v_mfma_f32_16x16x32_bf16 v[18:21], v[146:149], v[208:211], v[18:21]
	v_mfma_f32_16x16x32_bf16 v[10:13], v[160:163], v[208:211], v[10:13]
	v_mfma_f32_16x16x32_bf16 v[62:65], v[150:153], v[188:191], v[62:65]
	v_mfma_f32_16x16x32_bf16 v[58:61], v[164:167], v[188:191], v[58:61]
	v_mfma_f32_16x16x32_bf16 v[50:53], v[150:153], v[196:199], v[50:53]
	v_mfma_f32_16x16x32_bf16 v[42:45], v[164:167], v[196:199], v[42:45]
	v_mfma_f32_16x16x32_bf16 v[34:37], v[150:153], v[204:207], v[34:37]
	v_mfma_f32_16x16x32_bf16 v[26:29], v[164:167], v[204:207], v[26:29]
	v_mfma_f32_16x16x32_bf16 v[18:21], v[150:153], v[212:215], v[18:21]
	v_mfma_f32_16x16x32_bf16 v[10:13], v[164:167], v[212:215], v[10:13]
	v_mfma_f32_16x16x32_bf16 v[54:57], v[168:171], v[184:187], v[54:57]
	v_mfma_f32_16x16x32_bf16 v[46:49], v[176:179], v[184:187], v[46:49]
	v_mfma_f32_16x16x32_bf16 v[38:41], v[168:171], v[192:195], v[38:41]
	v_mfma_f32_16x16x32_bf16 v[30:33], v[176:179], v[192:195], v[30:33]
	v_mfma_f32_16x16x32_bf16 v[22:25], v[168:171], v[200:203], v[22:25]
	v_mfma_f32_16x16x32_bf16 v[14:17], v[176:179], v[200:203], v[14:17]
	v_mfma_f32_16x16x32_bf16 v[6:9], v[168:171], v[208:211], v[6:9]
	v_mfma_f32_16x16x32_bf16 v[2:5], v[176:179], v[208:211], v[2:5]
	v_mfma_f32_16x16x32_bf16 v[54:57], v[172:175], v[188:191], v[54:57]
	v_mfma_f32_16x16x32_bf16 v[46:49], v[180:183], v[188:191], v[46:49]
	v_mfma_f32_16x16x32_bf16 v[38:41], v[172:175], v[196:199], v[38:41]
	v_mfma_f32_16x16x32_bf16 v[30:33], v[180:183], v[196:199], v[30:33]
	v_mfma_f32_16x16x32_bf16 v[22:25], v[172:175], v[204:207], v[22:25]
	v_mfma_f32_16x16x32_bf16 v[14:17], v[180:183], v[204:207], v[14:17]
	v_mfma_f32_16x16x32_bf16 v[6:9], v[172:175], v[212:215], v[6:9]
	v_mfma_f32_16x16x32_bf16 v[2:5], v[180:183], v[212:215], v[2:5]
	s_barrier
	s_setprio 1
	s_add_i32 s18, 0, 0x18000
	v_add_u32_e32 v159, s18, v154
	s_add_i32 s19, 0, 0x1c000
	ds_read_b128 v[146:149], v159
	ds_read_b128 v[150:153], v159 offset:1024
	ds_read_b128 v[160:163], v159 offset:2048
	ds_read_b128 v[164:167], v159 offset:3072
	v_add_u32_e32 v159, s19, v154
	ds_read_b128 v[168:171], v159
	ds_read_b128 v[172:175], v159 offset:1024
	ds_read_b128 v[176:179], v159 offset:2048
	ds_read_b128 v[180:183], v159 offset:3072
	s_add_u32 s46, s46, 0x40000
	s_addc_u32 s47, s47, 0
	s_mov_b32 m0, s58
	ds_read_b128 v[184:187], v158 offset:32768
	ds_read_b128 v[188:191], v158 offset:33792
	ds_read_b128 v[192:195], v158 offset:34816
	ds_read_b128 v[196:199], v158 offset:35840
	ds_read_b128 v[200:203], v158 offset:36864
	ds_read_b128 v[204:207], v158 offset:37888
	ds_read_b128 v[208:211], v158 offset:38912
	ds_read_b128 v[212:215], v158 offset:39936
	global_load_lds_dwordx4 v136, s[46:47]
	s_mov_b32 m0, s59
	s_nop 0
	global_load_lds_dwordx4 v132, s[46:47]
	s_waitcnt vmcnt(8)
	s_waitcnt lgkmcnt(0)
	s_barrier
; #define PG8_STAGE(bufoff, gbase, voff) do { _Pragma("unroll") for (int _i = 0; _i < 2; ++_i) \
;         __builtin_amdgcn_global_load_lds((const unsigned*)((const char*)(gbase) + (voff)[_i]), (PG8_LAS unsigned*)(lds + (bufoff) + ldsw + _i * 8192), 16, 0, 0); } while (0)
; #define PG8_LDA(dst, b, h) do { _Pragma("unroll") for (int m = 0; m < 4; ++m) _Pragma("unroll") for (int k = 0; k < 2; ++k) dst[m][k] = *(const PG8_LAS bf16x8*)(lds + PG8_SA(b, h) + aoff + m * 2048 + k * 1024); } while (0)
; #define PG8_LDB(dst, b, h) do { _Pragma("unroll") for (int n = 0; n < 2; ++n) _Pragma("unroll") for (int k = 0; k < 2; ++k) dst[n][k] = *(const PG8_LAS bf16x8*)(lds + PG8_SB(b, h) + boff + n * 2048 + k * 1024); } while (0)
; #define PG8_MMA(ai, bj, At, Bt) do { __builtin_amdgcn_s_setprio(1); _Pragma("unroll") for (int m = 0; m < 4; ++m) _Pragma("unroll") for (int n = 0; n < 2; ++n) _Pragma("unroll") for (int k = 0; k < 2; ++k) \
;         acc[ai][bj][m][n] = __builtin_amdgcn_mfma_f32_16x16x32_bf16(Bt[n][k], At[m][k], acc[ai][bj][m][n], 0, 0, 0); __builtin_amdgcn_s_setprio(0); } while (0)
; #define PG8_WAIT_V(n) asm volatile("s_waitcnt vmcnt(" #n ")" ::: "memory")
; #define PG8_WAIT_L(n) asm volatile("s_waitcnt lgkmcnt(" #n ")" ::: "memory")
; #define PG8_BAR __builtin_amdgcn_s_barrier()
; #define PG8_SCHED __builtin_amdgcn_sched_barrier(0)
; template <class Epi, class Sched, bool ALIGN_EPI = false, bool SP2 = false>
; __device__ __forceinline__ void gemm_phase(PG8_LAS unsigned char* lds, const Gemm g, const Sched& S, const Epi& E) {
;     ...
;             PG8_LDB(B0, 1, 0); PG8_LDB(B1, 1, 1); PG8_SCHED; PG8_LDA(At, 1, 0); PG8_STAGE(PG8_SA(0, 1), a2 + hA, voffA);
;             PG8_WAIT_V(8); PG8_WAIT_L(0); PG8_BAR; PG8_MMA(0, 0, At, B0); PG8_MMA(0, 1, At, B1); PG8_BAR; PG8_SCHED;
;             PG8_LDA(At, 1, 1); PG8_STAGE(PG8_SB(1, 0), b3, voffB); PG8_STAGE(PG8_SB(1, 1), b3 + hB, voffB); PG8_STAGE(PG8_SA(1, 0), a3, voffA);
;             PG8_WAIT_V(8); PG8_WAIT_L(0); PG8_BAR; PG8_MMA(1, 0, At, B0); PG8_MMA(1, 1, At, B1); PG8_BAR; PG8_SCHED;
	s_setprio 0
	v_mfma_f32_16x16x32_bf16 v[126:129], v[146:149], v[184:187], v[126:129]
	v_mfma_f32_16x16x32_bf16 v[122:125], v[160:163], v[184:187], v[122:125]
	v_mfma_f32_16x16x32_bf16 v[114:117], v[146:149], v[192:195], v[114:117]
	v_mfma_f32_16x16x32_bf16 v[106:109], v[160:163], v[192:195], v[106:109]
	v_mfma_f32_16x16x32_bf16 v[98:101], v[146:149], v[200:203], v[98:101]
	v_mfma_f32_16x16x32_bf16 v[90:93], v[160:163], v[200:203], v[90:93]
	v_mfma_f32_16x16x32_bf16 v[82:85], v[146:149], v[208:211], v[82:85]
	v_mfma_f32_16x16x32_bf16 v[74:77], v[160:163], v[208:211], v[74:77]
	v_mfma_f32_16x16x32_bf16 v[126:129], v[150:153], v[188:191], v[126:129]
	v_mfma_f32_16x16x32_bf16 v[122:125], v[164:167], v[188:191], v[122:125]
	v_mfma_f32_16x16x32_bf16 v[114:117], v[150:153], v[196:199], v[114:117]
	v_mfma_f32_16x16x32_bf16 v[106:109], v[164:167], v[196:199], v[106:109]
	v_mfma_f32_16x16x32_bf16 v[98:101], v[150:153], v[204:207], v[98:101]
	v_mfma_f32_16x16x32_bf16 v[90:93], v[164:167], v[204:207], v[90:93]
	v_mfma_f32_16x16x32_bf16 v[82:85], v[150:153], v[212:215], v[82:85]
	v_mfma_f32_16x16x32_bf16 v[74:77], v[164:167], v[212:215], v[74:77]
	v_mfma_f32_16x16x32_bf16 v[118:121], v[168:171], v[184:187], v[118:121]
	v_mfma_f32_16x16x32_bf16 v[110:113], v[176:179], v[184:187], v[110:113]
	v_mfma_f32_16x16x32_bf16 v[102:105], v[168:171], v[192:195], v[102:105]
	v_mfma_f32_16x16x32_bf16 v[94:97], v[176:179], v[192:195], v[94:97]
	v_mfma_f32_16x16x32_bf16 v[86:89], v[168:171], v[200:203], v[86:89]
	v_mfma_f32_16x16x32_bf16 v[78:81], v[176:179], v[200:203], v[78:81]
	v_mfma_f32_16x16x32_bf16 v[70:73], v[168:171], v[208:211], v[70:73]
	v_mfma_f32_16x16x32_bf16 v[66:69], v[176:179], v[208:211], v[66:69]
	v_mfma_f32_16x16x32_bf16 v[118:121], v[172:175], v[188:191], v[118:121]
	v_mfma_f32_16x16x32_bf16 v[110:113], v[180:183], v[188:191], v[110:113]
	v_mfma_f32_16x16x32_bf16 v[102:105], v[172:175], v[196:199], v[102:105]
	v_mfma_f32_16x16x32_bf16 v[94:97], v[180:183], v[196:199], v[94:97]
	v_mfma_f32_16x16x32_bf16 v[86:89], v[172:175], v[204:207], v[86:89]
	v_mfma_f32_16x16x32_bf16 v[78:81], v[180:183], v[204:207], v[78:81]
	v_mfma_f32_16x16x32_bf16 v[70:73], v[172:175], v[212:215], v[70:73]
	v_mfma_f32_16x16x32_bf16 v[66:69], v[180:183], v[212:215], v[66:69]
	s_barrier
	s_setprio 1
	s_add_i32 s18, s18, s52
	s_mov_b32 m0, s18
	ds_read_b128 v[184:187], v158 offset:49152
	ds_read_b128 v[188:191], v158 offset:50176
	ds_read_b128 v[192:195], v158 offset:51200
	ds_read_b128 v[196:199], v158 offset:52224
	ds_read_b128 v[200:203], v158 offset:53248
	ds_read_b128 v[204:207], v158 offset:54272
	ds_read_b128 v[208:211], v158 offset:55296
	ds_read_b128 v[212:215], v158 offset:56320
	global_load_lds_dwordx4 v134, s[78:79]
	s_add_i32 m0, s18, 0x2000
	s_add_u32 s44, s44, 0x40080
	s_addc_u32 s45, s45, 0
	s_add_i32 s18, s19, s52
	global_load_lds_dwordx4 v130, s[78:79]
	s_mov_b32 m0, s18
	s_nop 0
	global_load_lds_dwordx4 v134, s[44:45]
	s_add_i32 m0, s18, 0x2000
	s_nop 0
	global_load_lds_dwordx4 v130, s[44:45]
	s_mov_b32 m0, s60
	s_nop 0
	global_load_lds_dwordx4 v136, s[80:81]
	s_mov_b32 m0, s61
	s_nop 0
	global_load_lds_dwordx4 v132, s[80:81]
	s_waitcnt vmcnt(8)
	s_waitcnt lgkmcnt(0)
	s_barrier
	s_setprio 0
	v_mfma_f32_16x16x32_bf16 v[62:65], v[146:149], v[184:187], v[62:65]
	v_mfma_f32_16x16x32_bf16 v[58:61], v[160:163], v[184:187], v[58:61]
	v_mfma_f32_16x16x32_bf16 v[50:53], v[146:149], v[192:195], v[50:53]
	v_mfma_f32_16x16x32_bf16 v[42:45], v[160:163], v[192:195], v[42:45]
	v_mfma_f32_16x16x32_bf16 v[34:37], v[146:149], v[200:203], v[34:37]
	v_mfma_f32_16x16x32_bf16 v[26:29], v[160:163], v[200:203], v[26:29]
	v_mfma_f32_16x16x32_bf16 v[18:21], v[146:149], v[208:211], v[18:21]
	v_mfma_f32_16x16x32_bf16 v[10:13], v[160:163], v[208:211], v[10:13]
	v_mfma_f32_16x16x32_bf16 v[62:65], v[150:153], v[188:191], v[62:65]
	v_mfma_f32_16x16x32_bf16 v[58:61], v[164:167], v[188:191], v[58:61]
	v_mfma_f32_16x16x32_bf16 v[50:53], v[150:153], v[196:199], v[50:53]
	v_mfma_f32_16x16x32_bf16 v[42:45], v[164:167], v[196:199], v[42:45]
	v_mfma_f32_16x16x32_bf16 v[34:37], v[150:153], v[204:207], v[34:37]
	v_mfma_f32_16x16x32_bf16 v[26:29], v[164:167], v[204:207], v[26:29]
	v_mfma_f32_16x16x32_bf16 v[18:21], v[150:153], v[212:215], v[18:21]
	v_mfma_f32_16x16x32_bf16 v[10:13], v[164:167], v[212:215], v[10:13]
	v_mfma_f32_16x16x32_bf16 v[54:57], v[168:171], v[184:187], v[54:57]
	v_mfma_f32_16x16x32_bf16 v[46:49], v[176:179], v[184:187], v[46:49]
	v_mfma_f32_16x16x32_bf16 v[38:41], v[168:171], v[192:195], v[38:41]
	v_mfma_f32_16x16x32_bf16 v[30:33], v[176:179], v[192:195], v[30:33]
	v_mfma_f32_16x16x32_bf16 v[22:25], v[168:171], v[200:203], v[22:25]
	v_mfma_f32_16x16x32_bf16 v[14:17], v[176:179], v[200:203], v[14:17]
	v_mfma_f32_16x16x32_bf16 v[6:9], v[168:171], v[208:211], v[6:9]
	v_mfma_f32_16x16x32_bf16 v[2:5], v[176:179], v[208:211], v[2:5]
	v_mfma_f32_16x16x32_bf16 v[54:57], v[172:175], v[188:191], v[54:57]
	v_mfma_f32_16x16x32_bf16 v[46:49], v[180:183], v[188:191], v[46:49]
	v_mfma_f32_16x16x32_bf16 v[38:41], v[172:175], v[196:199], v[38:41]
	v_mfma_f32_16x16x32_bf16 v[30:33], v[180:183], v[196:199], v[30:33]
	v_mfma_f32_16x16x32_bf16 v[22:25], v[172:175], v[204:207], v[22:25]
	v_mfma_f32_16x16x32_bf16 v[14:17], v[180:183], v[204:207], v[14:17]
	v_mfma_f32_16x16x32_bf16 v[6:9], v[172:175], v[212:215], v[6:9]
	v_mfma_f32_16x16x32_bf16 v[2:5], v[180:183], v[212:215], v[2:5]
	s_barrier
	s_add_i32 s72, s72, 2
	s_add_u32 s42, s42, 0x100
	s_addc_u32 s43, s43, 0
	s_add_u32 s70, s70, 0x100
	s_addc_u32 s71, s71, 0
	s_cmp_gt_u32 s72, 13
	s_cbranch_scc0 .LBB0_868
	s_and_b64 vcc, exec, s[14:15]
	s_cbranch_vccz .LBB0_871
	s_barrier

; #define PG8_STAGE(bufoff, gbase, voff) do { _Pragma("unroll") for (int _i = 0; _i < 2; ++_i) \
;         __builtin_amdgcn_global_load_lds((const unsigned*)((const char*)(gbase) + (voff)[_i]), (PG8_LAS unsigned*)(lds + (bufoff) + ldsw + _i * 8192), 16, 0, 0); } while (0)
; #define PG8_LDA(dst, b, h) do { _Pragma("unroll") for (int m = 0; m < 4; ++m) _Pragma("unroll") for (int k = 0; k < 2; ++k) dst[m][k] = *(const PG8_LAS bf16x8*)(lds + PG8_SA(b, h) + aoff + m * 2048 + k * 1024); } while (0)
; #define PG8_LDB(dst, b, h) do { _Pragma("unroll") for (int n = 0; n < 2; ++n) _Pragma("unroll") for (int k = 0; k < 2; ++k) dst[n][k] = *(const PG8_LAS bf16x8*)(lds + PG8_SB(b, h) + boff + n * 2048 + k * 1024); } while (0)
; #define PG8_WAIT_V(n) asm volatile("s_waitcnt vmcnt(" #n ")" ::: "memory")
; #define PG8_WAIT_L(n) asm volatile("s_waitcnt lgkmcnt(" #n ")" ::: "memory")
; #define PG8_BAR __builtin_amdgcn_s_barrier()
; #define PG8_SCHED __builtin_amdgcn_sched_barrier(0)
; template <class Epi, class Sched, bool ALIGN_EPI = false, bool SP2 = false>
; __device__ __forceinline__ void gemm_phase(PG8_LAS unsigned char* lds, const Gemm g, const Sched& S, const Epi& E) {
;     ...
;         const char* nA = has_next ? (const char*)g.A + (size_t)nxt.pm * tA + (size_t)nxt.pn * pnA : cA; const char* nB = has_next ? (const char*)g.Bt + (size_t)nxt.pn * tB : cB;
; #pragma nounroll
;         for (int t = 0; t < nt; t += 2) {
;             const bool last = (t == nt - 2);
;             const char* a1 = cA + (size_t)(t + 1) * kstep;
;             const char* a2 = last ? nA : cA + (size_t)(t + 2) * kstep; const char* b2 = last ? nB : cB + (size_t)(t + 2) * kstep;
;             const char* a3 = a2 + kstep; const char* b3 = b2 + kstep;
;             if (last && has_next) S.a_ready(nxt);
;             if constexpr (SP2) {
;             PG8_LDB(B0, 0, 0); PG8_LDB(B1, 0, 1); PG8_SCHED; PG8_LDA(At, 0, 0); PG8_STAGE(PG8_SA(1, 1), a1 + hA, voffA);
;             PG8_WAIT_V(8); PG8_WAIT_L(0); PG8_BAR; PG8_MMA(0, 0, At, B0); PG8_MMA(0, 1, At, B1); PG8_BAR; PG8_SCHED;
;             PG8_LDA(At, 0, 1); PG8_STAGE(PG8_SB(0, 0), b2, voffB); PG8_STAGE(PG8_SB(0, 1), b2 + hB, voffB); PG8_STAGE(PG8_SA(0, 0), a2, voffA);
;             PG8_WAIT_V(8); PG8_WAIT_L(0); PG8_BAR; PG8_MMA(1, 0, At, B0); PG8_MMA(1, 1, At, B1); PG8_BAR; PG8_SCHED;
.LBB0_887:
	s_ashr_i32 s25, s24, 31
	s_lshl_b64 s[38:39], s[24:25], 20
	s_add_u32 s38, s33, s38
	s_addc_u32 s39, s51, s39
	s_and_b64 s[40:41], s[6:7], exec
	s_cselect_b32 s25, s39, s45
	s_cselect_b32 s70, s38, s44
	s_ashr_i32 s23, s22, 31
	s_lshl_b64 s[40:41], s[22:23], 20
	s_add_u32 s40, s52, s40
	s_addc_u32 s41, s53, s41
	s_and_b64 s[48:49], s[6:7], exec
	s_cselect_b32 s23, s41, s47
	s_cselect_b32 s71, s40, s46
	s_add_u32 s44, s44, 0x80080
	s_addc_u32 s45, s45, 0
	s_add_u32 s72, s46, 0x100
	v_mov_b32_e32 v2, 0
	s_addc_u32 s73, s47, 0
	s_mov_b32 s74, -2
	v_mov_b32_e32 v3, v2
	s_setprio 1
	ds_read_b128 v[130:133], v172
	ds_read_b128 v[134:137], v172 offset:1024
	ds_read_b128 v[138:141], v172 offset:2048
	ds_read_b128 v[142:145], v172 offset:3072
	ds_read_b128 v[162:165], v173
	ds_read_b128 v[166:169], v173 offset:1024
	ds_read_b128 v[176:179], v173 offset:2048
	ds_read_b128 v[180:183], v173 offset:3072
	s_add_u32 s18, s44, 0xfff80080
	s_addc_u32 s19, s45, -1
	s_cmp_eq_u32 s74, 28
	s_cselect_b32 s49, s25, s19
	s_cselect_b32 s48, s70, s18
	s_cselect_b32 s47, s23, s73
	s_cselect_b32 s46, s71, s72
	s_add_i32 m0, s43, 0xc000
	ds_read_b128 v[184:187], v174
	ds_read_b128 v[188:191], v174 offset:1024
	ds_read_b128 v[192:195], v174 offset:2048
	ds_read_b128 v[196:199], v174 offset:3072
	ds_read_b128 v[200:203], v174 offset:4096
	ds_read_b128 v[204:207], v174 offset:5120
	ds_read_b128 v[208:211], v174 offset:6144
	ds_read_b128 v[212:215], v174 offset:7168
	global_load_lds_dwordx4 v154, s[44:45]
	s_add_i32 m0, s43, 0xe000
	s_nop 0
	global_load_lds_dwordx4 v156, s[44:45]
	s_waitcnt vmcnt(8)
	s_waitcnt lgkmcnt(0)
	s_barrier
	s_setprio 0
	v_mfma_f32_16x16x32_bf16 v[126:129], v[130:133], v[184:187], 0
	v_mfma_f32_16x16x32_bf16 v[122:125], v[138:141], v[184:187], 0
	v_mfma_f32_16x16x32_bf16 v[110:113], v[130:133], v[192:195], 0
	v_mfma_f32_16x16x32_bf16 v[106:109], v[138:141], v[192:195], 0
	v_mfma_f32_16x16x32_bf16 v[94:97], v[130:133], v[200:203], 0
	v_mfma_f32_16x16x32_bf16 v[90:93], v[138:141], v[200:203], 0
	v_mfma_f32_16x16x32_bf16 v[78:81], v[130:133], v[208:211], 0
	v_mfma_f32_16x16x32_bf16 v[74:77], v[138:141], v[208:211], 0
	v_mfma_f32_16x16x32_bf16 v[126:129], v[134:137], v[188:191], v[126:129]
	v_mfma_f32_16x16x32_bf16 v[122:125], v[142:145], v[188:191], v[122:125]
	v_mfma_f32_16x16x32_bf16 v[110:113], v[134:137], v[196:199], v[110:113]
	v_mfma_f32_16x16x32_bf16 v[106:109], v[142:145], v[196:199], v[106:109]
	v_mfma_f32_16x16x32_bf16 v[94:97], v[134:137], v[204:207], v[94:97]
	v_mfma_f32_16x16x32_bf16 v[90:93], v[142:145], v[204:207], v[90:93]
	v_mfma_f32_16x16x32_bf16 v[78:81], v[134:137], v[212:215], v[78:81]
	v_mfma_f32_16x16x32_bf16 v[74:77], v[142:145], v[212:215], v[74:77]
	v_mfma_f32_16x16x32_bf16 v[118:121], v[162:165], v[184:187], 0
	v_mfma_f32_16x16x32_bf16 v[114:117], v[176:179], v[184:187], 0
	v_mfma_f32_16x16x32_bf16 v[102:105], v[162:165], v[192:195], 0
	v_mfma_f32_16x16x32_bf16 v[98:101], v[176:179], v[192:195], 0
	v_mfma_f32_16x16x32_bf16 v[86:89], v[162:165], v[200:203], 0
	v_mfma_f32_16x16x32_bf16 v[82:85], v[176:179], v[200:203], 0
	v_mfma_f32_16x16x32_bf16 v[70:73], v[162:165], v[208:211], 0
	v_mfma_f32_16x16x32_bf16 v[66:69], v[176:179], v[208:211], 0
	v_mfma_f32_16x16x32_bf16 v[118:121], v[166:169], v[188:191], v[118:121]
	v_mfma_f32_16x16x32_bf16 v[114:117], v[180:183], v[188:191], v[114:117]
	v_mfma_f32_16x16x32_bf16 v[102:105], v[166:169], v[196:199], v[102:105]
	v_mfma_f32_16x16x32_bf16 v[98:101], v[180:183], v[196:199], v[98:101]
	v_mfma_f32_16x16x32_bf16 v[86:89], v[166:169], v[204:207], v[86:89]
	v_mfma_f32_16x16x32_bf16 v[82:85], v[180:183], v[204:207], v[82:85]
	v_mfma_f32_16x16x32_bf16 v[70:73], v[166:169], v[212:215], v[70:73]
	v_mfma_f32_16x16x32_bf16 v[66:69], v[180:183], v[212:215], v[66:69]
	s_barrier
	s_setprio 1
	s_add_i32 s18, s66, s58
	s_add_u32 s78, s46, s16
	s_addc_u32 s79, s47, s17
	s_mov_b32 m0, s18
	ds_read_b128 v[184:187], v174 offset:16384
	ds_read_b128 v[188:191], v174 offset:17408
	ds_read_b128 v[192:195], v174 offset:18432
	ds_read_b128 v[196:199], v174 offset:19456
	ds_read_b128 v[200:203], v174 offset:20480
	ds_read_b128 v[204:207], v174 offset:21504
	ds_read_b128 v[208:211], v174 offset:22528
	ds_read_b128 v[212:215], v174 offset:23552
	global_load_lds_dwordx4 v150, s[46:47]
	s_add_i32 m0, s18, 0x2000
	s_add_u32 s76, s46, 0x80000
	s_addc_u32 s77, s47, 0
	s_add_i32 s18, s67, s58
	global_load_lds_dwordx4 v146, s[46:47]
	s_mov_b32 m0, s18
	s_nop 0
	global_load_lds_dwordx4 v150, s[76:77]
	s_add_i32 m0, s18, 0x2000
	s_nop 0
	global_load_lds_dwordx4 v146, s[76:77]
	s_add_u32 s80, s48, s16
	s_addc_u32 s81, s49, s17
	s_mov_b32 m0, s43
	s_nop 0
	global_load_lds_dwordx4 v152, s[48:49]
	s_mov_b32 m0, s59
	s_nop 0
	global_load_lds_dwordx4 v148, s[48:49]
	s_waitcnt vmcnt(8)
	s_waitcnt lgkmcnt(0)
	s_barrier
; #define PG8_STAGE(bufoff, gbase, voff) do { _Pragma("unroll") for (int _i = 0; _i < 2; ++_i) \
;         __builtin_amdgcn_global_load_lds((const unsigned*)((const char*)(gbase) + (voff)[_i]), (PG8_LAS unsigned*)(lds + (bufoff) + ldsw + _i * 8192), 16, 0, 0); } while (0)
; #define PG8_LDA(dst, b, h) do { _Pragma("unroll") for (int m = 0; m < 4; ++m) _Pragma("unroll") for (int k = 0; k < 2; ++k) dst[m][k] = *(const PG8_LAS bf16x8*)(lds + PG8_SA(b, h) + aoff + m * 2048 + k * 1024); } while (0)
; #define PG8_LDB(dst, b, h) do { _Pragma("unroll") for (int n = 0; n < 2; ++n) _Pragma("unroll") for (int k = 0; k < 2; ++k) dst[n][k] = *(const PG8_LAS bf16x8*)(lds + PG8_SB(b, h) + boff + n * 2048 + k * 1024); } while (0)
; #define PG8_MMA(ai, bj, At, Bt) do { __builtin_amdgcn_s_setprio(1); _Pragma("unroll") for (int m = 0; m < 4; ++m) _Pragma("unroll") for (int n = 0; n < 2; ++n) _Pragma("unroll") for (int k = 0; k < 2; ++k) \
;         acc[ai][bj][m][n] = __builtin_amdgcn_mfma_f32_16x16x32_bf16(Bt[n][k], At[m][k], acc[ai][bj][m][n], 0, 0, 0); __builtin_amdgcn_s_setprio(0); } while (0)
; #define PG8_WAIT_V(n) asm volatile("s_waitcnt vmcnt(" #n ")" ::: "memory")
; #define PG8_WAIT_L(n) asm volatile("s_waitcnt lgkmcnt(" #n ")" ::: "memory")
; #define PG8_BAR __builtin_amdgcn_s_barrier()
; #define PG8_SCHED __builtin_amdgcn_sched_barrier(0)
; template <class Epi, class Sched, bool ALIGN_EPI = false, bool SP2 = false>
; __device__ __forceinline__ void gemm_phase(PG8_LAS unsigned char* lds, const Gemm g, const Sched& S, const Epi& E) {
;     ...
;             PG8_WAIT_V(8); PG8_WAIT_L(0); PG8_BAR; PG8_MMA(1, 0, At, B0); PG8_MMA(1, 1, At, B1); PG8_BAR; PG8_SCHED;
;             PG8_LDB(B0, 1, 0); PG8_LDB(B1, 1, 1); PG8_SCHED; PG8_LDA(At, 1, 0); PG8_STAGE(PG8_SA(0, 1), a2 + hA, voffA);
;             PG8_WAIT_V(8); PG8_WAIT_L(0); PG8_BAR; PG8_MMA(0, 0, At, B0); PG8_MMA(0, 1, At, B1); PG8_BAR; PG8_SCHED;
	s_setprio 0
	v_mfma_f32_16x16x32_bf16 v[62:65], v[130:133], v[184:187], 0
	v_mfma_f32_16x16x32_bf16 v[58:61], v[138:141], v[184:187], 0
	v_mfma_f32_16x16x32_bf16 v[46:49], v[130:133], v[192:195], 0
	v_mfma_f32_16x16x32_bf16 v[42:45], v[138:141], v[192:195], 0
	v_mfma_f32_16x16x32_bf16 v[30:33], v[130:133], v[200:203], 0
	v_mfma_f32_16x16x32_bf16 v[26:29], v[138:141], v[200:203], 0
	v_mfma_f32_16x16x32_bf16 v[14:17], v[130:133], v[208:211], 0
	v_mfma_f32_16x16x32_bf16 v[10:13], v[138:141], v[208:211], 0
	v_mfma_f32_16x16x32_bf16 v[62:65], v[134:137], v[188:191], v[62:65]
	v_mfma_f32_16x16x32_bf16 v[58:61], v[142:145], v[188:191], v[58:61]
	v_mfma_f32_16x16x32_bf16 v[46:49], v[134:137], v[196:199], v[46:49]
	v_mfma_f32_16x16x32_bf16 v[42:45], v[142:145], v[196:199], v[42:45]
	v_mfma_f32_16x16x32_bf16 v[30:33], v[134:137], v[204:207], v[30:33]
	v_mfma_f32_16x16x32_bf16 v[26:29], v[142:145], v[204:207], v[26:29]
	v_mfma_f32_16x16x32_bf16 v[14:17], v[134:137], v[212:215], v[14:17]
	v_mfma_f32_16x16x32_bf16 v[10:13], v[142:145], v[212:215], v[10:13]
	v_mfma_f32_16x16x32_bf16 v[54:57], v[162:165], v[184:187], 0
	v_mfma_f32_16x16x32_bf16 v[50:53], v[176:179], v[184:187], 0
	v_mfma_f32_16x16x32_bf16 v[38:41], v[162:165], v[192:195], 0
	v_mfma_f32_16x16x32_bf16 v[34:37], v[176:179], v[192:195], 0
	v_mfma_f32_16x16x32_bf16 v[22:25], v[162:165], v[200:203], 0
	v_mfma_f32_16x16x32_bf16 v[18:21], v[176:179], v[200:203], 0
	v_mfma_f32_16x16x32_bf16 v[6:9], v[162:165], v[208:211], 0
	v_mfma_f32_16x16x32_bf16 v[2:5], v[176:179], v[208:211], 0
	v_mfma_f32_16x16x32_bf16 v[54:57], v[166:169], v[188:191], v[54:57]
	v_mfma_f32_16x16x32_bf16 v[50:53], v[180:183], v[188:191], v[50:53]
	v_mfma_f32_16x16x32_bf16 v[38:41], v[166:169], v[196:199], v[38:41]
	v_mfma_f32_16x16x32_bf16 v[34:37], v[180:183], v[196:199], v[34:37]
	v_mfma_f32_16x16x32_bf16 v[22:25], v[166:169], v[204:207], v[22:25]
	v_mfma_f32_16x16x32_bf16 v[18:21], v[180:183], v[204:207], v[18:21]
	v_mfma_f32_16x16x32_bf16 v[6:9], v[166:169], v[212:215], v[6:9]
	v_mfma_f32_16x16x32_bf16 v[2:5], v[180:183], v[212:215], v[2:5]
	s_barrier
	s_setprio 1
	s_add_i32 s18, 0, 0x18000
	s_add_i32 s19, 0, 0x1c000
	v_add_u32_e32 v142, s18, v170
	v_add_u32_e32 v175, s19, v170
	ds_read_b128 v[130:133], v142
	ds_read_b128 v[134:137], v142 offset:1024
	ds_read_b128 v[138:141], v142 offset:2048
	ds_read_b128 v[142:145], v142 offset:3072
	ds_read_b128 v[162:165], v175
	ds_read_b128 v[166:169], v175 offset:1024
	ds_read_b128 v[176:179], v175 offset:2048
	ds_read_b128 v[180:183], v175 offset:3072
	s_add_u32 s48, s48, 0x80000
	s_addc_u32 s49, s49, 0
	s_mov_b32 m0, s60
	ds_read_b128 v[184:187], v174 offset:32768
	ds_read_b128 v[188:191], v174 offset:33792
	ds_read_b128 v[192:195], v174 offset:34816
	ds_read_b128 v[196:199], v174 offset:35840
	ds_read_b128 v[200:203], v174 offset:36864
	ds_read_b128 v[204:207], v174 offset:37888
	ds_read_b128 v[208:211], v174 offset:38912
	ds_read_b128 v[212:215], v174 offset:39936
	global_load_lds_dwordx4 v152, s[48:49]
	s_mov_b32 m0, s61
	s_nop 0
	global_load_lds_dwordx4 v148, s[48:49]
	s_waitcnt vmcnt(8)
	s_waitcnt lgkmcnt(0)
	s_barrier
	s_setprio 0
	v_mfma_f32_16x16x32_bf16 v[126:129], v[130:133], v[184:187], v[126:129]
	v_mfma_f32_16x16x32_bf16 v[122:125], v[138:141], v[184:187], v[122:125]
	v_mfma_f32_16x16x32_bf16 v[110:113], v[130:133], v[192:195], v[110:113]
	v_mfma_f32_16x16x32_bf16 v[106:109], v[138:141], v[192:195], v[106:109]
	v_mfma_f32_16x16x32_bf16 v[94:97], v[130:133], v[200:203], v[94:97]
	v_mfma_f32_16x16x32_bf16 v[90:93], v[138:141], v[200:203], v[90:93]
	v_mfma_f32_16x16x32_bf16 v[78:81], v[130:133], v[208:211], v[78:81]
	v_mfma_f32_16x16x32_bf16 v[74:77], v[138:141], v[208:211], v[74:77]
	v_mfma_f32_16x16x32_bf16 v[126:129], v[134:137], v[188:191], v[126:129]
	v_mfma_f32_16x16x32_bf16 v[122:125], v[142:145], v[188:191], v[122:125]
	v_mfma_f32_16x16x32_bf16 v[110:113], v[134:137], v[196:199], v[110:113]
	v_mfma_f32_16x16x32_bf16 v[106:109], v[142:145], v[196:199], v[106:109]
	v_mfma_f32_16x16x32_bf16 v[94:97], v[134:137], v[204:207], v[94:97]
	v_mfma_f32_16x16x32_bf16 v[90:93], v[142:145], v[204:207], v[90:93]
	v_mfma_f32_16x16x32_bf16 v[78:81], v[134:137], v[212:215], v[78:81]
	v_mfma_f32_16x16x32_bf16 v[74:77], v[142:145], v[212:215], v[74:77]
	v_mfma_f32_16x16x32_bf16 v[118:121], v[162:165], v[184:187], v[118:121]
	v_mfma_f32_16x16x32_bf16 v[114:117], v[176:179], v[184:187], v[114:117]
	v_mfma_f32_16x16x32_bf16 v[102:105], v[162:165], v[192:195], v[102:105]
	v_mfma_f32_16x16x32_bf16 v[98:101], v[176:179], v[192:195], v[98:101]
	v_mfma_f32_16x16x32_bf16 v[86:89], v[162:165], v[200:203], v[86:89]
	v_mfma_f32_16x16x32_bf16 v[82:85], v[176:179], v[200:203], v[82:85]
	v_mfma_f32_16x16x32_bf16 v[70:73], v[162:165], v[208:211], v[70:73]
	v_mfma_f32_16x16x32_bf16 v[66:69], v[176:179], v[208:211], v[66:69]
	v_mfma_f32_16x16x32_bf16 v[118:121], v[166:169], v[188:191], v[118:121]
	v_mfma_f32_16x16x32_bf16 v[114:117], v[180:183], v[188:191], v[114:117]
	v_mfma_f32_16x16x32_bf16 v[102:105], v[166:169], v[196:199], v[102:105]
	v_mfma_f32_16x16x32_bf16 v[98:101], v[180:183], v[196:199], v[98:101]
	v_mfma_f32_16x16x32_bf16 v[86:89], v[166:169], v[204:207], v[86:89]
	v_mfma_f32_16x16x32_bf16 v[82:85], v[180:183], v[204:207], v[82:85]
	v_mfma_f32_16x16x32_bf16 v[70:73], v[166:169], v[212:215], v[70:73]
	v_mfma_f32_16x16x32_bf16 v[66:69], v[180:183], v[212:215], v[66:69]
	s_barrier
; #define PG8_STAGE(bufoff, gbase, voff) do { _Pragma("unroll") for (int _i = 0; _i < 2; ++_i) \
;         __builtin_amdgcn_global_load_lds((const unsigned*)((const char*)(gbase) + (voff)[_i]), (PG8_LAS unsigned*)(lds + (bufoff) + ldsw + _i * 8192), 16, 0, 0); } while (0)
; #define PG8_LDA(dst, b, h) do { _Pragma("unroll") for (int m = 0; m < 4; ++m) _Pragma("unroll") for (int k = 0; k < 2; ++k) dst[m][k] = *(const PG8_LAS bf16x8*)(lds + PG8_SA(b, h) + aoff + m * 2048 + k * 1024); } while (0)
; #define PG8_LDB(dst, b, h) do { _Pragma("unroll") for (int n = 0; n < 2; ++n) _Pragma("unroll") for (int k = 0; k < 2; ++k) dst[n][k] = *(const PG8_LAS bf16x8*)(lds + PG8_SB(b, h) + boff + n * 2048 + k * 1024); } while (0)
; #define PG8_MMA(ai, bj, At, Bt) do { __builtin_amdgcn_s_setprio(1); _Pragma("unroll") for (int m = 0; m < 4; ++m) _Pragma("unroll") for (int n = 0; n < 2; ++n) _Pragma("unroll") for (int k = 0; k < 2; ++k) \
;         acc[ai][bj][m][n] = __builtin_amdgcn_mfma_f32_16x16x32_bf16(Bt[n][k], At[m][k], acc[ai][bj][m][n], 0, 0, 0); __builtin_amdgcn_s_setprio(0); } while (0)
; #define PG8_WAIT_V(n) asm volatile("s_waitcnt vmcnt(" #n ")" ::: "memory")
; #define PG8_WAIT_L(n) asm volatile("s_waitcnt lgkmcnt(" #n ")" ::: "memory")
; #define PG8_BAR __builtin_amdgcn_s_barrier()
; #define PG8_SCHED __builtin_amdgcn_sched_barrier(0)
; template <class Epi, class Sched, bool ALIGN_EPI = false, bool SP2 = false>
; __device__ __forceinline__ void gemm_phase(PG8_LAS unsigned char* lds, const Gemm g, const Sched& S, const Epi& E) {
;     ...
;             PG8_LDB(B0, 0, 0); PG8_LDB(B1, 0, 1); PG8_SCHED; PG8_LDA(At, 0, 0); PG8_STAGE(PG8_SA(1, 1), a1 + hA, voffA);
;             PG8_WAIT_V(8); PG8_WAIT_L(0); PG8_BAR; PG8_MMA(0, 0, At, B0); PG8_MMA(0, 1, At, B1); PG8_BAR; PG8_SCHED;
;     ...
;             PG8_LDA(At, 1, 1); PG8_STAGE(PG8_SB(1, 0), b3, voffB); PG8_STAGE(PG8_SB(1, 1), b3 + hB, voffB); PG8_STAGE(PG8_SA(1, 0), a3, voffA);
;             PG8_WAIT_V(8); PG8_WAIT_L(0); PG8_BAR; PG8_MMA(1, 0, At, B0); PG8_MMA(1, 1, At, B1); PG8_BAR; PG8_SCHED;
	s_setprio 1
	s_add_i32 s18, s18, s58
	s_mov_b32 m0, s18
	ds_read_b128 v[184:187], v174 offset:49152
	ds_read_b128 v[188:191], v174 offset:50176
	ds_read_b128 v[192:195], v174 offset:51200
	ds_read_b128 v[196:199], v174 offset:52224
	ds_read_b128 v[200:203], v174 offset:53248
	ds_read_b128 v[204:207], v174 offset:54272
	ds_read_b128 v[208:211], v174 offset:55296
	ds_read_b128 v[212:215], v174 offset:56320
	global_load_lds_dwordx4 v150, s[78:79]
	s_add_i32 m0, s18, 0x2000
	s_add_u32 s46, s46, 0x80080
	s_addc_u32 s47, s47, 0
	s_add_i32 s18, s19, s58
	global_load_lds_dwordx4 v146, s[78:79]
	s_mov_b32 m0, s18
	s_nop 0
	global_load_lds_dwordx4 v150, s[46:47]
	s_add_i32 m0, s18, 0x2000
	s_nop 0
	global_load_lds_dwordx4 v146, s[46:47]
	s_mov_b32 m0, s63
	s_nop 0
	global_load_lds_dwordx4 v152, s[80:81]
	s_mov_b32 m0, s64
	s_nop 0
	global_load_lds_dwordx4 v148, s[80:81]
	s_waitcnt vmcnt(8)
	s_waitcnt lgkmcnt(0)
	s_barrier
	s_setprio 0
	v_mfma_f32_16x16x32_bf16 v[62:65], v[130:133], v[184:187], v[62:65]
	v_mfma_f32_16x16x32_bf16 v[58:61], v[138:141], v[184:187], v[58:61]
	v_mfma_f32_16x16x32_bf16 v[46:49], v[130:133], v[192:195], v[46:49]
	v_mfma_f32_16x16x32_bf16 v[42:45], v[138:141], v[192:195], v[42:45]
	v_mfma_f32_16x16x32_bf16 v[30:33], v[130:133], v[200:203], v[30:33]
	v_mfma_f32_16x16x32_bf16 v[26:29], v[138:141], v[200:203], v[26:29]
	v_mfma_f32_16x16x32_bf16 v[14:17], v[130:133], v[208:211], v[14:17]
	v_mfma_f32_16x16x32_bf16 v[10:13], v[138:141], v[208:211], v[10:13]
	v_mfma_f32_16x16x32_bf16 v[62:65], v[134:137], v[188:191], v[62:65]
	v_mfma_f32_16x16x32_bf16 v[58:61], v[142:145], v[188:191], v[58:61]
	v_mfma_f32_16x16x32_bf16 v[46:49], v[134:137], v[196:199], v[46:49]
	v_mfma_f32_16x16x32_bf16 v[42:45], v[142:145], v[196:199], v[42:45]
	v_mfma_f32_16x16x32_bf16 v[30:33], v[134:137], v[204:207], v[30:33]
	v_mfma_f32_16x16x32_bf16 v[26:29], v[142:145], v[204:207], v[26:29]
	v_mfma_f32_16x16x32_bf16 v[14:17], v[134:137], v[212:215], v[14:17]
	v_mfma_f32_16x16x32_bf16 v[10:13], v[142:145], v[212:215], v[10:13]
	v_mfma_f32_16x16x32_bf16 v[54:57], v[162:165], v[184:187], v[54:57]
	v_mfma_f32_16x16x32_bf16 v[50:53], v[176:179], v[184:187], v[50:53]
	v_mfma_f32_16x16x32_bf16 v[38:41], v[162:165], v[192:195], v[38:41]
	v_mfma_f32_16x16x32_bf16 v[34:37], v[176:179], v[192:195], v[34:37]
	v_mfma_f32_16x16x32_bf16 v[22:25], v[162:165], v[200:203], v[22:25]
	v_mfma_f32_16x16x32_bf16 v[18:21], v[176:179], v[200:203], v[18:21]
	v_mfma_f32_16x16x32_bf16 v[6:9], v[162:165], v[208:211], v[6:9]
	v_mfma_f32_16x16x32_bf16 v[2:5], v[176:179], v[208:211], v[2:5]
	v_mfma_f32_16x16x32_bf16 v[54:57], v[166:169], v[188:191], v[54:57]
	v_mfma_f32_16x16x32_bf16 v[50:53], v[180:183], v[188:191], v[50:53]
	v_mfma_f32_16x16x32_bf16 v[38:41], v[166:169], v[196:199], v[38:41]
	v_mfma_f32_16x16x32_bf16 v[34:37], v[180:183], v[196:199], v[34:37]
	v_mfma_f32_16x16x32_bf16 v[22:25], v[166:169], v[204:207], v[22:25]
	v_mfma_f32_16x16x32_bf16 v[18:21], v[180:183], v[204:207], v[18:21]
	v_mfma_f32_16x16x32_bf16 v[6:9], v[166:169], v[212:215], v[6:9]
	v_mfma_f32_16x16x32_bf16 v[2:5], v[180:183], v[212:215], v[2:5]
	s_barrier
	s_add_i32 s74, s74, 2
	s_add_u32 s44, s44, 0x100
	s_addc_u32 s45, s45, 0
	s_add_u32 s72, s72, 0x100
	s_addc_u32 s73, s73, 0
	s_cmp_gt_u32 s74, 29
.LBB0_888:
	s_setprio 1
	ds_read_b128 v[130:133], v172
	ds_read_b128 v[134:137], v172 offset:1024
	ds_read_b128 v[138:141], v172 offset:2048
	ds_read_b128 v[142:145], v172 offset:3072
	ds_read_b128 v[162:165], v173
	ds_read_b128 v[166:169], v173 offset:1024
	ds_read_b128 v[176:179], v173 offset:2048
	ds_read_b128 v[180:183], v173 offset:3072
	s_add_u32 s18, s44, 0xfff80080
	s_addc_u32 s19, s45, -1
	s_cmp_eq_u32 s74, 28
	s_cselect_b32 s49, s25, s19
	s_cselect_b32 s48, s70, s18
	s_cselect_b32 s47, s23, s73
	s_cselect_b32 s46, s71, s72
	s_add_i32 m0, s43, 0xc000
	ds_read_b128 v[184:187], v174
	ds_read_b128 v[188:191], v174 offset:1024
	ds_read_b128 v[192:195], v174 offset:2048
	ds_read_b128 v[196:199], v174 offset:3072
	ds_read_b128 v[200:203], v174 offset:4096
	ds_read_b128 v[204:207], v174 offset:5120
	ds_read_b128 v[208:211], v174 offset:6144
	ds_read_b128 v[212:215], v174 offset:7168
	global_load_lds_dwordx4 v154, s[44:45]
	s_add_i32 m0, s43, 0xe000
	s_nop 0
	global_load_lds_dwordx4 v156, s[44:45]
	s_waitcnt vmcnt(8)
	s_waitcnt lgkmcnt(0)
	s_barrier
	s_setprio 0
	v_mfma_f32_16x16x32_bf16 v[126:129], v[130:133], v[184:187], v[126:129]
	v_mfma_f32_16x16x32_bf16 v[122:125], v[138:141], v[184:187], v[122:125]
	v_mfma_f32_16x16x32_bf16 v[110:113], v[130:133], v[192:195], v[110:113]
	v_mfma_f32_16x16x32_bf16 v[106:109], v[138:141], v[192:195], v[106:109]
	v_mfma_f32_16x16x32_bf16 v[94:97], v[130:133], v[200:203], v[94:97]
	v_mfma_f32_16x16x32_bf16 v[90:93], v[138:141], v[200:203], v[90:93]
	v_mfma_f32_16x16x32_bf16 v[78:81], v[130:133], v[208:211], v[78:81]
	v_mfma_f32_16x16x32_bf16 v[74:77], v[138:141], v[208:211], v[74:77]
	v_mfma_f32_16x16x32_bf16 v[126:129], v[134:137], v[188:191], v[126:129]
	v_mfma_f32_16x16x32_bf16 v[122:125], v[142:145], v[188:191], v[122:125]
	v_mfma_f32_16x16x32_bf16 v[110:113], v[134:137], v[196:199], v[110:113]
	v_mfma_f32_16x16x32_bf16 v[106:109], v[142:145], v[196:199], v[106:109]
	v_mfma_f32_16x16x32_bf16 v[94:97], v[134:137], v[204:207], v[94:97]
	v_mfma_f32_16x16x32_bf16 v[90:93], v[142:145], v[204:207], v[90:93]
	v_mfma_f32_16x16x32_bf16 v[78:81], v[134:137], v[212:215], v[78:81]
	v_mfma_f32_16x16x32_bf16 v[74:77], v[142:145], v[212:215], v[74:77]
	v_mfma_f32_16x16x32_bf16 v[118:121], v[162:165], v[184:187], v[118:121]
	v_mfma_f32_16x16x32_bf16 v[114:117], v[176:179], v[184:187], v[114:117]
	v_mfma_f32_16x16x32_bf16 v[102:105], v[162:165], v[192:195], v[102:105]
	v_mfma_f32_16x16x32_bf16 v[98:101], v[176:179], v[192:195], v[98:101]
	v_mfma_f32_16x16x32_bf16 v[86:89], v[162:165], v[200:203], v[86:89]
	v_mfma_f32_16x16x32_bf16 v[82:85], v[176:179], v[200:203], v[82:85]
	v_mfma_f32_16x16x32_bf16 v[70:73], v[162:165], v[208:211], v[70:73]
	v_mfma_f32_16x16x32_bf16 v[66:69], v[176:179], v[208:211], v[66:69]
	v_mfma_f32_16x16x32_bf16 v[118:121], v[166:169], v[188:191], v[118:121]
	v_mfma_f32_16x16x32_bf16 v[114:117], v[180:183], v[188:191], v[114:117]
	v_mfma_f32_16x16x32_bf16 v[102:105], v[166:169], v[196:199], v[102:105]
	v_mfma_f32_16x16x32_bf16 v[98:101], v[180:183], v[196:199], v[98:101]
	v_mfma_f32_16x16x32_bf16 v[86:89], v[166:169], v[204:207], v[86:89]
	v_mfma_f32_16x16x32_bf16 v[82:85], v[180:183], v[204:207], v[82:85]
	v_mfma_f32_16x16x32_bf16 v[70:73], v[166:169], v[212:215], v[70:73]
	v_mfma_f32_16x16x32_bf16 v[66:69], v[180:183], v[212:215], v[66:69]
	s_barrier
; #define PG8_STAGE(bufoff, gbase, voff) do { _Pragma("unroll") for (int _i = 0; _i < 2; ++_i) \
;         __builtin_amdgcn_global_load_lds((const unsigned*)((const char*)(gbase) + (voff)[_i]), (PG8_LAS unsigned*)(lds + (bufoff) + ldsw + _i * 8192), 16, 0, 0); } while (0)
; #define PG8_LDA(dst, b, h) do { _Pragma("unroll") for (int m = 0; m < 4; ++m) _Pragma("unroll") for (int k = 0; k < 2; ++k) dst[m][k] = *(const PG8_LAS bf16x8*)(lds + PG8_SA(b, h) + aoff + m * 2048 + k * 1024); } while (0)
; #define PG8_LDB(dst, b, h) do { _Pragma("unroll") for (int n = 0; n < 2; ++n) _Pragma("unroll") for (int k = 0; k < 2; ++k) dst[n][k] = *(const PG8_LAS bf16x8*)(lds + PG8_SB(b, h) + boff + n * 2048 + k * 1024); } while (0)
; #define PG8_MMA(ai, bj, At, Bt) do { __builtin_amdgcn_s_setprio(1); _Pragma("unroll") for (int m = 0; m < 4; ++m) _Pragma("unroll") for (int n = 0; n < 2; ++n) _Pragma("unroll") for (int k = 0; k < 2; ++k) \
;         acc[ai][bj][m][n] = __builtin_amdgcn_mfma_f32_16x16x32_bf16(Bt[n][k], At[m][k], acc[ai][bj][m][n], 0, 0, 0); __builtin_amdgcn_s_setprio(0); } while (0)
; #define PG8_WAIT_V(n) asm volatile("s_waitcnt vmcnt(" #n ")" ::: "memory")
; #define PG8_WAIT_L(n) asm volatile("s_waitcnt lgkmcnt(" #n ")" ::: "memory")
; #define PG8_BAR __builtin_amdgcn_s_barrier()
; #define PG8_SCHED __builtin_amdgcn_sched_barrier(0)
; template <class Epi, class Sched, bool ALIGN_EPI = false, bool SP2 = false>
; __device__ __forceinline__ void gemm_phase(PG8_LAS unsigned char* lds, const Gemm g, const Sched& S, const Epi& E) {
;     ...
;             PG8_LDA(At, 0, 1); PG8_STAGE(PG8_SB(0, 0), b2, voffB); PG8_STAGE(PG8_SB(0, 1), b2 + hB, voffB); PG8_STAGE(PG8_SA(0, 0), a2, voffA);
;             PG8_WAIT_V(8); PG8_WAIT_L(0); PG8_BAR; PG8_MMA(1, 0, At, B0); PG8_MMA(1, 1, At, B1); PG8_BAR; PG8_SCHED;
;             PG8_LDB(B0, 1, 0); PG8_LDB(B1, 1, 1); PG8_SCHED; PG8_LDA(At, 1, 0); PG8_STAGE(PG8_SA(0, 1), a2 + hA, voffA);
	s_setprio 1
	s_add_i32 s18, s66, s58
	s_add_u32 s78, s46, s16
	s_addc_u32 s79, s47, s17
	s_mov_b32 m0, s18
	ds_read_b128 v[184:187], v174 offset:16384
	ds_read_b128 v[188:191], v174 offset:17408
	ds_read_b128 v[192:195], v174 offset:18432
	ds_read_b128 v[196:199], v174 offset:19456
	ds_read_b128 v[200:203], v174 offset:20480
	ds_read_b128 v[204:207], v174 offset:21504
	ds_read_b128 v[208:211], v174 offset:22528
	ds_read_b128 v[212:215], v174 offset:23552
	global_load_lds_dwordx4 v150, s[46:47]
	s_add_i32 m0, s18, 0x2000
	s_add_u32 s76, s46, 0x80000
	s_addc_u32 s77, s47, 0
	s_add_i32 s18, s67, s58
	global_load_lds_dwordx4 v146, s[46:47]
	s_mov_b32 m0, s18
	s_nop 0
	global_load_lds_dwordx4 v150, s[76:77]
	s_add_i32 m0, s18, 0x2000
	s_nop 0
	global_load_lds_dwordx4 v146, s[76:77]
	s_add_u32 s80, s48, s16
	s_addc_u32 s81, s49, s17
	s_mov_b32 m0, s43
	s_nop 0
	global_load_lds_dwordx4 v152, s[48:49]
	s_mov_b32 m0, s59
	s_nop 0
	global_load_lds_dwordx4 v148, s[48:49]
	s_waitcnt vmcnt(8)
	s_waitcnt lgkmcnt(0)
	s_barrier
	s_setprio 0
	v_mfma_f32_16x16x32_bf16 v[62:65], v[130:133], v[184:187], v[62:65]
	v_mfma_f32_16x16x32_bf16 v[58:61], v[138:141], v[184:187], v[58:61]
	v_mfma_f32_16x16x32_bf16 v[46:49], v[130:133], v[192:195], v[46:49]
	v_mfma_f32_16x16x32_bf16 v[42:45], v[138:141], v[192:195], v[42:45]
	v_mfma_f32_16x16x32_bf16 v[30:33], v[130:133], v[200:203], v[30:33]
	v_mfma_f32_16x16x32_bf16 v[26:29], v[138:141], v[200:203], v[26:29]
	v_mfma_f32_16x16x32_bf16 v[14:17], v[130:133], v[208:211], v[14:17]
	v_mfma_f32_16x16x32_bf16 v[10:13], v[138:141], v[208:211], v[10:13]
	v_mfma_f32_16x16x32_bf16 v[62:65], v[134:137], v[188:191], v[62:65]
	v_mfma_f32_16x16x32_bf16 v[58:61], v[142:145], v[188:191], v[58:61]
	v_mfma_f32_16x16x32_bf16 v[46:49], v[134:137], v[196:199], v[46:49]
	v_mfma_f32_16x16x32_bf16 v[42:45], v[142:145], v[196:199], v[42:45]
	v_mfma_f32_16x16x32_bf16 v[30:33], v[134:137], v[204:207], v[30:33]
	v_mfma_f32_16x16x32_bf16 v[26:29], v[142:145], v[204:207], v[26:29]
	v_mfma_f32_16x16x32_bf16 v[14:17], v[134:137], v[212:215], v[14:17]
	v_mfma_f32_16x16x32_bf16 v[10:13], v[142:145], v[212:215], v[10:13]
	v_mfma_f32_16x16x32_bf16 v[54:57], v[162:165], v[184:187], v[54:57]
	v_mfma_f32_16x16x32_bf16 v[50:53], v[176:179], v[184:187], v[50:53]
	v_mfma_f32_16x16x32_bf16 v[38:41], v[162:165], v[192:195], v[38:41]
	v_mfma_f32_16x16x32_bf16 v[34:37], v[176:179], v[192:195], v[34:37]
	v_mfma_f32_16x16x32_bf16 v[22:25], v[162:165], v[200:203], v[22:25]
	v_mfma_f32_16x16x32_bf16 v[18:21], v[176:179], v[200:203], v[18:21]
	v_mfma_f32_16x16x32_bf16 v[6:9], v[162:165], v[208:211], v[6:9]
	v_mfma_f32_16x16x32_bf16 v[2:5], v[176:179], v[208:211], v[2:5]
	v_mfma_f32_16x16x32_bf16 v[54:57], v[166:169], v[188:191], v[54:57]
	v_mfma_f32_16x16x32_bf16 v[50:53], v[180:183], v[188:191], v[50:53]
	v_mfma_f32_16x16x32_bf16 v[38:41], v[166:169], v[196:199], v[38:41]
	v_mfma_f32_16x16x32_bf16 v[34:37], v[180:183], v[196:199], v[34:37]
	v_mfma_f32_16x16x32_bf16 v[22:25], v[166:169], v[204:207], v[22:25]
	v_mfma_f32_16x16x32_bf16 v[18:21], v[180:183], v[204:207], v[18:21]
	v_mfma_f32_16x16x32_bf16 v[6:9], v[166:169], v[212:215], v[6:9]
	v_mfma_f32_16x16x32_bf16 v[2:5], v[180:183], v[212:215], v[2:5]
	s_barrier
	s_setprio 1
	s_add_i32 s18, 0, 0x18000
	s_add_i32 s19, 0, 0x1c000
	v_add_u32_e32 v142, s18, v170
	v_add_u32_e32 v175, s19, v170
	ds_read_b128 v[130:133], v142
	ds_read_b128 v[134:137], v142 offset:1024
	ds_read_b128 v[138:141], v142 offset:2048
	ds_read_b128 v[142:145], v142 offset:3072
	ds_read_b128 v[162:165], v175
	ds_read_b128 v[166:169], v175 offset:1024
	ds_read_b128 v[176:179], v175 offset:2048
	ds_read_b128 v[180:183], v175 offset:3072
	s_add_u32 s48, s48, 0x80000
	s_addc_u32 s49, s49, 0
	s_mov_b32 m0, s60
	ds_read_b128 v[184:187], v174 offset:32768
	ds_read_b128 v[188:191], v174 offset:33792
	ds_read_b128 v[192:195], v174 offset:34816
	ds_read_b128 v[196:199], v174 offset:35840
	ds_read_b128 v[200:203], v174 offset:36864
	ds_read_b128 v[204:207], v174 offset:37888
	ds_read_b128 v[208:211], v174 offset:38912
	ds_read_b128 v[212:215], v174 offset:39936
	global_load_lds_dwordx4 v152, s[48:49]
	s_mov_b32 m0, s61
	s_nop 0
	global_load_lds_dwordx4 v148, s[48:49]
	s_waitcnt vmcnt(8)
	s_waitcnt lgkmcnt(0)
	s_barrier
; #define PG8_STAGE(bufoff, gbase, voff) do { _Pragma("unroll") for (int _i = 0; _i < 2; ++_i) \
;         __builtin_amdgcn_global_load_lds((const unsigned*)((const char*)(gbase) + (voff)[_i]), (PG8_LAS unsigned*)(lds + (bufoff) + ldsw + _i * 8192), 16, 0, 0); } while (0)
; #define PG8_LDA(dst, b, h) do { _Pragma("unroll") for (int m = 0; m < 4; ++m) _Pragma("unroll") for (int k = 0; k < 2; ++k) dst[m][k] = *(const PG8_LAS bf16x8*)(lds + PG8_SA(b, h) + aoff + m * 2048 + k * 1024); } while (0)
; #define PG8_LDB(dst, b, h) do { _Pragma("unroll") for (int n = 0; n < 2; ++n) _Pragma("unroll") for (int k = 0; k < 2; ++k) dst[n][k] = *(const PG8_LAS bf16x8*)(lds + PG8_SB(b, h) + boff + n * 2048 + k * 1024); } while (0)
; #define PG8_MMA(ai, bj, At, Bt) do { __builtin_amdgcn_s_setprio(1); _Pragma("unroll") for (int m = 0; m < 4; ++m) _Pragma("unroll") for (int n = 0; n < 2; ++n) _Pragma("unroll") for (int k = 0; k < 2; ++k) \
;         acc[ai][bj][m][n] = __builtin_amdgcn_mfma_f32_16x16x32_bf16(Bt[n][k], At[m][k], acc[ai][bj][m][n], 0, 0, 0); __builtin_amdgcn_s_setprio(0); } while (0)
; #define PG8_WAIT_V(n) asm volatile("s_waitcnt vmcnt(" #n ")" ::: "memory")
; #define PG8_WAIT_L(n) asm volatile("s_waitcnt lgkmcnt(" #n ")" ::: "memory")
; #define PG8_BAR __builtin_amdgcn_s_barrier()
; #define PG8_SCHED __builtin_amdgcn_sched_barrier(0)
; template <class Epi, class Sched, bool ALIGN_EPI = false, bool SP2 = false>
; __device__ __forceinline__ void gemm_phase(PG8_LAS unsigned char* lds, const Gemm g, const Sched& S, const Epi& E) {
;     ...
;             PG8_LDB(B0, 1, 0); PG8_LDB(B1, 1, 1); PG8_SCHED; PG8_LDA(At, 1, 0); PG8_STAGE(PG8_SA(0, 1), a2 + hA, voffA);
;             PG8_WAIT_V(8); PG8_WAIT_L(0); PG8_BAR; PG8_MMA(0, 0, At, B0); PG8_MMA(0, 1, At, B1); PG8_BAR; PG8_SCHED;
;             PG8_LDA(At, 1, 1); PG8_STAGE(PG8_SB(1, 0), b3, voffB); PG8_STAGE(PG8_SB(1, 1), b3 + hB, voffB); PG8_STAGE(PG8_SA(1, 0), a3, voffA);
;             PG8_WAIT_V(8); PG8_WAIT_L(0); PG8_BAR; PG8_MMA(1, 0, At, B0); PG8_MMA(1, 1, At, B1); PG8_BAR; PG8_SCHED;
	s_setprio 0
	v_mfma_f32_16x16x32_bf16 v[126:129], v[130:133], v[184:187], v[126:129]
	v_mfma_f32_16x16x32_bf16 v[122:125], v[138:141], v[184:187], v[122:125]
	v_mfma_f32_16x16x32_bf16 v[110:113], v[130:133], v[192:195], v[110:113]
	v_mfma_f32_16x16x32_bf16 v[106:109], v[138:141], v[192:195], v[106:109]
	v_mfma_f32_16x16x32_bf16 v[94:97], v[130:133], v[200:203], v[94:97]
	v_mfma_f32_16x16x32_bf16 v[90:93], v[138:141], v[200:203], v[90:93]
	v_mfma_f32_16x16x32_bf16 v[78:81], v[130:133], v[208:211], v[78:81]
	v_mfma_f32_16x16x32_bf16 v[74:77], v[138:141], v[208:211], v[74:77]
	v_mfma_f32_16x16x32_bf16 v[126:129], v[134:137], v[188:191], v[126:129]
	v_mfma_f32_16x16x32_bf16 v[122:125], v[142:145], v[188:191], v[122:125]
	v_mfma_f32_16x16x32_bf16 v[110:113], v[134:137], v[196:199], v[110:113]
	v_mfma_f32_16x16x32_bf16 v[106:109], v[142:145], v[196:199], v[106:109]
	v_mfma_f32_16x16x32_bf16 v[94:97], v[134:137], v[204:207], v[94:97]
	v_mfma_f32_16x16x32_bf16 v[90:93], v[142:145], v[204:207], v[90:93]
	v_mfma_f32_16x16x32_bf16 v[78:81], v[134:137], v[212:215], v[78:81]
	v_mfma_f32_16x16x32_bf16 v[74:77], v[142:145], v[212:215], v[74:77]
	v_mfma_f32_16x16x32_bf16 v[118:121], v[162:165], v[184:187], v[118:121]
	v_mfma_f32_16x16x32_bf16 v[114:117], v[176:179], v[184:187], v[114:117]
	v_mfma_f32_16x16x32_bf16 v[102:105], v[162:165], v[192:195], v[102:105]
	v_mfma_f32_16x16x32_bf16 v[98:101], v[176:179], v[192:195], v[98:101]
	v_mfma_f32_16x16x32_bf16 v[86:89], v[162:165], v[200:203], v[86:89]
	v_mfma_f32_16x16x32_bf16 v[82:85], v[176:179], v[200:203], v[82:85]
	v_mfma_f32_16x16x32_bf16 v[70:73], v[162:165], v[208:211], v[70:73]
	v_mfma_f32_16x16x32_bf16 v[66:69], v[176:179], v[208:211], v[66:69]
	v_mfma_f32_16x16x32_bf16 v[118:121], v[166:169], v[188:191], v[118:121]
	v_mfma_f32_16x16x32_bf16 v[114:117], v[180:183], v[188:191], v[114:117]
	v_mfma_f32_16x16x32_bf16 v[102:105], v[166:169], v[196:199], v[102:105]
	v_mfma_f32_16x16x32_bf16 v[98:101], v[180:183], v[196:199], v[98:101]
	v_mfma_f32_16x16x32_bf16 v[86:89], v[166:169], v[204:207], v[86:89]
	v_mfma_f32_16x16x32_bf16 v[82:85], v[180:183], v[204:207], v[82:85]
	v_mfma_f32_16x16x32_bf16 v[70:73], v[166:169], v[212:215], v[70:73]
	v_mfma_f32_16x16x32_bf16 v[66:69], v[180:183], v[212:215], v[66:69]
	s_barrier
	s_setprio 1
	s_add_i32 s18, s18, s58
	s_mov_b32 m0, s18
	ds_read_b128 v[184:187], v174 offset:49152
	ds_read_b128 v[188:191], v174 offset:50176
	ds_read_b128 v[192:195], v174 offset:51200
	ds_read_b128 v[196:199], v174 offset:52224
	ds_read_b128 v[200:203], v174 offset:53248
	ds_read_b128 v[204:207], v174 offset:54272
	ds_read_b128 v[208:211], v174 offset:55296
	ds_read_b128 v[212:215], v174 offset:56320
	global_load_lds_dwordx4 v150, s[78:79]
	s_add_i32 m0, s18, 0x2000
	s_add_u32 s46, s46, 0x80080
	s_addc_u32 s47, s47, 0
	s_add_i32 s18, s19, s58
	global_load_lds_dwordx4 v146, s[78:79]
	s_mov_b32 m0, s18
	s_nop 0
	global_load_lds_dwordx4 v150, s[46:47]
	s_add_i32 m0, s18, 0x2000
	s_nop 0
	global_load_lds_dwordx4 v146, s[46:47]
	s_mov_b32 m0, s63
	s_nop 0
	global_load_lds_dwordx4 v152, s[80:81]
	s_mov_b32 m0, s64
	s_nop 0
	global_load_lds_dwordx4 v148, s[80:81]
	s_waitcnt vmcnt(8)
	s_waitcnt lgkmcnt(0)
	s_barrier
	s_setprio 0
	v_mfma_f32_16x16x32_bf16 v[62:65], v[130:133], v[184:187], v[62:65]
	v_mfma_f32_16x16x32_bf16 v[58:61], v[138:141], v[184:187], v[58:61]
	v_mfma_f32_16x16x32_bf16 v[46:49], v[130:133], v[192:195], v[46:49]
	v_mfma_f32_16x16x32_bf16 v[42:45], v[138:141], v[192:195], v[42:45]
	v_mfma_f32_16x16x32_bf16 v[30:33], v[130:133], v[200:203], v[30:33]
	v_mfma_f32_16x16x32_bf16 v[26:29], v[138:141], v[200:203], v[26:29]
	v_mfma_f32_16x16x32_bf16 v[14:17], v[130:133], v[208:211], v[14:17]
	v_mfma_f32_16x16x32_bf16 v[10:13], v[138:141], v[208:211], v[10:13]
	v_mfma_f32_16x16x32_bf16 v[62:65], v[134:137], v[188:191], v[62:65]
	v_mfma_f32_16x16x32_bf16 v[58:61], v[142:145], v[188:191], v[58:61]
	v_mfma_f32_16x16x32_bf16 v[46:49], v[134:137], v[196:199], v[46:49]
	v_mfma_f32_16x16x32_bf16 v[42:45], v[142:145], v[196:199], v[42:45]
	v_mfma_f32_16x16x32_bf16 v[30:33], v[134:137], v[204:207], v[30:33]
	v_mfma_f32_16x16x32_bf16 v[26:29], v[142:145], v[204:207], v[26:29]
	v_mfma_f32_16x16x32_bf16 v[14:17], v[134:137], v[212:215], v[14:17]
	v_mfma_f32_16x16x32_bf16 v[10:13], v[142:145], v[212:215], v[10:13]
	v_mfma_f32_16x16x32_bf16 v[54:57], v[162:165], v[184:187], v[54:57]
	v_mfma_f32_16x16x32_bf16 v[50:53], v[176:179], v[184:187], v[50:53]
	v_mfma_f32_16x16x32_bf16 v[38:41], v[162:165], v[192:195], v[38:41]
	v_mfma_f32_16x16x32_bf16 v[34:37], v[176:179], v[192:195], v[34:37]
	v_mfma_f32_16x16x32_bf16 v[22:25], v[162:165], v[200:203], v[22:25]
	v_mfma_f32_16x16x32_bf16 v[18:21], v[176:179], v[200:203], v[18:21]
	v_mfma_f32_16x16x32_bf16 v[6:9], v[162:165], v[208:211], v[6:9]
	v_mfma_f32_16x16x32_bf16 v[2:5], v[176:179], v[208:211], v[2:5]
	v_mfma_f32_16x16x32_bf16 v[54:57], v[166:169], v[188:191], v[54:57]
	v_mfma_f32_16x16x32_bf16 v[50:53], v[180:183], v[188:191], v[50:53]
	v_mfma_f32_16x16x32_bf16 v[38:41], v[166:169], v[196:199], v[38:41]
	v_mfma_f32_16x16x32_bf16 v[34:37], v[180:183], v[196:199], v[34:37]
	v_mfma_f32_16x16x32_bf16 v[22:25], v[166:169], v[204:207], v[22:25]
	v_mfma_f32_16x16x32_bf16 v[18:21], v[180:183], v[204:207], v[18:21]
	v_mfma_f32_16x16x32_bf16 v[6:9], v[166:169], v[212:215], v[6:9]
	v_mfma_f32_16x16x32_bf16 v[2:5], v[180:183], v[212:215], v[2:5]
	s_barrier
	s_add_i32 s74, s74, 2
	s_add_u32 s44, s44, 0x100
	s_addc_u32 s45, s45, 0
	s_add_u32 s72, s72, 0x100
	s_addc_u32 s73, s73, 0
	s_cmp_gt_u32 s74, 29
	s_cbranch_scc0 .LBB0_888
	s_and_b64 vcc, exec, s[20:21]
	s_cbranch_vccz .LBB0_891
	s_barrier

; #define PG8_STAGE(bufoff, gbase, voff) do { _Pragma("unroll") for (int _i = 0; _i < 2; ++_i) \
;         __builtin_amdgcn_global_load_lds((const unsigned*)((const char*)(gbase) + (voff)[_i]), (PG8_LAS unsigned*)(lds + (bufoff) + ldsw + _i * 8192), 16, 0, 0); } while (0)
; #define PG8_LDA(dst, b, h) do { _Pragma("unroll") for (int m = 0; m < 4; ++m) _Pragma("unroll") for (int k = 0; k < 2; ++k) dst[m][k] = *(const PG8_LAS bf16x8*)(lds + PG8_SA(b, h) + aoff + m * 2048 + k * 1024); } while (0)
; #define PG8_LDB(dst, b, h) do { _Pragma("unroll") for (int n = 0; n < 2; ++n) _Pragma("unroll") for (int k = 0; k < 2; ++k) dst[n][k] = *(const PG8_LAS bf16x8*)(lds + PG8_SB(b, h) + boff + n * 2048 + k * 1024); } while (0)
; #define PG8_WAIT_V(n) asm volatile("s_waitcnt vmcnt(" #n ")" ::: "memory")
; #define PG8_WAIT_L(n) asm volatile("s_waitcnt lgkmcnt(" #n ")" ::: "memory")
; #define PG8_BAR __builtin_amdgcn_s_barrier()
; #define PG8_SCHED __builtin_amdgcn_sched_barrier(0)
; template <class Epi, class Sched, bool ALIGN_EPI = false, bool SP2 = false>
; __device__ __forceinline__ void gemm_phase(PG8_LAS unsigned char* lds, const Gemm g, const Sched& S, const Epi& E) {
;     ...
;         const char* nA = has_next ? (const char*)g.A + (size_t)nxt.pm * tA + (size_t)nxt.pn * pnA : cA; const char* nB = has_next ? (const char*)g.Bt + (size_t)nxt.pn * tB : cB;
; #pragma nounroll
;         for (int t = 0; t < nt; t += 2) {
;             const bool last = (t == nt - 2);
;             const char* a1 = cA + (size_t)(t + 1) * kstep;
;             const char* a2 = last ? nA : cA + (size_t)(t + 2) * kstep; const char* b2 = last ? nB : cB + (size_t)(t + 2) * kstep;
;             const char* a3 = a2 + kstep; const char* b3 = b2 + kstep;
;             if (last && has_next) S.a_ready(nxt);
;             if constexpr (SP2) {
;             PG8_LDB(B0, 0, 0); PG8_LDB(B1, 0, 1); PG8_SCHED; PG8_LDA(At, 0, 0); PG8_STAGE(PG8_SA(1, 1), a1 + hA, voffA);
;             PG8_WAIT_V(8); PG8_WAIT_L(0); PG8_BAR; PG8_MMA(0, 0, At, B0); PG8_MMA(0, 1, At, B1); PG8_BAR; PG8_SCHED;
;             PG8_LDA(At, 0, 1); PG8_STAGE(PG8_SB(0, 0), b2, voffB); PG8_STAGE(PG8_SB(0, 1), b2 + hB, voffB); PG8_STAGE(PG8_SA(0, 0), a2, voffA);
;             PG8_WAIT_V(8); PG8_WAIT_L(0); PG8_BAR; PG8_MMA(1, 0, At, B0); PG8_MMA(1, 1, At, B1); PG8_BAR; PG8_SCHED;
.LBB0_962:
	s_ashr_i32 s41, s40, 31
	s_lshl_b64 s[42:43], s[40:41], 20
	s_add_u32 s42, s33, s42
	s_addc_u32 s43, s58, s43
	s_and_b64 s[44:45], s[8:9], exec
	s_cselect_b32 s41, s43, s49
	s_cselect_b32 s47, s42, s48
	s_ashr_i32 s39, s38, 31
	s_lshl_b64 s[44:45], s[38:39], 20
	s_add_u32 s44, s59, s44
	s_addc_u32 s45, s60, s45
	s_and_b64 s[52:53], s[8:9], exec
	s_cselect_b32 s39, s45, s51
	s_cselect_b32 s75, s44, s50
	s_add_u32 s48, s48, 0x80080
	s_addc_u32 s49, s49, 0
	s_add_u32 s76, s50, 0x100
	v_mov_b32_e32 v2, 0
	s_addc_u32 s77, s51, 0
	s_mov_b32 s78, -2
	s_waitcnt lgkmcnt(0)
	v_mov_b32_e32 v3, v2
	s_setprio 1
	ds_read_b128 v[130:133], v208
	ds_read_b128 v[134:137], v208 offset:1024
	ds_read_b128 v[138:141], v208 offset:2048
	ds_read_b128 v[142:145], v208 offset:3072
	ds_read_b128 v[146:149], v209
	ds_read_b128 v[150:153], v209 offset:1024
	ds_read_b128 v[154:157], v209 offset:2048
	ds_read_b128 v[158:161], v209 offset:3072
	s_add_u32 s18, s48, 0xfff80080
	s_addc_u32 s19, s49, -1
	s_cmp_eq_u32 s78, 28
	s_cselect_b32 s53, s41, s19
	s_cselect_b32 s52, s47, s18
	s_cselect_b32 s51, s39, s77
	s_cselect_b32 s50, s75, s76
	s_add_i32 m0, s62, 0xc000
	ds_read_b128 v[162:165], v210
	ds_read_b128 v[166:169], v210 offset:1024
	ds_read_b128 v[170:173], v210 offset:2048
	ds_read_b128 v[174:177], v210 offset:3072
	ds_read_b128 v[194:197], v210 offset:4096
	ds_read_b128 v[198:201], v210 offset:5120
	ds_read_b128 v[202:205], v210 offset:6144
	ds_read_b128 v[212:215], v210 offset:7168
	global_load_lds_dwordx4 v186, s[48:49]
	s_add_i32 m0, s62, 0xe000
	s_nop 0
	global_load_lds_dwordx4 v188, s[48:49]
	s_waitcnt vmcnt(8)
	s_waitcnt lgkmcnt(0)
	s_barrier
	s_setprio 0
	v_mfma_f32_16x16x32_bf16 v[126:129], v[130:133], v[162:165], 0
	v_mfma_f32_16x16x32_bf16 v[122:125], v[138:141], v[162:165], 0
	v_mfma_f32_16x16x32_bf16 v[110:113], v[130:133], v[170:173], 0
	v_mfma_f32_16x16x32_bf16 v[106:109], v[138:141], v[170:173], 0
	v_mfma_f32_16x16x32_bf16 v[94:97], v[130:133], v[194:197], 0
	v_mfma_f32_16x16x32_bf16 v[90:93], v[138:141], v[194:197], 0
	v_mfma_f32_16x16x32_bf16 v[78:81], v[130:133], v[202:205], 0
	v_mfma_f32_16x16x32_bf16 v[74:77], v[138:141], v[202:205], 0
	v_mfma_f32_16x16x32_bf16 v[126:129], v[134:137], v[166:169], v[126:129]
	v_mfma_f32_16x16x32_bf16 v[122:125], v[142:145], v[166:169], v[122:125]
	v_mfma_f32_16x16x32_bf16 v[110:113], v[134:137], v[174:177], v[110:113]
	v_mfma_f32_16x16x32_bf16 v[106:109], v[142:145], v[174:177], v[106:109]
	v_mfma_f32_16x16x32_bf16 v[94:97], v[134:137], v[198:201], v[94:97]
	v_mfma_f32_16x16x32_bf16 v[90:93], v[142:145], v[198:201], v[90:93]
	v_mfma_f32_16x16x32_bf16 v[78:81], v[134:137], v[212:215], v[78:81]
	v_mfma_f32_16x16x32_bf16 v[74:77], v[142:145], v[212:215], v[74:77]
	v_mfma_f32_16x16x32_bf16 v[118:121], v[146:149], v[162:165], 0
	v_mfma_f32_16x16x32_bf16 v[114:117], v[154:157], v[162:165], 0
	v_mfma_f32_16x16x32_bf16 v[102:105], v[146:149], v[170:173], 0
	v_mfma_f32_16x16x32_bf16 v[98:101], v[154:157], v[170:173], 0
	v_mfma_f32_16x16x32_bf16 v[86:89], v[146:149], v[194:197], 0
	v_mfma_f32_16x16x32_bf16 v[82:85], v[154:157], v[194:197], 0
	v_mfma_f32_16x16x32_bf16 v[70:73], v[146:149], v[202:205], 0
	v_mfma_f32_16x16x32_bf16 v[66:69], v[154:157], v[202:205], 0
	v_mfma_f32_16x16x32_bf16 v[118:121], v[150:153], v[166:169], v[118:121]
	v_mfma_f32_16x16x32_bf16 v[114:117], v[158:161], v[166:169], v[114:117]
	v_mfma_f32_16x16x32_bf16 v[102:105], v[150:153], v[174:177], v[102:105]
	v_mfma_f32_16x16x32_bf16 v[98:101], v[158:161], v[174:177], v[98:101]
	v_mfma_f32_16x16x32_bf16 v[86:89], v[150:153], v[198:201], v[86:89]
	v_mfma_f32_16x16x32_bf16 v[82:85], v[158:161], v[198:201], v[82:85]
	v_mfma_f32_16x16x32_bf16 v[70:73], v[150:153], v[212:215], v[70:73]
	v_mfma_f32_16x16x32_bf16 v[66:69], v[158:161], v[212:215], v[66:69]
	s_barrier
	s_setprio 1
	s_add_i32 s18, s72, s61
	s_add_u32 s82, s50, s22
	s_addc_u32 s83, s51, s23
	s_mov_b32 m0, s18
	ds_read_b128 v[162:165], v210 offset:16384
	ds_read_b128 v[166:169], v210 offset:17408
	ds_read_b128 v[170:173], v210 offset:18432
	ds_read_b128 v[174:177], v210 offset:19456
	ds_read_b128 v[194:197], v210 offset:20480
	ds_read_b128 v[198:201], v210 offset:21504
	ds_read_b128 v[202:205], v210 offset:22528
	ds_read_b128 v[212:215], v210 offset:23552
	global_load_lds_dwordx4 v180, s[50:51]
	s_add_i32 m0, s18, 0x2000
	s_add_u32 s80, s50, 0x80000
	s_addc_u32 s81, s51, 0
	s_add_i32 s18, s73, s61
	global_load_lds_dwordx4 v184, s[50:51]
	s_mov_b32 m0, s18
	s_nop 0
	global_load_lds_dwordx4 v180, s[80:81]
	s_add_i32 m0, s18, 0x2000
	s_nop 0
	global_load_lds_dwordx4 v184, s[80:81]
	s_add_u32 s88, s52, s22
	s_addc_u32 s89, s53, s23
	s_mov_b32 m0, s62
	s_nop 0
	global_load_lds_dwordx4 v178, s[52:53]
	s_mov_b32 m0, s63
	s_nop 0
	global_load_lds_dwordx4 v182, s[52:53]
	s_waitcnt vmcnt(8)
	s_waitcnt lgkmcnt(0)
	s_barrier
; #define PG8_STAGE(bufoff, gbase, voff) do { _Pragma("unroll") for (int _i = 0; _i < 2; ++_i) \
;         __builtin_amdgcn_global_load_lds((const unsigned*)((const char*)(gbase) + (voff)[_i]), (PG8_LAS unsigned*)(lds + (bufoff) + ldsw + _i * 8192), 16, 0, 0); } while (0)
; #define PG8_LDA(dst, b, h) do { _Pragma("unroll") for (int m = 0; m < 4; ++m) _Pragma("unroll") for (int k = 0; k < 2; ++k) dst[m][k] = *(const PG8_LAS bf16x8*)(lds + PG8_SA(b, h) + aoff + m * 2048 + k * 1024); } while (0)
; #define PG8_LDB(dst, b, h) do { _Pragma("unroll") for (int n = 0; n < 2; ++n) _Pragma("unroll") for (int k = 0; k < 2; ++k) dst[n][k] = *(const PG8_LAS bf16x8*)(lds + PG8_SB(b, h) + boff + n * 2048 + k * 1024); } while (0)
; #define PG8_MMA(ai, bj, At, Bt) do { __builtin_amdgcn_s_setprio(1); _Pragma("unroll") for (int m = 0; m < 4; ++m) _Pragma("unroll") for (int n = 0; n < 2; ++n) _Pragma("unroll") for (int k = 0; k < 2; ++k) \
;         acc[ai][bj][m][n] = __builtin_amdgcn_mfma_f32_16x16x32_bf16(Bt[n][k], At[m][k], acc[ai][bj][m][n], 0, 0, 0); __builtin_amdgcn_s_setprio(0); } while (0)
; #define PG8_WAIT_V(n) asm volatile("s_waitcnt vmcnt(" #n ")" ::: "memory")
; #define PG8_WAIT_L(n) asm volatile("s_waitcnt lgkmcnt(" #n ")" ::: "memory")
; #define PG8_BAR __builtin_amdgcn_s_barrier()
; #define PG8_SCHED __builtin_amdgcn_sched_barrier(0)
; template <class Epi, class Sched, bool ALIGN_EPI = false, bool SP2 = false>
; __device__ __forceinline__ void gemm_phase(PG8_LAS unsigned char* lds, const Gemm g, const Sched& S, const Epi& E) {
;     ...
;             PG8_WAIT_V(8); PG8_WAIT_L(0); PG8_BAR; PG8_MMA(1, 0, At, B0); PG8_MMA(1, 1, At, B1); PG8_BAR; PG8_SCHED;
;             PG8_LDB(B0, 1, 0); PG8_LDB(B1, 1, 1); PG8_SCHED; PG8_LDA(At, 1, 0); PG8_STAGE(PG8_SA(0, 1), a2 + hA, voffA);
;             PG8_WAIT_V(8); PG8_WAIT_L(0); PG8_BAR; PG8_MMA(0, 0, At, B0); PG8_MMA(0, 1, At, B1); PG8_BAR; PG8_SCHED;
	s_setprio 0
	v_mfma_f32_16x16x32_bf16 v[62:65], v[130:133], v[162:165], 0
	v_mfma_f32_16x16x32_bf16 v[58:61], v[138:141], v[162:165], 0
	v_mfma_f32_16x16x32_bf16 v[46:49], v[130:133], v[170:173], 0
	v_mfma_f32_16x16x32_bf16 v[42:45], v[138:141], v[170:173], 0
	v_mfma_f32_16x16x32_bf16 v[30:33], v[130:133], v[194:197], 0
	v_mfma_f32_16x16x32_bf16 v[26:29], v[138:141], v[194:197], 0
	v_mfma_f32_16x16x32_bf16 v[14:17], v[130:133], v[202:205], 0
	v_mfma_f32_16x16x32_bf16 v[10:13], v[138:141], v[202:205], 0
	v_mfma_f32_16x16x32_bf16 v[62:65], v[134:137], v[166:169], v[62:65]
	v_mfma_f32_16x16x32_bf16 v[58:61], v[142:145], v[166:169], v[58:61]
	v_mfma_f32_16x16x32_bf16 v[46:49], v[134:137], v[174:177], v[46:49]
	v_mfma_f32_16x16x32_bf16 v[42:45], v[142:145], v[174:177], v[42:45]
	v_mfma_f32_16x16x32_bf16 v[30:33], v[134:137], v[198:201], v[30:33]
	v_mfma_f32_16x16x32_bf16 v[26:29], v[142:145], v[198:201], v[26:29]
	v_mfma_f32_16x16x32_bf16 v[14:17], v[134:137], v[212:215], v[14:17]
	v_mfma_f32_16x16x32_bf16 v[10:13], v[142:145], v[212:215], v[10:13]
	v_mfma_f32_16x16x32_bf16 v[54:57], v[146:149], v[162:165], 0
	v_mfma_f32_16x16x32_bf16 v[50:53], v[154:157], v[162:165], 0
	v_mfma_f32_16x16x32_bf16 v[38:41], v[146:149], v[170:173], 0
	v_mfma_f32_16x16x32_bf16 v[34:37], v[154:157], v[170:173], 0
	v_mfma_f32_16x16x32_bf16 v[22:25], v[146:149], v[194:197], 0
	v_mfma_f32_16x16x32_bf16 v[18:21], v[154:157], v[194:197], 0
	v_mfma_f32_16x16x32_bf16 v[6:9], v[146:149], v[202:205], 0
	v_mfma_f32_16x16x32_bf16 v[2:5], v[154:157], v[202:205], 0
	v_mfma_f32_16x16x32_bf16 v[54:57], v[150:153], v[166:169], v[54:57]
	v_mfma_f32_16x16x32_bf16 v[50:53], v[158:161], v[166:169], v[50:53]
	v_mfma_f32_16x16x32_bf16 v[38:41], v[150:153], v[174:177], v[38:41]
	v_mfma_f32_16x16x32_bf16 v[34:37], v[158:161], v[174:177], v[34:37]
	v_mfma_f32_16x16x32_bf16 v[22:25], v[150:153], v[198:201], v[22:25]
	v_mfma_f32_16x16x32_bf16 v[18:21], v[158:161], v[198:201], v[18:21]
	v_mfma_f32_16x16x32_bf16 v[6:9], v[150:153], v[212:215], v[6:9]
	v_mfma_f32_16x16x32_bf16 v[2:5], v[158:161], v[212:215], v[2:5]
	s_barrier
	s_setprio 1
	s_add_i32 s18, 0, 0x18000
	s_add_i32 s19, 0, 0x1c000
	v_add_u32_e32 v142, s18, v206
	v_add_u32_e32 v158, s19, v206
	ds_read_b128 v[130:133], v142
	ds_read_b128 v[134:137], v142 offset:1024
	ds_read_b128 v[138:141], v142 offset:2048
	ds_read_b128 v[142:145], v142 offset:3072
	ds_read_b128 v[146:149], v158
	ds_read_b128 v[150:153], v158 offset:1024
	ds_read_b128 v[154:157], v158 offset:2048
	ds_read_b128 v[158:161], v158 offset:3072
	s_add_u32 s52, s52, 0x80000
	s_addc_u32 s53, s53, 0
	s_mov_b32 m0, s64
	ds_read_b128 v[162:165], v210 offset:32768
	ds_read_b128 v[166:169], v210 offset:33792
	ds_read_b128 v[170:173], v210 offset:34816
	ds_read_b128 v[174:177], v210 offset:35840
	ds_read_b128 v[194:197], v210 offset:36864
	ds_read_b128 v[198:201], v210 offset:37888
	ds_read_b128 v[202:205], v210 offset:38912
	ds_read_b128 v[212:215], v210 offset:39936
	global_load_lds_dwordx4 v178, s[52:53]
	s_mov_b32 m0, s65
	s_nop 0
	global_load_lds_dwordx4 v182, s[52:53]
	s_waitcnt vmcnt(8)
	s_waitcnt lgkmcnt(0)
	s_barrier
	s_setprio 0
	v_mfma_f32_16x16x32_bf16 v[126:129], v[130:133], v[162:165], v[126:129]
	v_mfma_f32_16x16x32_bf16 v[122:125], v[138:141], v[162:165], v[122:125]
	v_mfma_f32_16x16x32_bf16 v[110:113], v[130:133], v[170:173], v[110:113]
	v_mfma_f32_16x16x32_bf16 v[106:109], v[138:141], v[170:173], v[106:109]
	v_mfma_f32_16x16x32_bf16 v[94:97], v[130:133], v[194:197], v[94:97]
	v_mfma_f32_16x16x32_bf16 v[90:93], v[138:141], v[194:197], v[90:93]
	v_mfma_f32_16x16x32_bf16 v[78:81], v[130:133], v[202:205], v[78:81]
	v_mfma_f32_16x16x32_bf16 v[74:77], v[138:141], v[202:205], v[74:77]
	v_mfma_f32_16x16x32_bf16 v[126:129], v[134:137], v[166:169], v[126:129]
	v_mfma_f32_16x16x32_bf16 v[122:125], v[142:145], v[166:169], v[122:125]
	v_mfma_f32_16x16x32_bf16 v[110:113], v[134:137], v[174:177], v[110:113]
	v_mfma_f32_16x16x32_bf16 v[106:109], v[142:145], v[174:177], v[106:109]
	v_mfma_f32_16x16x32_bf16 v[94:97], v[134:137], v[198:201], v[94:97]
	v_mfma_f32_16x16x32_bf16 v[90:93], v[142:145], v[198:201], v[90:93]
	v_mfma_f32_16x16x32_bf16 v[78:81], v[134:137], v[212:215], v[78:81]
	v_mfma_f32_16x16x32_bf16 v[74:77], v[142:145], v[212:215], v[74:77]
	v_mfma_f32_16x16x32_bf16 v[118:121], v[146:149], v[162:165], v[118:121]
	v_mfma_f32_16x16x32_bf16 v[114:117], v[154:157], v[162:165], v[114:117]
	v_mfma_f32_16x16x32_bf16 v[102:105], v[146:149], v[170:173], v[102:105]
	v_mfma_f32_16x16x32_bf16 v[98:101], v[154:157], v[170:173], v[98:101]
	v_mfma_f32_16x16x32_bf16 v[86:89], v[146:149], v[194:197], v[86:89]
	v_mfma_f32_16x16x32_bf16 v[82:85], v[154:157], v[194:197], v[82:85]
	v_mfma_f32_16x16x32_bf16 v[70:73], v[146:149], v[202:205], v[70:73]
	v_mfma_f32_16x16x32_bf16 v[66:69], v[154:157], v[202:205], v[66:69]
	v_mfma_f32_16x16x32_bf16 v[118:121], v[150:153], v[166:169], v[118:121]
	v_mfma_f32_16x16x32_bf16 v[114:117], v[158:161], v[166:169], v[114:117]
	v_mfma_f32_16x16x32_bf16 v[102:105], v[150:153], v[174:177], v[102:105]
	v_mfma_f32_16x16x32_bf16 v[98:101], v[158:161], v[174:177], v[98:101]
	v_mfma_f32_16x16x32_bf16 v[86:89], v[150:153], v[198:201], v[86:89]
	v_mfma_f32_16x16x32_bf16 v[82:85], v[158:161], v[198:201], v[82:85]
	v_mfma_f32_16x16x32_bf16 v[70:73], v[150:153], v[212:215], v[70:73]
	v_mfma_f32_16x16x32_bf16 v[66:69], v[158:161], v[212:215], v[66:69]
	s_barrier
; #define PG8_STAGE(bufoff, gbase, voff) do { _Pragma("unroll") for (int _i = 0; _i < 2; ++_i) \
;         __builtin_amdgcn_global_load_lds((const unsigned*)((const char*)(gbase) + (voff)[_i]), (PG8_LAS unsigned*)(lds + (bufoff) + ldsw + _i * 8192), 16, 0, 0); } while (0)
; #define PG8_LDA(dst, b, h) do { _Pragma("unroll") for (int m = 0; m < 4; ++m) _Pragma("unroll") for (int k = 0; k < 2; ++k) dst[m][k] = *(const PG8_LAS bf16x8*)(lds + PG8_SA(b, h) + aoff + m * 2048 + k * 1024); } while (0)
; #define PG8_LDB(dst, b, h) do { _Pragma("unroll") for (int n = 0; n < 2; ++n) _Pragma("unroll") for (int k = 0; k < 2; ++k) dst[n][k] = *(const PG8_LAS bf16x8*)(lds + PG8_SB(b, h) + boff + n * 2048 + k * 1024); } while (0)
; #define PG8_MMA(ai, bj, At, Bt) do { __builtin_amdgcn_s_setprio(1); _Pragma("unroll") for (int m = 0; m < 4; ++m) _Pragma("unroll") for (int n = 0; n < 2; ++n) _Pragma("unroll") for (int k = 0; k < 2; ++k) \
;         acc[ai][bj][m][n] = __builtin_amdgcn_mfma_f32_16x16x32_bf16(Bt[n][k], At[m][k], acc[ai][bj][m][n], 0, 0, 0); __builtin_amdgcn_s_setprio(0); } while (0)
; #define PG8_WAIT_V(n) asm volatile("s_waitcnt vmcnt(" #n ")" ::: "memory")
; #define PG8_WAIT_L(n) asm volatile("s_waitcnt lgkmcnt(" #n ")" ::: "memory")
; #define PG8_BAR __builtin_amdgcn_s_barrier()
; #define PG8_SCHED __builtin_amdgcn_sched_barrier(0)
; template <class Epi, class Sched, bool ALIGN_EPI = false, bool SP2 = false>
; __device__ __forceinline__ void gemm_phase(PG8_LAS unsigned char* lds, const Gemm g, const Sched& S, const Epi& E) {
;     ...
;             PG8_LDB(B0, 0, 0); PG8_LDB(B1, 0, 1); PG8_SCHED; PG8_LDA(At, 0, 0); PG8_STAGE(PG8_SA(1, 1), a1 + hA, voffA);
;             PG8_WAIT_V(8); PG8_WAIT_L(0); PG8_BAR; PG8_MMA(0, 0, At, B0); PG8_MMA(0, 1, At, B1); PG8_BAR; PG8_SCHED;
;     ...
;             PG8_LDA(At, 1, 1); PG8_STAGE(PG8_SB(1, 0), b3, voffB); PG8_STAGE(PG8_SB(1, 1), b3 + hB, voffB); PG8_STAGE(PG8_SA(1, 0), a3, voffA);
;             PG8_WAIT_V(8); PG8_WAIT_L(0); PG8_BAR; PG8_MMA(1, 0, At, B0); PG8_MMA(1, 1, At, B1); PG8_BAR; PG8_SCHED;
	s_setprio 1
	s_add_i32 s18, s18, s61
	s_mov_b32 m0, s18
	ds_read_b128 v[162:165], v210 offset:49152
	ds_read_b128 v[166:169], v210 offset:50176
	ds_read_b128 v[170:173], v210 offset:51200
	ds_read_b128 v[174:177], v210 offset:52224
	ds_read_b128 v[194:197], v210 offset:53248
	ds_read_b128 v[198:201], v210 offset:54272
	ds_read_b128 v[202:205], v210 offset:55296
	ds_read_b128 v[212:215], v210 offset:56320
	global_load_lds_dwordx4 v180, s[82:83]
	s_add_i32 m0, s18, 0x2000
	s_add_u32 s50, s50, 0x80080
	s_addc_u32 s51, s51, 0
	s_add_i32 s18, s19, s61
	global_load_lds_dwordx4 v184, s[82:83]
	s_mov_b32 m0, s18
	s_nop 0
	global_load_lds_dwordx4 v180, s[50:51]
	s_add_i32 m0, s18, 0x2000
	s_nop 0
	global_load_lds_dwordx4 v184, s[50:51]
	s_mov_b32 m0, s69
	s_nop 0
	global_load_lds_dwordx4 v178, s[88:89]
	s_mov_b32 m0, s70
	s_nop 0
	global_load_lds_dwordx4 v182, s[88:89]
	s_waitcnt vmcnt(8)
	s_waitcnt lgkmcnt(0)
	s_barrier
	s_setprio 0
	v_mfma_f32_16x16x32_bf16 v[62:65], v[130:133], v[162:165], v[62:65]
	v_mfma_f32_16x16x32_bf16 v[58:61], v[138:141], v[162:165], v[58:61]
	v_mfma_f32_16x16x32_bf16 v[46:49], v[130:133], v[170:173], v[46:49]
	v_mfma_f32_16x16x32_bf16 v[42:45], v[138:141], v[170:173], v[42:45]
	v_mfma_f32_16x16x32_bf16 v[30:33], v[130:133], v[194:197], v[30:33]
	v_mfma_f32_16x16x32_bf16 v[26:29], v[138:141], v[194:197], v[26:29]
	v_mfma_f32_16x16x32_bf16 v[14:17], v[130:133], v[202:205], v[14:17]
	v_mfma_f32_16x16x32_bf16 v[10:13], v[138:141], v[202:205], v[10:13]
	v_mfma_f32_16x16x32_bf16 v[62:65], v[134:137], v[166:169], v[62:65]
	v_mfma_f32_16x16x32_bf16 v[58:61], v[142:145], v[166:169], v[58:61]
	v_mfma_f32_16x16x32_bf16 v[46:49], v[134:137], v[174:177], v[46:49]
	v_mfma_f32_16x16x32_bf16 v[42:45], v[142:145], v[174:177], v[42:45]
	v_mfma_f32_16x16x32_bf16 v[30:33], v[134:137], v[198:201], v[30:33]
	v_mfma_f32_16x16x32_bf16 v[26:29], v[142:145], v[198:201], v[26:29]
	v_mfma_f32_16x16x32_bf16 v[14:17], v[134:137], v[212:215], v[14:17]
	v_mfma_f32_16x16x32_bf16 v[10:13], v[142:145], v[212:215], v[10:13]
	v_mfma_f32_16x16x32_bf16 v[54:57], v[146:149], v[162:165], v[54:57]
	v_mfma_f32_16x16x32_bf16 v[50:53], v[154:157], v[162:165], v[50:53]
	v_mfma_f32_16x16x32_bf16 v[38:41], v[146:149], v[170:173], v[38:41]
	v_mfma_f32_16x16x32_bf16 v[34:37], v[154:157], v[170:173], v[34:37]
	v_mfma_f32_16x16x32_bf16 v[22:25], v[146:149], v[194:197], v[22:25]
	v_mfma_f32_16x16x32_bf16 v[18:21], v[154:157], v[194:197], v[18:21]
	v_mfma_f32_16x16x32_bf16 v[6:9], v[146:149], v[202:205], v[6:9]
	v_mfma_f32_16x16x32_bf16 v[2:5], v[154:157], v[202:205], v[2:5]
	v_mfma_f32_16x16x32_bf16 v[54:57], v[150:153], v[166:169], v[54:57]
	v_mfma_f32_16x16x32_bf16 v[50:53], v[158:161], v[166:169], v[50:53]
	v_mfma_f32_16x16x32_bf16 v[38:41], v[150:153], v[174:177], v[38:41]
	v_mfma_f32_16x16x32_bf16 v[34:37], v[158:161], v[174:177], v[34:37]
	v_mfma_f32_16x16x32_bf16 v[22:25], v[150:153], v[198:201], v[22:25]
	v_mfma_f32_16x16x32_bf16 v[18:21], v[158:161], v[198:201], v[18:21]
	v_mfma_f32_16x16x32_bf16 v[6:9], v[150:153], v[212:215], v[6:9]
	v_mfma_f32_16x16x32_bf16 v[2:5], v[158:161], v[212:215], v[2:5]
	s_barrier
	s_add_i32 s78, s78, 2
	s_add_u32 s48, s48, 0x100
	s_addc_u32 s49, s49, 0
	s_add_u32 s76, s76, 0x100
	s_addc_u32 s77, s77, 0
	s_cmp_gt_u32 s78, 29
.LBB0_963:
	s_setprio 1
	ds_read_b128 v[130:133], v208
	ds_read_b128 v[134:137], v208 offset:1024
	ds_read_b128 v[138:141], v208 offset:2048
	ds_read_b128 v[142:145], v208 offset:3072
	ds_read_b128 v[146:149], v209
	ds_read_b128 v[150:153], v209 offset:1024
	ds_read_b128 v[154:157], v209 offset:2048
	ds_read_b128 v[158:161], v209 offset:3072
	s_add_u32 s18, s48, 0xfff80080
	s_addc_u32 s19, s49, -1
	s_cmp_eq_u32 s78, 28
	s_cselect_b32 s53, s41, s19
	s_cselect_b32 s52, s47, s18
	s_cselect_b32 s51, s39, s77
	s_cselect_b32 s50, s75, s76
	s_add_i32 m0, s62, 0xc000
	ds_read_b128 v[162:165], v210
	ds_read_b128 v[166:169], v210 offset:1024
	ds_read_b128 v[170:173], v210 offset:2048
	ds_read_b128 v[174:177], v210 offset:3072
	ds_read_b128 v[194:197], v210 offset:4096
	ds_read_b128 v[198:201], v210 offset:5120
	ds_read_b128 v[202:205], v210 offset:6144
	ds_read_b128 v[212:215], v210 offset:7168
	global_load_lds_dwordx4 v186, s[48:49]
	s_add_i32 m0, s62, 0xe000
	s_nop 0
	global_load_lds_dwordx4 v188, s[48:49]
	s_waitcnt vmcnt(8)
	s_waitcnt lgkmcnt(0)
	s_barrier
	s_setprio 0
	v_mfma_f32_16x16x32_bf16 v[126:129], v[130:133], v[162:165], v[126:129]
	v_mfma_f32_16x16x32_bf16 v[122:125], v[138:141], v[162:165], v[122:125]
	v_mfma_f32_16x16x32_bf16 v[110:113], v[130:133], v[170:173], v[110:113]
	v_mfma_f32_16x16x32_bf16 v[106:109], v[138:141], v[170:173], v[106:109]
	v_mfma_f32_16x16x32_bf16 v[94:97], v[130:133], v[194:197], v[94:97]
	v_mfma_f32_16x16x32_bf16 v[90:93], v[138:141], v[194:197], v[90:93]
	v_mfma_f32_16x16x32_bf16 v[78:81], v[130:133], v[202:205], v[78:81]
	v_mfma_f32_16x16x32_bf16 v[74:77], v[138:141], v[202:205], v[74:77]
	v_mfma_f32_16x16x32_bf16 v[126:129], v[134:137], v[166:169], v[126:129]
	v_mfma_f32_16x16x32_bf16 v[122:125], v[142:145], v[166:169], v[122:125]
	v_mfma_f32_16x16x32_bf16 v[110:113], v[134:137], v[174:177], v[110:113]
	v_mfma_f32_16x16x32_bf16 v[106:109], v[142:145], v[174:177], v[106:109]
	v_mfma_f32_16x16x32_bf16 v[94:97], v[134:137], v[198:201], v[94:97]
	v_mfma_f32_16x16x32_bf16 v[90:93], v[142:145], v[198:201], v[90:93]
	v_mfma_f32_16x16x32_bf16 v[78:81], v[134:137], v[212:215], v[78:81]
	v_mfma_f32_16x16x32_bf16 v[74:77], v[142:145], v[212:215], v[74:77]
	v_mfma_f32_16x16x32_bf16 v[118:121], v[146:149], v[162:165], v[118:121]
	v_mfma_f32_16x16x32_bf16 v[114:117], v[154:157], v[162:165], v[114:117]
	v_mfma_f32_16x16x32_bf16 v[102:105], v[146:149], v[170:173], v[102:105]
	v_mfma_f32_16x16x32_bf16 v[98:101], v[154:157], v[170:173], v[98:101]
	v_mfma_f32_16x16x32_bf16 v[86:89], v[146:149], v[194:197], v[86:89]
	v_mfma_f32_16x16x32_bf16 v[82:85], v[154:157], v[194:197], v[82:85]
	v_mfma_f32_16x16x32_bf16 v[70:73], v[146:149], v[202:205], v[70:73]
	v_mfma_f32_16x16x32_bf16 v[66:69], v[154:157], v[202:205], v[66:69]
	v_mfma_f32_16x16x32_bf16 v[118:121], v[150:153], v[166:169], v[118:121]
	v_mfma_f32_16x16x32_bf16 v[114:117], v[158:161], v[166:169], v[114:117]
	v_mfma_f32_16x16x32_bf16 v[102:105], v[150:153], v[174:177], v[102:105]
	v_mfma_f32_16x16x32_bf16 v[98:101], v[158:161], v[174:177], v[98:101]
	v_mfma_f32_16x16x32_bf16 v[86:89], v[150:153], v[198:201], v[86:89]
	v_mfma_f32_16x16x32_bf16 v[82:85], v[158:161], v[198:201], v[82:85]
	v_mfma_f32_16x16x32_bf16 v[70:73], v[150:153], v[212:215], v[70:73]
	v_mfma_f32_16x16x32_bf16 v[66:69], v[158:161], v[212:215], v[66:69]
	s_barrier
; #define PG8_STAGE(bufoff, gbase, voff) do { _Pragma("unroll") for (int _i = 0; _i < 2; ++_i) \
;         __builtin_amdgcn_global_load_lds((const unsigned*)((const char*)(gbase) + (voff)[_i]), (PG8_LAS unsigned*)(lds + (bufoff) + ldsw + _i * 8192), 16, 0, 0); } while (0)
; #define PG8_LDA(dst, b, h) do { _Pragma("unroll") for (int m = 0; m < 4; ++m) _Pragma("unroll") for (int k = 0; k < 2; ++k) dst[m][k] = *(const PG8_LAS bf16x8*)(lds + PG8_SA(b, h) + aoff + m * 2048 + k * 1024); } while (0)
; #define PG8_LDB(dst, b, h) do { _Pragma("unroll") for (int n = 0; n < 2; ++n) _Pragma("unroll") for (int k = 0; k < 2; ++k) dst[n][k] = *(const PG8_LAS bf16x8*)(lds + PG8_SB(b, h) + boff + n * 2048 + k * 1024); } while (0)
; #define PG8_MMA(ai, bj, At, Bt) do { __builtin_amdgcn_s_setprio(1); _Pragma("unroll") for (int m = 0; m < 4; ++m) _Pragma("unroll") for (int n = 0; n < 2; ++n) _Pragma("unroll") for (int k = 0; k < 2; ++k) \
;         acc[ai][bj][m][n] = __builtin_amdgcn_mfma_f32_16x16x32_bf16(Bt[n][k], At[m][k], acc[ai][bj][m][n], 0, 0, 0); __builtin_amdgcn_s_setprio(0); } while (0)
; #define PG8_WAIT_V(n) asm volatile("s_waitcnt vmcnt(" #n ")" ::: "memory")
; #define PG8_WAIT_L(n) asm volatile("s_waitcnt lgkmcnt(" #n ")" ::: "memory")
; #define PG8_BAR __builtin_amdgcn_s_barrier()
; #define PG8_SCHED __builtin_amdgcn_sched_barrier(0)
; template <class Epi, class Sched, bool ALIGN_EPI = false, bool SP2 = false>
; __device__ __forceinline__ void gemm_phase(PG8_LAS unsigned char* lds, const Gemm g, const Sched& S, const Epi& E) {
;     ...
;             PG8_LDA(At, 0, 1); PG8_STAGE(PG8_SB(0, 0), b2, voffB); PG8_STAGE(PG8_SB(0, 1), b2 + hB, voffB); PG8_STAGE(PG8_SA(0, 0), a2, voffA);
;             PG8_WAIT_V(8); PG8_WAIT_L(0); PG8_BAR; PG8_MMA(1, 0, At, B0); PG8_MMA(1, 1, At, B1); PG8_BAR; PG8_SCHED;
;             PG8_LDB(B0, 1, 0); PG8_LDB(B1, 1, 1); PG8_SCHED; PG8_LDA(At, 1, 0); PG8_STAGE(PG8_SA(0, 1), a2 + hA, voffA);
	s_setprio 1
	s_add_i32 s18, s72, s61
	s_add_u32 s82, s50, s22
	s_addc_u32 s83, s51, s23
	s_mov_b32 m0, s18
	ds_read_b128 v[162:165], v210 offset:16384
	ds_read_b128 v[166:169], v210 offset:17408
	ds_read_b128 v[170:173], v210 offset:18432
	ds_read_b128 v[174:177], v210 offset:19456
	ds_read_b128 v[194:197], v210 offset:20480
	ds_read_b128 v[198:201], v210 offset:21504
	ds_read_b128 v[202:205], v210 offset:22528
	ds_read_b128 v[212:215], v210 offset:23552
	global_load_lds_dwordx4 v180, s[50:51]
	s_add_i32 m0, s18, 0x2000
	s_add_u32 s80, s50, 0x80000
	s_addc_u32 s81, s51, 0
	s_add_i32 s18, s73, s61
	global_load_lds_dwordx4 v184, s[50:51]
	s_mov_b32 m0, s18
	s_nop 0
	global_load_lds_dwordx4 v180, s[80:81]
	s_add_i32 m0, s18, 0x2000
	s_nop 0
	global_load_lds_dwordx4 v184, s[80:81]
	s_add_u32 s88, s52, s22
	s_addc_u32 s89, s53, s23
	s_mov_b32 m0, s62
	s_nop 0
	global_load_lds_dwordx4 v178, s[52:53]
	s_mov_b32 m0, s63
	s_nop 0
	global_load_lds_dwordx4 v182, s[52:53]
	s_waitcnt vmcnt(8)
	s_waitcnt lgkmcnt(0)
	s_barrier
	s_setprio 0
	v_mfma_f32_16x16x32_bf16 v[62:65], v[130:133], v[162:165], v[62:65]
	v_mfma_f32_16x16x32_bf16 v[58:61], v[138:141], v[162:165], v[58:61]
	v_mfma_f32_16x16x32_bf16 v[46:49], v[130:133], v[170:173], v[46:49]
	v_mfma_f32_16x16x32_bf16 v[42:45], v[138:141], v[170:173], v[42:45]
	v_mfma_f32_16x16x32_bf16 v[30:33], v[130:133], v[194:197], v[30:33]
	v_mfma_f32_16x16x32_bf16 v[26:29], v[138:141], v[194:197], v[26:29]
	v_mfma_f32_16x16x32_bf16 v[14:17], v[130:133], v[202:205], v[14:17]
	v_mfma_f32_16x16x32_bf16 v[10:13], v[138:141], v[202:205], v[10:13]
	v_mfma_f32_16x16x32_bf16 v[62:65], v[134:137], v[166:169], v[62:65]
	v_mfma_f32_16x16x32_bf16 v[58:61], v[142:145], v[166:169], v[58:61]
	v_mfma_f32_16x16x32_bf16 v[46:49], v[134:137], v[174:177], v[46:49]
	v_mfma_f32_16x16x32_bf16 v[42:45], v[142:145], v[174:177], v[42:45]
	v_mfma_f32_16x16x32_bf16 v[30:33], v[134:137], v[198:201], v[30:33]
	v_mfma_f32_16x16x32_bf16 v[26:29], v[142:145], v[198:201], v[26:29]
	v_mfma_f32_16x16x32_bf16 v[14:17], v[134:137], v[212:215], v[14:17]
	v_mfma_f32_16x16x32_bf16 v[10:13], v[142:145], v[212:215], v[10:13]
	v_mfma_f32_16x16x32_bf16 v[54:57], v[146:149], v[162:165], v[54:57]
	v_mfma_f32_16x16x32_bf16 v[50:53], v[154:157], v[162:165], v[50:53]
	v_mfma_f32_16x16x32_bf16 v[38:41], v[146:149], v[170:173], v[38:41]
	v_mfma_f32_16x16x32_bf16 v[34:37], v[154:157], v[170:173], v[34:37]
	v_mfma_f32_16x16x32_bf16 v[22:25], v[146:149], v[194:197], v[22:25]
	v_mfma_f32_16x16x32_bf16 v[18:21], v[154:157], v[194:197], v[18:21]
	v_mfma_f32_16x16x32_bf16 v[6:9], v[146:149], v[202:205], v[6:9]
	v_mfma_f32_16x16x32_bf16 v[2:5], v[154:157], v[202:205], v[2:5]
	v_mfma_f32_16x16x32_bf16 v[54:57], v[150:153], v[166:169], v[54:57]
	v_mfma_f32_16x16x32_bf16 v[50:53], v[158:161], v[166:169], v[50:53]
	v_mfma_f32_16x16x32_bf16 v[38:41], v[150:153], v[174:177], v[38:41]
	v_mfma_f32_16x16x32_bf16 v[34:37], v[158:161], v[174:177], v[34:37]
	v_mfma_f32_16x16x32_bf16 v[22:25], v[150:153], v[198:201], v[22:25]
	v_mfma_f32_16x16x32_bf16 v[18:21], v[158:161], v[198:201], v[18:21]
	v_mfma_f32_16x16x32_bf16 v[6:9], v[150:153], v[212:215], v[6:9]
	v_mfma_f32_16x16x32_bf16 v[2:5], v[158:161], v[212:215], v[2:5]
	s_barrier
	s_setprio 1
	s_add_i32 s18, 0, 0x18000
	s_add_i32 s19, 0, 0x1c000
	v_add_u32_e32 v142, s18, v206
	v_add_u32_e32 v158, s19, v206
	ds_read_b128 v[130:133], v142
	ds_read_b128 v[134:137], v142 offset:1024
	ds_read_b128 v[138:141], v142 offset:2048
	ds_read_b128 v[142:145], v142 offset:3072
	ds_read_b128 v[146:149], v158
	ds_read_b128 v[150:153], v158 offset:1024
	ds_read_b128 v[154:157], v158 offset:2048
	ds_read_b128 v[158:161], v158 offset:3072
	s_add_u32 s52, s52, 0x80000
	s_addc_u32 s53, s53, 0
	s_mov_b32 m0, s64
	ds_read_b128 v[162:165], v210 offset:32768
	ds_read_b128 v[166:169], v210 offset:33792
	ds_read_b128 v[170:173], v210 offset:34816
	ds_read_b128 v[174:177], v210 offset:35840
	ds_read_b128 v[194:197], v210 offset:36864
	ds_read_b128 v[198:201], v210 offset:37888
	ds_read_b128 v[202:205], v210 offset:38912
	ds_read_b128 v[212:215], v210 offset:39936
	global_load_lds_dwordx4 v178, s[52:53]
	s_mov_b32 m0, s65
	s_nop 0
	global_load_lds_dwordx4 v182, s[52:53]
	s_waitcnt vmcnt(8)
	s_waitcnt lgkmcnt(0)
	s_barrier
; #define PG8_STAGE(bufoff, gbase, voff) do { _Pragma("unroll") for (int _i = 0; _i < 2; ++_i) \
;         __builtin_amdgcn_global_load_lds((const unsigned*)((const char*)(gbase) + (voff)[_i]), (PG8_LAS unsigned*)(lds + (bufoff) + ldsw + _i * 8192), 16, 0, 0); } while (0)
; #define PG8_LDA(dst, b, h) do { _Pragma("unroll") for (int m = 0; m < 4; ++m) _Pragma("unroll") for (int k = 0; k < 2; ++k) dst[m][k] = *(const PG8_LAS bf16x8*)(lds + PG8_SA(b, h) + aoff + m * 2048 + k * 1024); } while (0)
; #define PG8_LDB(dst, b, h) do { _Pragma("unroll") for (int n = 0; n < 2; ++n) _Pragma("unroll") for (int k = 0; k < 2; ++k) dst[n][k] = *(const PG8_LAS bf16x8*)(lds + PG8_SB(b, h) + boff + n * 2048 + k * 1024); } while (0)
; #define PG8_MMA(ai, bj, At, Bt) do { __builtin_amdgcn_s_setprio(1); _Pragma("unroll") for (int m = 0; m < 4; ++m) _Pragma("unroll") for (int n = 0; n < 2; ++n) _Pragma("unroll") for (int k = 0; k < 2; ++k) \
;         acc[ai][bj][m][n] = __builtin_amdgcn_mfma_f32_16x16x32_bf16(Bt[n][k], At[m][k], acc[ai][bj][m][n], 0, 0, 0); __builtin_amdgcn_s_setprio(0); } while (0)
; #define PG8_WAIT_V(n) asm volatile("s_waitcnt vmcnt(" #n ")" ::: "memory")
; #define PG8_WAIT_L(n) asm volatile("s_waitcnt lgkmcnt(" #n ")" ::: "memory")
; #define PG8_BAR __builtin_amdgcn_s_barrier()
; #define PG8_SCHED __builtin_amdgcn_sched_barrier(0)
; template <class Epi, class Sched, bool ALIGN_EPI = false, bool SP2 = false>
; __device__ __forceinline__ void gemm_phase(PG8_LAS unsigned char* lds, const Gemm g, const Sched& S, const Epi& E) {
;     ...
;             PG8_LDB(B0, 1, 0); PG8_LDB(B1, 1, 1); PG8_SCHED; PG8_LDA(At, 1, 0); PG8_STAGE(PG8_SA(0, 1), a2 + hA, voffA);
;             PG8_WAIT_V(8); PG8_WAIT_L(0); PG8_BAR; PG8_MMA(0, 0, At, B0); PG8_MMA(0, 1, At, B1); PG8_BAR; PG8_SCHED;
;             PG8_LDA(At, 1, 1); PG8_STAGE(PG8_SB(1, 0), b3, voffB); PG8_STAGE(PG8_SB(1, 1), b3 + hB, voffB); PG8_STAGE(PG8_SA(1, 0), a3, voffA);
;             PG8_WAIT_V(8); PG8_WAIT_L(0); PG8_BAR; PG8_MMA(1, 0, At, B0); PG8_MMA(1, 1, At, B1); PG8_BAR; PG8_SCHED;
	s_setprio 0
	v_mfma_f32_16x16x32_bf16 v[126:129], v[130:133], v[162:165], v[126:129]
	v_mfma_f32_16x16x32_bf16 v[122:125], v[138:141], v[162:165], v[122:125]
	v_mfma_f32_16x16x32_bf16 v[110:113], v[130:133], v[170:173], v[110:113]
	v_mfma_f32_16x16x32_bf16 v[106:109], v[138:141], v[170:173], v[106:109]
	v_mfma_f32_16x16x32_bf16 v[94:97], v[130:133], v[194:197], v[94:97]
	v_mfma_f32_16x16x32_bf16 v[90:93], v[138:141], v[194:197], v[90:93]
	v_mfma_f32_16x16x32_bf16 v[78:81], v[130:133], v[202:205], v[78:81]
	v_mfma_f32_16x16x32_bf16 v[74:77], v[138:141], v[202:205], v[74:77]
	v_mfma_f32_16x16x32_bf16 v[126:129], v[134:137], v[166:169], v[126:129]
	v_mfma_f32_16x16x32_bf16 v[122:125], v[142:145], v[166:169], v[122:125]
	v_mfma_f32_16x16x32_bf16 v[110:113], v[134:137], v[174:177], v[110:113]
	v_mfma_f32_16x16x32_bf16 v[106:109], v[142:145], v[174:177], v[106:109]
	v_mfma_f32_16x16x32_bf16 v[94:97], v[134:137], v[198:201], v[94:97]
	v_mfma_f32_16x16x32_bf16 v[90:93], v[142:145], v[198:201], v[90:93]
	v_mfma_f32_16x16x32_bf16 v[78:81], v[134:137], v[212:215], v[78:81]
	v_mfma_f32_16x16x32_bf16 v[74:77], v[142:145], v[212:215], v[74:77]
	v_mfma_f32_16x16x32_bf16 v[118:121], v[146:149], v[162:165], v[118:121]
	v_mfma_f32_16x16x32_bf16 v[114:117], v[154:157], v[162:165], v[114:117]
	v_mfma_f32_16x16x32_bf16 v[102:105], v[146:149], v[170:173], v[102:105]
	v_mfma_f32_16x16x32_bf16 v[98:101], v[154:157], v[170:173], v[98:101]
	v_mfma_f32_16x16x32_bf16 v[86:89], v[146:149], v[194:197], v[86:89]
	v_mfma_f32_16x16x32_bf16 v[82:85], v[154:157], v[194:197], v[82:85]
	v_mfma_f32_16x16x32_bf16 v[70:73], v[146:149], v[202:205], v[70:73]
	v_mfma_f32_16x16x32_bf16 v[66:69], v[154:157], v[202:205], v[66:69]
	v_mfma_f32_16x16x32_bf16 v[118:121], v[150:153], v[166:169], v[118:121]
	v_mfma_f32_16x16x32_bf16 v[114:117], v[158:161], v[166:169], v[114:117]
	v_mfma_f32_16x16x32_bf16 v[102:105], v[150:153], v[174:177], v[102:105]
	v_mfma_f32_16x16x32_bf16 v[98:101], v[158:161], v[174:177], v[98:101]
	v_mfma_f32_16x16x32_bf16 v[86:89], v[150:153], v[198:201], v[86:89]
	v_mfma_f32_16x16x32_bf16 v[82:85], v[158:161], v[198:201], v[82:85]
	v_mfma_f32_16x16x32_bf16 v[70:73], v[150:153], v[212:215], v[70:73]
	v_mfma_f32_16x16x32_bf16 v[66:69], v[158:161], v[212:215], v[66:69]
	s_barrier
	s_setprio 1
	s_add_i32 s18, s18, s61
	s_mov_b32 m0, s18
	ds_read_b128 v[162:165], v210 offset:49152
	ds_read_b128 v[166:169], v210 offset:50176
	ds_read_b128 v[170:173], v210 offset:51200
	ds_read_b128 v[174:177], v210 offset:52224
	ds_read_b128 v[194:197], v210 offset:53248
	ds_read_b128 v[198:201], v210 offset:54272
	ds_read_b128 v[202:205], v210 offset:55296
	ds_read_b128 v[212:215], v210 offset:56320
	global_load_lds_dwordx4 v180, s[82:83]
	s_add_i32 m0, s18, 0x2000
	s_add_u32 s50, s50, 0x80080
	s_addc_u32 s51, s51, 0
	s_add_i32 s18, s19, s61
	global_load_lds_dwordx4 v184, s[82:83]
	s_mov_b32 m0, s18
	s_nop 0
	global_load_lds_dwordx4 v180, s[50:51]
	s_add_i32 m0, s18, 0x2000
	s_nop 0
	global_load_lds_dwordx4 v184, s[50:51]
	s_mov_b32 m0, s69
	s_nop 0
	global_load_lds_dwordx4 v178, s[88:89]
	s_mov_b32 m0, s70
	s_nop 0
	global_load_lds_dwordx4 v182, s[88:89]
	s_waitcnt vmcnt(8)
	s_waitcnt lgkmcnt(0)
	s_barrier
	s_setprio 0
	v_mfma_f32_16x16x32_bf16 v[62:65], v[130:133], v[162:165], v[62:65]
	v_mfma_f32_16x16x32_bf16 v[58:61], v[138:141], v[162:165], v[58:61]
	v_mfma_f32_16x16x32_bf16 v[46:49], v[130:133], v[170:173], v[46:49]
	v_mfma_f32_16x16x32_bf16 v[42:45], v[138:141], v[170:173], v[42:45]
	v_mfma_f32_16x16x32_bf16 v[30:33], v[130:133], v[194:197], v[30:33]
	v_mfma_f32_16x16x32_bf16 v[26:29], v[138:141], v[194:197], v[26:29]
	v_mfma_f32_16x16x32_bf16 v[14:17], v[130:133], v[202:205], v[14:17]
	v_mfma_f32_16x16x32_bf16 v[10:13], v[138:141], v[202:205], v[10:13]
	v_mfma_f32_16x16x32_bf16 v[62:65], v[134:137], v[166:169], v[62:65]
	v_mfma_f32_16x16x32_bf16 v[58:61], v[142:145], v[166:169], v[58:61]
	v_mfma_f32_16x16x32_bf16 v[46:49], v[134:137], v[174:177], v[46:49]
	v_mfma_f32_16x16x32_bf16 v[42:45], v[142:145], v[174:177], v[42:45]
	v_mfma_f32_16x16x32_bf16 v[30:33], v[134:137], v[198:201], v[30:33]
	v_mfma_f32_16x16x32_bf16 v[26:29], v[142:145], v[198:201], v[26:29]
	v_mfma_f32_16x16x32_bf16 v[14:17], v[134:137], v[212:215], v[14:17]
	v_mfma_f32_16x16x32_bf16 v[10:13], v[142:145], v[212:215], v[10:13]
	v_mfma_f32_16x16x32_bf16 v[54:57], v[146:149], v[162:165], v[54:57]
	v_mfma_f32_16x16x32_bf16 v[50:53], v[154:157], v[162:165], v[50:53]
	v_mfma_f32_16x16x32_bf16 v[38:41], v[146:149], v[170:173], v[38:41]
	v_mfma_f32_16x16x32_bf16 v[34:37], v[154:157], v[170:173], v[34:37]
	v_mfma_f32_16x16x32_bf16 v[22:25], v[146:149], v[194:197], v[22:25]
	v_mfma_f32_16x16x32_bf16 v[18:21], v[154:157], v[194:197], v[18:21]
	v_mfma_f32_16x16x32_bf16 v[6:9], v[146:149], v[202:205], v[6:9]
	v_mfma_f32_16x16x32_bf16 v[2:5], v[154:157], v[202:205], v[2:5]
	v_mfma_f32_16x16x32_bf16 v[54:57], v[150:153], v[166:169], v[54:57]
	v_mfma_f32_16x16x32_bf16 v[50:53], v[158:161], v[166:169], v[50:53]
	v_mfma_f32_16x16x32_bf16 v[38:41], v[150:153], v[174:177], v[38:41]
	v_mfma_f32_16x16x32_bf16 v[34:37], v[158:161], v[174:177], v[34:37]
	v_mfma_f32_16x16x32_bf16 v[22:25], v[150:153], v[198:201], v[22:25]
	v_mfma_f32_16x16x32_bf16 v[18:21], v[158:161], v[198:201], v[18:21]
	v_mfma_f32_16x16x32_bf16 v[6:9], v[150:153], v[212:215], v[6:9]
	v_mfma_f32_16x16x32_bf16 v[2:5], v[158:161], v[212:215], v[2:5]
	s_barrier
	s_add_i32 s78, s78, 2
	s_add_u32 s48, s48, 0x100
	s_addc_u32 s49, s49, 0
	s_add_u32 s76, s76, 0x100
	s_addc_u32 s77, s77, 0
	s_cmp_gt_u32 s78, 29
	s_cbranch_scc0 .LBB0_963
	s_and_b64 vcc, exec, s[24:25]
	s_cbranch_vccz .LBB0_966
	s_barrier

; #define PG8_STAGE(bufoff, gbase, voff) do { _Pragma("unroll") for (int _i = 0; _i < 2; ++_i) \
;         __builtin_amdgcn_global_load_lds((const unsigned*)((const char*)(gbase) + (voff)[_i]), (PG8_LAS unsigned*)(lds + (bufoff) + ldsw + _i * 8192), 16, 0, 0); } while (0)
; #define PG8_LDA(dst, b, h) do { _Pragma("unroll") for (int m = 0; m < 4; ++m) _Pragma("unroll") for (int k = 0; k < 2; ++k) dst[m][k] = *(const PG8_LAS bf16x8*)(lds + PG8_SA(b, h) + aoff + m * 2048 + k * 1024); } while (0)
; #define PG8_LDB(dst, b, h) do { _Pragma("unroll") for (int n = 0; n < 2; ++n) _Pragma("unroll") for (int k = 0; k < 2; ++k) dst[n][k] = *(const PG8_LAS bf16x8*)(lds + PG8_SB(b, h) + boff + n * 2048 + k * 1024); } while (0)
; #define PG8_WAIT_V(n) asm volatile("s_waitcnt vmcnt(" #n ")" ::: "memory")
; #define PG8_WAIT_L(n) asm volatile("s_waitcnt lgkmcnt(" #n ")" ::: "memory")
; #define PG8_BAR __builtin_amdgcn_s_barrier()
; #define PG8_SCHED __builtin_amdgcn_sched_barrier(0)
; template <class Epi, class Sched, bool ALIGN_EPI = false, bool SP2 = false>
; __device__ __forceinline__ void gemm_phase(PG8_LAS unsigned char* lds, const Gemm g, const Sched& S, const Epi& E) {
;     ...
;         const char* nA = has_next ? (const char*)g.A + (size_t)nxt.pm * tA + (size_t)nxt.pn * pnA : cA; const char* nB = has_next ? (const char*)g.Bt + (size_t)nxt.pn * tB : cB;
; #pragma nounroll
;         for (int t = 0; t < nt; t += 2) {
;             const bool last = (t == nt - 2);
;             const char* a1 = cA + (size_t)(t + 1) * kstep;
;             const char* a2 = last ? nA : cA + (size_t)(t + 2) * kstep; const char* b2 = last ? nB : cB + (size_t)(t + 2) * kstep;
;             const char* a3 = a2 + kstep; const char* b3 = b2 + kstep;
;             if (last && has_next) S.a_ready(nxt);
;             if constexpr (SP2) {
;             PG8_LDB(B0, 0, 0); PG8_LDB(B1, 0, 1); PG8_SCHED; PG8_LDA(At, 0, 0); PG8_STAGE(PG8_SA(1, 1), a1 + hA, voffA);
;             PG8_WAIT_V(8); PG8_WAIT_L(0); PG8_BAR; PG8_MMA(0, 0, At, B0); PG8_MMA(0, 1, At, B1); PG8_BAR; PG8_SCHED;
;             PG8_LDA(At, 0, 1); PG8_STAGE(PG8_SB(0, 0), b2, voffB); PG8_STAGE(PG8_SB(0, 1), b2 + hB, voffB); PG8_STAGE(PG8_SA(0, 0), a2, voffA);
;             PG8_WAIT_V(8); PG8_WAIT_L(0); PG8_BAR; PG8_MMA(1, 0, At, B0); PG8_MMA(1, 1, At, B1); PG8_BAR; PG8_SCHED;
.LBB0_1047:
	s_ashr_i32 s37, s36, 31
	s_lshl_b64 s[38:39], s[36:37], 20
	s_add_u32 s38, s33, s38
	s_addc_u32 s39, s46, s39
	s_and_b64 s[40:41], s[6:7], exec
	s_cselect_b32 s1, s39, s9
	s_cselect_b32 s37, s38, s8
	s_ashr_i32 s25, s24, 31
	s_lshl_b64 s[40:41], s[24:25], 20
	s_add_u32 s40, s47, s40
	s_addc_u32 s41, s48, s41
	s_and_b64 s[44:45], s[6:7], exec
	s_cselect_b32 s25, s41, s43
	s_cselect_b32 s69, s40, s42
	s_add_u32 s8, s8, 0x80080
	s_addc_u32 s9, s9, 0
	s_add_u32 s70, s42, 0x100
	v_mov_b32_e32 v2, 0
	s_addc_u32 s71, s43, 0
	s_mov_b32 s72, -2
	v_mov_b32_e32 v3, v2
	s_setprio 1
	ds_read_b128 v[148:151], v169
	ds_read_b128 v[152:155], v169 offset:1024
	ds_read_b128 v[156:159], v169 offset:2048
	ds_read_b128 v[160:163], v169 offset:3072
	ds_read_b128 v[180:183], v171
	ds_read_b128 v[184:187], v171 offset:1024
	ds_read_b128 v[188:191], v171 offset:2048
	ds_read_b128 v[192:195], v171 offset:3072
	s_add_u32 s18, s8, 0xfff80080
	s_addc_u32 s19, s9, -1
	s_cmp_eq_u32 s72, 28
	s_cselect_b32 s45, s1, s19
	s_cselect_b32 s44, s37, s18
	s_cselect_b32 s43, s25, s71
	s_cselect_b32 s42, s69, s70
	s_add_i32 m0, s51, 0xc000
	ds_read_b128 v[196:199], v173
	ds_read_b128 v[200:203], v173 offset:1024
	ds_read_b128 v[204:207], v173 offset:2048
	ds_read_b128 v[208:211], v173 offset:3072
	ds_read_b128 v[212:215], v173 offset:4096
	ds_read_b128 v[216:219], v173 offset:5120
	ds_read_b128 v[224:227], v173 offset:6144
	ds_read_b128 v[228:231], v173 offset:7168
	global_load_lds_dwordx4 v140, s[8:9]
	s_add_i32 m0, s51, 0xe000
	s_nop 0
	global_load_lds_dwordx4 v142, s[8:9]
	s_waitcnt vmcnt(8)
	s_waitcnt lgkmcnt(0)
	s_barrier
	s_setprio 0
	v_mfma_f32_16x16x32_bf16 v[126:129], v[148:151], v[196:199], 0
	v_mfma_f32_16x16x32_bf16 v[122:125], v[156:159], v[196:199], 0
	v_mfma_f32_16x16x32_bf16 v[110:113], v[148:151], v[204:207], 0
	v_mfma_f32_16x16x32_bf16 v[106:109], v[156:159], v[204:207], 0
	v_mfma_f32_16x16x32_bf16 v[94:97], v[148:151], v[212:215], 0
	v_mfma_f32_16x16x32_bf16 v[90:93], v[156:159], v[212:215], 0
	v_mfma_f32_16x16x32_bf16 v[78:81], v[148:151], v[224:227], 0
	v_mfma_f32_16x16x32_bf16 v[74:77], v[156:159], v[224:227], 0
	v_mfma_f32_16x16x32_bf16 v[126:129], v[152:155], v[200:203], v[126:129]
	v_mfma_f32_16x16x32_bf16 v[122:125], v[160:163], v[200:203], v[122:125]
	v_mfma_f32_16x16x32_bf16 v[110:113], v[152:155], v[208:211], v[110:113]
	v_mfma_f32_16x16x32_bf16 v[106:109], v[160:163], v[208:211], v[106:109]
	v_mfma_f32_16x16x32_bf16 v[94:97], v[152:155], v[216:219], v[94:97]
	v_mfma_f32_16x16x32_bf16 v[90:93], v[160:163], v[216:219], v[90:93]
	v_mfma_f32_16x16x32_bf16 v[78:81], v[152:155], v[228:231], v[78:81]
	v_mfma_f32_16x16x32_bf16 v[74:77], v[160:163], v[228:231], v[74:77]
	v_mfma_f32_16x16x32_bf16 v[118:121], v[180:183], v[196:199], 0
	v_mfma_f32_16x16x32_bf16 v[114:117], v[188:191], v[196:199], 0
	v_mfma_f32_16x16x32_bf16 v[102:105], v[180:183], v[204:207], 0
	v_mfma_f32_16x16x32_bf16 v[98:101], v[188:191], v[204:207], 0
	v_mfma_f32_16x16x32_bf16 v[86:89], v[180:183], v[212:215], 0
	v_mfma_f32_16x16x32_bf16 v[82:85], v[188:191], v[212:215], 0
	v_mfma_f32_16x16x32_bf16 v[70:73], v[180:183], v[224:227], 0
	v_mfma_f32_16x16x32_bf16 v[66:69], v[188:191], v[224:227], 0
	v_mfma_f32_16x16x32_bf16 v[118:121], v[184:187], v[200:203], v[118:121]
	v_mfma_f32_16x16x32_bf16 v[114:117], v[192:195], v[200:203], v[114:117]
	v_mfma_f32_16x16x32_bf16 v[102:105], v[184:187], v[208:211], v[102:105]
	v_mfma_f32_16x16x32_bf16 v[98:101], v[192:195], v[208:211], v[98:101]
	v_mfma_f32_16x16x32_bf16 v[86:89], v[184:187], v[216:219], v[86:89]
	v_mfma_f32_16x16x32_bf16 v[82:85], v[192:195], v[216:219], v[82:85]
	v_mfma_f32_16x16x32_bf16 v[70:73], v[184:187], v[228:231], v[70:73]
	v_mfma_f32_16x16x32_bf16 v[66:69], v[192:195], v[228:231], v[66:69]
	s_barrier
	s_setprio 1
	s_add_i32 s18, s63, s49
	s_add_u32 s76, s42, s20
	s_addc_u32 s77, s43, s21
	s_mov_b32 m0, s18
	ds_read_b128 v[196:199], v173 offset:16384
	ds_read_b128 v[200:203], v173 offset:17408
	ds_read_b128 v[204:207], v173 offset:18432
	ds_read_b128 v[208:211], v173 offset:19456
	ds_read_b128 v[212:215], v173 offset:20480
	ds_read_b128 v[216:219], v173 offset:21504
	ds_read_b128 v[224:227], v173 offset:22528
	ds_read_b128 v[228:231], v173 offset:23552
	global_load_lds_dwordx4 v134, s[42:43]
	s_add_i32 m0, s18, 0x2000
	s_add_u32 s74, s42, 0x80000
	s_addc_u32 s75, s43, 0
	s_add_i32 s18, s64, s49
	global_load_lds_dwordx4 v130, s[42:43]
	s_mov_b32 m0, s18
	s_nop 0
	global_load_lds_dwordx4 v134, s[74:75]
	s_add_i32 m0, s18, 0x2000
	s_nop 0
	global_load_lds_dwordx4 v130, s[74:75]
	s_add_u32 s78, s44, s20
	s_addc_u32 s79, s45, s21
	s_mov_b32 m0, s51
	s_nop 0
	global_load_lds_dwordx4 v136, s[44:45]
	s_mov_b32 m0, s52
	s_nop 0
	global_load_lds_dwordx4 v132, s[44:45]
	s_waitcnt vmcnt(8)
	s_waitcnt lgkmcnt(0)
	s_barrier
; #define PG8_STAGE(bufoff, gbase, voff) do { _Pragma("unroll") for (int _i = 0; _i < 2; ++_i) \
;         __builtin_amdgcn_global_load_lds((const unsigned*)((const char*)(gbase) + (voff)[_i]), (PG8_LAS unsigned*)(lds + (bufoff) + ldsw + _i * 8192), 16, 0, 0); } while (0)
; #define PG8_LDA(dst, b, h) do { _Pragma("unroll") for (int m = 0; m < 4; ++m) _Pragma("unroll") for (int k = 0; k < 2; ++k) dst[m][k] = *(const PG8_LAS bf16x8*)(lds + PG8_SA(b, h) + aoff + m * 2048 + k * 1024); } while (0)
; #define PG8_LDB(dst, b, h) do { _Pragma("unroll") for (int n = 0; n < 2; ++n) _Pragma("unroll") for (int k = 0; k < 2; ++k) dst[n][k] = *(const PG8_LAS bf16x8*)(lds + PG8_SB(b, h) + boff + n * 2048 + k * 1024); } while (0)
; #define PG8_MMA(ai, bj, At, Bt) do { __builtin_amdgcn_s_setprio(1); _Pragma("unroll") for (int m = 0; m < 4; ++m) _Pragma("unroll") for (int n = 0; n < 2; ++n) _Pragma("unroll") for (int k = 0; k < 2; ++k) \
;         acc[ai][bj][m][n] = __builtin_amdgcn_mfma_f32_16x16x32_bf16(Bt[n][k], At[m][k], acc[ai][bj][m][n], 0, 0, 0); __builtin_amdgcn_s_setprio(0); } while (0)
; #define PG8_WAIT_V(n) asm volatile("s_waitcnt vmcnt(" #n ")" ::: "memory")
; #define PG8_WAIT_L(n) asm volatile("s_waitcnt lgkmcnt(" #n ")" ::: "memory")
; #define PG8_BAR __builtin_amdgcn_s_barrier()
; #define PG8_SCHED __builtin_amdgcn_sched_barrier(0)
; template <class Epi, class Sched, bool ALIGN_EPI = false, bool SP2 = false>
; __device__ __forceinline__ void gemm_phase(PG8_LAS unsigned char* lds, const Gemm g, const Sched& S, const Epi& E) {
;     ...
;             PG8_LDA(At, 0, 1); PG8_STAGE(PG8_SB(0, 0), b2, voffB); PG8_STAGE(PG8_SB(0, 1), b2 + hB, voffB); PG8_STAGE(PG8_SA(0, 0), a2, voffA);
;             PG8_WAIT_V(8); PG8_WAIT_L(0); PG8_BAR; PG8_MMA(1, 0, At, B0); PG8_MMA(1, 1, At, B1); PG8_BAR; PG8_SCHED;
;             PG8_LDB(B0, 1, 0); PG8_LDB(B1, 1, 1); PG8_SCHED; PG8_LDA(At, 1, 0); PG8_STAGE(PG8_SA(0, 1), a2 + hA, voffA);
;             PG8_WAIT_V(8); PG8_WAIT_L(0); PG8_BAR; PG8_MMA(0, 0, At, B0); PG8_MMA(0, 1, At, B1); PG8_BAR; PG8_SCHED;
	s_setprio 0
	v_mfma_f32_16x16x32_bf16 v[62:65], v[148:151], v[196:199], 0
	v_mfma_f32_16x16x32_bf16 v[58:61], v[156:159], v[196:199], 0
	v_mfma_f32_16x16x32_bf16 v[46:49], v[148:151], v[204:207], 0
	v_mfma_f32_16x16x32_bf16 v[42:45], v[156:159], v[204:207], 0
	v_mfma_f32_16x16x32_bf16 v[30:33], v[148:151], v[212:215], 0
	v_mfma_f32_16x16x32_bf16 v[26:29], v[156:159], v[212:215], 0
	v_mfma_f32_16x16x32_bf16 v[14:17], v[148:151], v[224:227], 0
	v_mfma_f32_16x16x32_bf16 v[10:13], v[156:159], v[224:227], 0
	v_mfma_f32_16x16x32_bf16 v[62:65], v[152:155], v[200:203], v[62:65]
	v_mfma_f32_16x16x32_bf16 v[58:61], v[160:163], v[200:203], v[58:61]
	v_mfma_f32_16x16x32_bf16 v[46:49], v[152:155], v[208:211], v[46:49]
	v_mfma_f32_16x16x32_bf16 v[42:45], v[160:163], v[208:211], v[42:45]
	v_mfma_f32_16x16x32_bf16 v[30:33], v[152:155], v[216:219], v[30:33]
	v_mfma_f32_16x16x32_bf16 v[26:29], v[160:163], v[216:219], v[26:29]
	v_mfma_f32_16x16x32_bf16 v[14:17], v[152:155], v[228:231], v[14:17]
	v_mfma_f32_16x16x32_bf16 v[10:13], v[160:163], v[228:231], v[10:13]
	v_mfma_f32_16x16x32_bf16 v[54:57], v[180:183], v[196:199], 0
	v_mfma_f32_16x16x32_bf16 v[50:53], v[188:191], v[196:199], 0
	v_mfma_f32_16x16x32_bf16 v[38:41], v[180:183], v[204:207], 0
	v_mfma_f32_16x16x32_bf16 v[34:37], v[188:191], v[204:207], 0
	v_mfma_f32_16x16x32_bf16 v[22:25], v[180:183], v[212:215], 0
	v_mfma_f32_16x16x32_bf16 v[18:21], v[188:191], v[212:215], 0
	v_mfma_f32_16x16x32_bf16 v[6:9], v[180:183], v[224:227], 0
	v_mfma_f32_16x16x32_bf16 v[2:5], v[188:191], v[224:227], 0
	v_mfma_f32_16x16x32_bf16 v[54:57], v[184:187], v[200:203], v[54:57]
	v_mfma_f32_16x16x32_bf16 v[50:53], v[192:195], v[200:203], v[50:53]
	v_mfma_f32_16x16x32_bf16 v[38:41], v[184:187], v[208:211], v[38:41]
	v_mfma_f32_16x16x32_bf16 v[34:37], v[192:195], v[208:211], v[34:37]
	v_mfma_f32_16x16x32_bf16 v[22:25], v[184:187], v[216:219], v[22:25]
	v_mfma_f32_16x16x32_bf16 v[18:21], v[192:195], v[216:219], v[18:21]
	v_mfma_f32_16x16x32_bf16 v[6:9], v[184:187], v[228:231], v[6:9]
	v_mfma_f32_16x16x32_bf16 v[2:5], v[192:195], v[228:231], v[2:5]
	s_barrier
	s_setprio 1
	s_add_i32 s18, 0, 0x18000
	s_add_i32 s19, 0, 0x1c000
	v_add_u32_e32 v160, s18, v165
	v_add_u32_e32 v164, s19, v165
	ds_read_b128 v[148:151], v160
	ds_read_b128 v[152:155], v160 offset:1024
	ds_read_b128 v[156:159], v160 offset:2048
	ds_read_b128 v[160:163], v160 offset:3072
	ds_read_b128 v[180:183], v164
	ds_read_b128 v[184:187], v164 offset:1024
	ds_read_b128 v[188:191], v164 offset:2048
	ds_read_b128 v[192:195], v164 offset:3072
	s_add_u32 s44, s44, 0x80000
	s_addc_u32 s45, s45, 0
	s_mov_b32 m0, s53
	ds_read_b128 v[196:199], v173 offset:32768
	ds_read_b128 v[200:203], v173 offset:33792
	ds_read_b128 v[204:207], v173 offset:34816
	ds_read_b128 v[208:211], v173 offset:35840
	ds_read_b128 v[212:215], v173 offset:36864
	ds_read_b128 v[216:219], v173 offset:37888
	ds_read_b128 v[224:227], v173 offset:38912
	ds_read_b128 v[228:231], v173 offset:39936
	global_load_lds_dwordx4 v136, s[44:45]
	s_mov_b32 m0, s57
	s_nop 0
	global_load_lds_dwordx4 v132, s[44:45]
	s_waitcnt vmcnt(8)
	s_waitcnt lgkmcnt(0)
	s_barrier
	s_setprio 0
	v_mfma_f32_16x16x32_bf16 v[126:129], v[148:151], v[196:199], v[126:129]
	v_mfma_f32_16x16x32_bf16 v[122:125], v[156:159], v[196:199], v[122:125]
	v_mfma_f32_16x16x32_bf16 v[110:113], v[148:151], v[204:207], v[110:113]
	v_mfma_f32_16x16x32_bf16 v[106:109], v[156:159], v[204:207], v[106:109]
	v_mfma_f32_16x16x32_bf16 v[94:97], v[148:151], v[212:215], v[94:97]
	v_mfma_f32_16x16x32_bf16 v[90:93], v[156:159], v[212:215], v[90:93]
	v_mfma_f32_16x16x32_bf16 v[78:81], v[148:151], v[224:227], v[78:81]
	v_mfma_f32_16x16x32_bf16 v[74:77], v[156:159], v[224:227], v[74:77]
	v_mfma_f32_16x16x32_bf16 v[126:129], v[152:155], v[200:203], v[126:129]
	v_mfma_f32_16x16x32_bf16 v[122:125], v[160:163], v[200:203], v[122:125]
	v_mfma_f32_16x16x32_bf16 v[110:113], v[152:155], v[208:211], v[110:113]
	v_mfma_f32_16x16x32_bf16 v[106:109], v[160:163], v[208:211], v[106:109]
	v_mfma_f32_16x16x32_bf16 v[94:97], v[152:155], v[216:219], v[94:97]
	v_mfma_f32_16x16x32_bf16 v[90:93], v[160:163], v[216:219], v[90:93]
	v_mfma_f32_16x16x32_bf16 v[78:81], v[152:155], v[228:231], v[78:81]
	v_mfma_f32_16x16x32_bf16 v[74:77], v[160:163], v[228:231], v[74:77]
	v_mfma_f32_16x16x32_bf16 v[118:121], v[180:183], v[196:199], v[118:121]
	v_mfma_f32_16x16x32_bf16 v[114:117], v[188:191], v[196:199], v[114:117]
	v_mfma_f32_16x16x32_bf16 v[102:105], v[180:183], v[204:207], v[102:105]
	v_mfma_f32_16x16x32_bf16 v[98:101], v[188:191], v[204:207], v[98:101]
	v_mfma_f32_16x16x32_bf16 v[86:89], v[180:183], v[212:215], v[86:89]
	v_mfma_f32_16x16x32_bf16 v[82:85], v[188:191], v[212:215], v[82:85]
	v_mfma_f32_16x16x32_bf16 v[70:73], v[180:183], v[224:227], v[70:73]
	v_mfma_f32_16x16x32_bf16 v[66:69], v[188:191], v[224:227], v[66:69]
	v_mfma_f32_16x16x32_bf16 v[118:121], v[184:187], v[200:203], v[118:121]
	v_mfma_f32_16x16x32_bf16 v[114:117], v[192:195], v[200:203], v[114:117]
	v_mfma_f32_16x16x32_bf16 v[102:105], v[184:187], v[208:211], v[102:105]
	v_mfma_f32_16x16x32_bf16 v[98:101], v[192:195], v[208:211], v[98:101]
	v_mfma_f32_16x16x32_bf16 v[86:89], v[184:187], v[216:219], v[86:89]
	v_mfma_f32_16x16x32_bf16 v[82:85], v[192:195], v[216:219], v[82:85]
	v_mfma_f32_16x16x32_bf16 v[70:73], v[184:187], v[228:231], v[70:73]
	v_mfma_f32_16x16x32_bf16 v[66:69], v[192:195], v[228:231], v[66:69]
	s_barrier
; #define PG8_STAGE(bufoff, gbase, voff) do { _Pragma("unroll") for (int _i = 0; _i < 2; ++_i) \
;         __builtin_amdgcn_global_load_lds((const unsigned*)((const char*)(gbase) + (voff)[_i]), (PG8_LAS unsigned*)(lds + (bufoff) + ldsw + _i * 8192), 16, 0, 0); } while (0)
; #define PG8_LDA(dst, b, h) do { _Pragma("unroll") for (int m = 0; m < 4; ++m) _Pragma("unroll") for (int k = 0; k < 2; ++k) dst[m][k] = *(const PG8_LAS bf16x8*)(lds + PG8_SA(b, h) + aoff + m * 2048 + k * 1024); } while (0)
; #define PG8_LDB(dst, b, h) do { _Pragma("unroll") for (int n = 0; n < 2; ++n) _Pragma("unroll") for (int k = 0; k < 2; ++k) dst[n][k] = *(const PG8_LAS bf16x8*)(lds + PG8_SB(b, h) + boff + n * 2048 + k * 1024); } while (0)
; template <class Epi, class Sched, bool ALIGN_EPI = false, bool SP2 = false>
; __device__ __forceinline__ void gemm_phase(PG8_LAS unsigned char* lds, const Gemm g, const Sched& S, const Epi& E) {
;     ...
;         for (int t = 0; t < nt; t += 2) {
;             const bool last = (t == nt - 2);
;             const char* a1 = cA + (size_t)(t + 1) * kstep;
;             const char* a2 = last ? nA : cA + (size_t)(t + 2) * kstep; const char* b2 = last ? nB : cB + (size_t)(t + 2) * kstep;
;             const char* a3 = a2 + kstep; const char* b3 = b2 + kstep;
;             if (last && has_next) S.a_ready(nxt);
;             if constexpr (SP2) {
;             PG8_LDB(B0, 0, 0); PG8_LDB(B1, 0, 1); PG8_SCHED; PG8_LDA(At, 0, 0); PG8_STAGE(PG8_SA(1, 1), a1 + hA, voffA);
;             PG8_WAIT_V(8); PG8_WAIT_L(0); PG8_BAR; PG8_MMA(0, 0, At, B0); PG8_MMA(0, 1, At, B1); PG8_BAR; PG8_SCHED;
;             PG8_LDA(At, 0, 1); PG8_STAGE(PG8_SB(0, 0), b2, voffB); PG8_STAGE(PG8_SB(0, 1), b2 + hB, voffB); PG8_STAGE(PG8_SA(0, 0), a2, voffA);
;             PG8_WAIT_V(8); PG8_WAIT_L(0); PG8_BAR; PG8_MMA(1, 0, At, B0); PG8_MMA(1, 1, At, B1); PG8_BAR; PG8_SCHED;
;             PG8_LDB(B0, 1, 0); PG8_LDB(B1, 1, 1); PG8_SCHED; PG8_LDA(At, 1, 0); PG8_STAGE(PG8_SA(0, 1), a2 + hA, voffA);
;             PG8_WAIT_V(8); PG8_WAIT_L(0); PG8_BAR; PG8_MMA(0, 0, At, B0); PG8_MMA(0, 1, At, B1); PG8_BAR; PG8_SCHED;
;             PG8_LDA(At, 1, 1); PG8_STAGE(PG8_SB(1, 0), b3, voffB); PG8_STAGE(PG8_SB(1, 1), b3 + hB, voffB); PG8_STAGE(PG8_SA(1, 0), a3, voffA);
;             PG8_WAIT_V(8); PG8_WAIT_L(0); PG8_BAR; PG8_MMA(1, 0, At, B0); PG8_MMA(1, 1, At, B1); PG8_BAR; PG8_SCHED;
	s_setprio 1
	s_add_i32 s18, s18, s49
	s_mov_b32 m0, s18
	ds_read_b128 v[196:199], v173 offset:49152
	ds_read_b128 v[200:203], v173 offset:50176
	ds_read_b128 v[204:207], v173 offset:51200
	ds_read_b128 v[208:211], v173 offset:52224
	ds_read_b128 v[212:215], v173 offset:53248
	ds_read_b128 v[216:219], v173 offset:54272
	ds_read_b128 v[224:227], v173 offset:55296
	ds_read_b128 v[228:231], v173 offset:56320
	global_load_lds_dwordx4 v134, s[76:77]
	s_add_i32 m0, s18, 0x2000
	s_add_u32 s42, s42, 0x80080
	s_addc_u32 s43, s43, 0
	s_add_i32 s18, s19, s49
	global_load_lds_dwordx4 v130, s[76:77]
	s_mov_b32 m0, s18
	s_nop 0
	global_load_lds_dwordx4 v134, s[42:43]
	s_add_i32 m0, s18, 0x2000
	s_nop 0
	global_load_lds_dwordx4 v130, s[42:43]
	s_mov_b32 m0, s60
	s_nop 0
	global_load_lds_dwordx4 v136, s[78:79]
	s_mov_b32 m0, s61
	s_nop 0
	global_load_lds_dwordx4 v132, s[78:79]
	s_waitcnt vmcnt(8)
	s_waitcnt lgkmcnt(0)
	s_barrier
	s_setprio 0
	v_mfma_f32_16x16x32_bf16 v[62:65], v[148:151], v[196:199], v[62:65]
	v_mfma_f32_16x16x32_bf16 v[58:61], v[156:159], v[196:199], v[58:61]
	v_mfma_f32_16x16x32_bf16 v[46:49], v[148:151], v[204:207], v[46:49]
	v_mfma_f32_16x16x32_bf16 v[42:45], v[156:159], v[204:207], v[42:45]
	v_mfma_f32_16x16x32_bf16 v[30:33], v[148:151], v[212:215], v[30:33]
	v_mfma_f32_16x16x32_bf16 v[26:29], v[156:159], v[212:215], v[26:29]
	v_mfma_f32_16x16x32_bf16 v[14:17], v[148:151], v[224:227], v[14:17]
	v_mfma_f32_16x16x32_bf16 v[10:13], v[156:159], v[224:227], v[10:13]
	v_mfma_f32_16x16x32_bf16 v[62:65], v[152:155], v[200:203], v[62:65]
	v_mfma_f32_16x16x32_bf16 v[58:61], v[160:163], v[200:203], v[58:61]
	v_mfma_f32_16x16x32_bf16 v[46:49], v[152:155], v[208:211], v[46:49]
	v_mfma_f32_16x16x32_bf16 v[42:45], v[160:163], v[208:211], v[42:45]
	v_mfma_f32_16x16x32_bf16 v[30:33], v[152:155], v[216:219], v[30:33]
	v_mfma_f32_16x16x32_bf16 v[26:29], v[160:163], v[216:219], v[26:29]
	v_mfma_f32_16x16x32_bf16 v[14:17], v[152:155], v[228:231], v[14:17]
	v_mfma_f32_16x16x32_bf16 v[10:13], v[160:163], v[228:231], v[10:13]
	v_mfma_f32_16x16x32_bf16 v[54:57], v[180:183], v[196:199], v[54:57]
	v_mfma_f32_16x16x32_bf16 v[50:53], v[188:191], v[196:199], v[50:53]
	v_mfma_f32_16x16x32_bf16 v[38:41], v[180:183], v[204:207], v[38:41]
	v_mfma_f32_16x16x32_bf16 v[34:37], v[188:191], v[204:207], v[34:37]
	v_mfma_f32_16x16x32_bf16 v[22:25], v[180:183], v[212:215], v[22:25]
	v_mfma_f32_16x16x32_bf16 v[18:21], v[188:191], v[212:215], v[18:21]
	v_mfma_f32_16x16x32_bf16 v[6:9], v[180:183], v[224:227], v[6:9]
	v_mfma_f32_16x16x32_bf16 v[2:5], v[188:191], v[224:227], v[2:5]
	v_mfma_f32_16x16x32_bf16 v[54:57], v[184:187], v[200:203], v[54:57]
	v_mfma_f32_16x16x32_bf16 v[50:53], v[192:195], v[200:203], v[50:53]
	v_mfma_f32_16x16x32_bf16 v[38:41], v[184:187], v[208:211], v[38:41]
	v_mfma_f32_16x16x32_bf16 v[34:37], v[192:195], v[208:211], v[34:37]
	v_mfma_f32_16x16x32_bf16 v[22:25], v[184:187], v[216:219], v[22:25]
	v_mfma_f32_16x16x32_bf16 v[18:21], v[192:195], v[216:219], v[18:21]
	v_mfma_f32_16x16x32_bf16 v[6:9], v[184:187], v[228:231], v[6:9]
	v_mfma_f32_16x16x32_bf16 v[2:5], v[192:195], v[228:231], v[2:5]
	s_barrier
	s_add_i32 s72, s72, 2
	s_add_u32 s8, s8, 0x100
	s_addc_u32 s9, s9, 0
	s_add_u32 s70, s70, 0x100
	s_addc_u32 s71, s71, 0
	s_cmp_gt_u32 s72, 29
.LBB0_1048:
	s_setprio 1
	ds_read_b128 v[148:151], v169
	ds_read_b128 v[152:155], v169 offset:1024
	ds_read_b128 v[156:159], v169 offset:2048
	ds_read_b128 v[160:163], v169 offset:3072
	ds_read_b128 v[180:183], v171
	ds_read_b128 v[184:187], v171 offset:1024
	ds_read_b128 v[188:191], v171 offset:2048
	ds_read_b128 v[192:195], v171 offset:3072
	s_add_u32 s18, s8, 0xfff80080
	s_addc_u32 s19, s9, -1
	s_cmp_eq_u32 s72, 28
	s_cselect_b32 s45, s1, s19
	s_cselect_b32 s44, s37, s18
	s_cselect_b32 s43, s25, s71
	s_cselect_b32 s42, s69, s70
	s_add_i32 m0, s51, 0xc000
	ds_read_b128 v[196:199], v173
	ds_read_b128 v[200:203], v173 offset:1024
	ds_read_b128 v[204:207], v173 offset:2048
	ds_read_b128 v[208:211], v173 offset:3072
	ds_read_b128 v[212:215], v173 offset:4096
	ds_read_b128 v[216:219], v173 offset:5120
	ds_read_b128 v[224:227], v173 offset:6144
	ds_read_b128 v[228:231], v173 offset:7168
	global_load_lds_dwordx4 v140, s[8:9]
	s_add_i32 m0, s51, 0xe000
	s_nop 0
	global_load_lds_dwordx4 v142, s[8:9]
	s_waitcnt vmcnt(8)
	s_waitcnt lgkmcnt(0)
	s_barrier
	s_setprio 0
	v_mfma_f32_16x16x32_bf16 v[126:129], v[148:151], v[196:199], v[126:129]
	v_mfma_f32_16x16x32_bf16 v[122:125], v[156:159], v[196:199], v[122:125]
	v_mfma_f32_16x16x32_bf16 v[110:113], v[148:151], v[204:207], v[110:113]
	v_mfma_f32_16x16x32_bf16 v[106:109], v[156:159], v[204:207], v[106:109]
	v_mfma_f32_16x16x32_bf16 v[94:97], v[148:151], v[212:215], v[94:97]
	v_mfma_f32_16x16x32_bf16 v[90:93], v[156:159], v[212:215], v[90:93]
	v_mfma_f32_16x16x32_bf16 v[78:81], v[148:151], v[224:227], v[78:81]
	v_mfma_f32_16x16x32_bf16 v[74:77], v[156:159], v[224:227], v[74:77]
	v_mfma_f32_16x16x32_bf16 v[126:129], v[152:155], v[200:203], v[126:129]
	v_mfma_f32_16x16x32_bf16 v[122:125], v[160:163], v[200:203], v[122:125]
	v_mfma_f32_16x16x32_bf16 v[110:113], v[152:155], v[208:211], v[110:113]
	v_mfma_f32_16x16x32_bf16 v[106:109], v[160:163], v[208:211], v[106:109]
	v_mfma_f32_16x16x32_bf16 v[94:97], v[152:155], v[216:219], v[94:97]
	v_mfma_f32_16x16x32_bf16 v[90:93], v[160:163], v[216:219], v[90:93]
	v_mfma_f32_16x16x32_bf16 v[78:81], v[152:155], v[228:231], v[78:81]
	v_mfma_f32_16x16x32_bf16 v[74:77], v[160:163], v[228:231], v[74:77]
	v_mfma_f32_16x16x32_bf16 v[118:121], v[180:183], v[196:199], v[118:121]
	v_mfma_f32_16x16x32_bf16 v[114:117], v[188:191], v[196:199], v[114:117]
	v_mfma_f32_16x16x32_bf16 v[102:105], v[180:183], v[204:207], v[102:105]
	v_mfma_f32_16x16x32_bf16 v[98:101], v[188:191], v[204:207], v[98:101]
	v_mfma_f32_16x16x32_bf16 v[86:89], v[180:183], v[212:215], v[86:89]
	v_mfma_f32_16x16x32_bf16 v[82:85], v[188:191], v[212:215], v[82:85]
	v_mfma_f32_16x16x32_bf16 v[70:73], v[180:183], v[224:227], v[70:73]
	v_mfma_f32_16x16x32_bf16 v[66:69], v[188:191], v[224:227], v[66:69]
	v_mfma_f32_16x16x32_bf16 v[118:121], v[184:187], v[200:203], v[118:121]
	v_mfma_f32_16x16x32_bf16 v[114:117], v[192:195], v[200:203], v[114:117]
	v_mfma_f32_16x16x32_bf16 v[102:105], v[184:187], v[208:211], v[102:105]
	v_mfma_f32_16x16x32_bf16 v[98:101], v[192:195], v[208:211], v[98:101]
	v_mfma_f32_16x16x32_bf16 v[86:89], v[184:187], v[216:219], v[86:89]
	v_mfma_f32_16x16x32_bf16 v[82:85], v[192:195], v[216:219], v[82:85]
	v_mfma_f32_16x16x32_bf16 v[70:73], v[184:187], v[228:231], v[70:73]
	v_mfma_f32_16x16x32_bf16 v[66:69], v[192:195], v[228:231], v[66:69]
	s_barrier
; #define PG8_STAGE(bufoff, gbase, voff) do { _Pragma("unroll") for (int _i = 0; _i < 2; ++_i) \
;         __builtin_amdgcn_global_load_lds((const unsigned*)((const char*)(gbase) + (voff)[_i]), (PG8_LAS unsigned*)(lds + (bufoff) + ldsw + _i * 8192), 16, 0, 0); } while (0)
; #define PG8_LDA(dst, b, h) do { _Pragma("unroll") for (int m = 0; m < 4; ++m) _Pragma("unroll") for (int k = 0; k < 2; ++k) dst[m][k] = *(const PG8_LAS bf16x8*)(lds + PG8_SA(b, h) + aoff + m * 2048 + k * 1024); } while (0)
; #define PG8_LDB(dst, b, h) do { _Pragma("unroll") for (int n = 0; n < 2; ++n) _Pragma("unroll") for (int k = 0; k < 2; ++k) dst[n][k] = *(const PG8_LAS bf16x8*)(lds + PG8_SB(b, h) + boff + n * 2048 + k * 1024); } while (0)
; #define PG8_MMA(ai, bj, At, Bt) do { __builtin_amdgcn_s_setprio(1); _Pragma("unroll") for (int m = 0; m < 4; ++m) _Pragma("unroll") for (int n = 0; n < 2; ++n) _Pragma("unroll") for (int k = 0; k < 2; ++k) \
;         acc[ai][bj][m][n] = __builtin_amdgcn_mfma_f32_16x16x32_bf16(Bt[n][k], At[m][k], acc[ai][bj][m][n], 0, 0, 0); __builtin_amdgcn_s_setprio(0); } while (0)
; #define PG8_WAIT_V(n) asm volatile("s_waitcnt vmcnt(" #n ")" ::: "memory")
; #define PG8_WAIT_L(n) asm volatile("s_waitcnt lgkmcnt(" #n ")" ::: "memory")
; #define PG8_BAR __builtin_amdgcn_s_barrier()
; #define PG8_SCHED __builtin_amdgcn_sched_barrier(0)
; template <class Epi, class Sched, bool ALIGN_EPI = false, bool SP2 = false>
; __device__ __forceinline__ void gemm_phase(PG8_LAS unsigned char* lds, const Gemm g, const Sched& S, const Epi& E) {
;     ...
;             PG8_LDA(At, 0, 1); PG8_STAGE(PG8_SB(0, 0), b2, voffB); PG8_STAGE(PG8_SB(0, 1), b2 + hB, voffB); PG8_STAGE(PG8_SA(0, 0), a2, voffA);
;             PG8_WAIT_V(8); PG8_WAIT_L(0); PG8_BAR; PG8_MMA(1, 0, At, B0); PG8_MMA(1, 1, At, B1); PG8_BAR; PG8_SCHED;
;             PG8_LDB(B0, 1, 0); PG8_LDB(B1, 1, 1); PG8_SCHED; PG8_LDA(At, 1, 0); PG8_STAGE(PG8_SA(0, 1), a2 + hA, voffA);
	s_setprio 1
	s_add_i32 s18, s63, s49
	s_add_u32 s76, s42, s20
	s_addc_u32 s77, s43, s21
	s_mov_b32 m0, s18
	ds_read_b128 v[196:199], v173 offset:16384
	ds_read_b128 v[200:203], v173 offset:17408
	ds_read_b128 v[204:207], v173 offset:18432
	ds_read_b128 v[208:211], v173 offset:19456
	ds_read_b128 v[212:215], v173 offset:20480
	ds_read_b128 v[216:219], v173 offset:21504
	ds_read_b128 v[224:227], v173 offset:22528
	ds_read_b128 v[228:231], v173 offset:23552
	global_load_lds_dwordx4 v134, s[42:43]
	s_add_i32 m0, s18, 0x2000
	s_add_u32 s74, s42, 0x80000
	s_addc_u32 s75, s43, 0
	s_add_i32 s18, s64, s49
	global_load_lds_dwordx4 v130, s[42:43]
	s_mov_b32 m0, s18
	s_nop 0
	global_load_lds_dwordx4 v134, s[74:75]
	s_add_i32 m0, s18, 0x2000
	s_nop 0
	global_load_lds_dwordx4 v130, s[74:75]
	s_add_u32 s78, s44, s20
	s_addc_u32 s79, s45, s21
	s_mov_b32 m0, s51
	s_nop 0
	global_load_lds_dwordx4 v136, s[44:45]
	s_mov_b32 m0, s52
	s_nop 0
	global_load_lds_dwordx4 v132, s[44:45]
	s_waitcnt vmcnt(8)
	s_waitcnt lgkmcnt(0)
	s_barrier
	s_setprio 0
	v_mfma_f32_16x16x32_bf16 v[62:65], v[148:151], v[196:199], v[62:65]
	v_mfma_f32_16x16x32_bf16 v[58:61], v[156:159], v[196:199], v[58:61]
	v_mfma_f32_16x16x32_bf16 v[46:49], v[148:151], v[204:207], v[46:49]
	v_mfma_f32_16x16x32_bf16 v[42:45], v[156:159], v[204:207], v[42:45]
	v_mfma_f32_16x16x32_bf16 v[30:33], v[148:151], v[212:215], v[30:33]
	v_mfma_f32_16x16x32_bf16 v[26:29], v[156:159], v[212:215], v[26:29]
	v_mfma_f32_16x16x32_bf16 v[14:17], v[148:151], v[224:227], v[14:17]
	v_mfma_f32_16x16x32_bf16 v[10:13], v[156:159], v[224:227], v[10:13]
	v_mfma_f32_16x16x32_bf16 v[62:65], v[152:155], v[200:203], v[62:65]
	v_mfma_f32_16x16x32_bf16 v[58:61], v[160:163], v[200:203], v[58:61]
	v_mfma_f32_16x16x32_bf16 v[46:49], v[152:155], v[208:211], v[46:49]
	v_mfma_f32_16x16x32_bf16 v[42:45], v[160:163], v[208:211], v[42:45]
	v_mfma_f32_16x16x32_bf16 v[30:33], v[152:155], v[216:219], v[30:33]
	v_mfma_f32_16x16x32_bf16 v[26:29], v[160:163], v[216:219], v[26:29]
	v_mfma_f32_16x16x32_bf16 v[14:17], v[152:155], v[228:231], v[14:17]
	v_mfma_f32_16x16x32_bf16 v[10:13], v[160:163], v[228:231], v[10:13]
	v_mfma_f32_16x16x32_bf16 v[54:57], v[180:183], v[196:199], v[54:57]
	v_mfma_f32_16x16x32_bf16 v[50:53], v[188:191], v[196:199], v[50:53]
	v_mfma_f32_16x16x32_bf16 v[38:41], v[180:183], v[204:207], v[38:41]
	v_mfma_f32_16x16x32_bf16 v[34:37], v[188:191], v[204:207], v[34:37]
	v_mfma_f32_16x16x32_bf16 v[22:25], v[180:183], v[212:215], v[22:25]
	v_mfma_f32_16x16x32_bf16 v[18:21], v[188:191], v[212:215], v[18:21]
	v_mfma_f32_16x16x32_bf16 v[6:9], v[180:183], v[224:227], v[6:9]
	v_mfma_f32_16x16x32_bf16 v[2:5], v[188:191], v[224:227], v[2:5]
	v_mfma_f32_16x16x32_bf16 v[54:57], v[184:187], v[200:203], v[54:57]
	v_mfma_f32_16x16x32_bf16 v[50:53], v[192:195], v[200:203], v[50:53]
	v_mfma_f32_16x16x32_bf16 v[38:41], v[184:187], v[208:211], v[38:41]
	v_mfma_f32_16x16x32_bf16 v[34:37], v[192:195], v[208:211], v[34:37]
	v_mfma_f32_16x16x32_bf16 v[22:25], v[184:187], v[216:219], v[22:25]
	v_mfma_f32_16x16x32_bf16 v[18:21], v[192:195], v[216:219], v[18:21]
	v_mfma_f32_16x16x32_bf16 v[6:9], v[184:187], v[228:231], v[6:9]
	v_mfma_f32_16x16x32_bf16 v[2:5], v[192:195], v[228:231], v[2:5]
	s_barrier
	s_setprio 1
	s_add_i32 s18, 0, 0x18000
	s_add_i32 s19, 0, 0x1c000
	v_add_u32_e32 v160, s18, v165
	v_add_u32_e32 v164, s19, v165
	ds_read_b128 v[148:151], v160
	ds_read_b128 v[152:155], v160 offset:1024
	ds_read_b128 v[156:159], v160 offset:2048
	ds_read_b128 v[160:163], v160 offset:3072
	ds_read_b128 v[180:183], v164
	ds_read_b128 v[184:187], v164 offset:1024
	ds_read_b128 v[188:191], v164 offset:2048
	ds_read_b128 v[192:195], v164 offset:3072
	s_add_u32 s44, s44, 0x80000
	s_addc_u32 s45, s45, 0
	s_mov_b32 m0, s53
	ds_read_b128 v[196:199], v173 offset:32768
	ds_read_b128 v[200:203], v173 offset:33792
	ds_read_b128 v[204:207], v173 offset:34816
	ds_read_b128 v[208:211], v173 offset:35840
	ds_read_b128 v[212:215], v173 offset:36864
	ds_read_b128 v[216:219], v173 offset:37888
	ds_read_b128 v[224:227], v173 offset:38912
	ds_read_b128 v[228:231], v173 offset:39936
	global_load_lds_dwordx4 v136, s[44:45]
	s_mov_b32 m0, s57
	s_nop 0
	global_load_lds_dwordx4 v132, s[44:45]
	s_waitcnt vmcnt(8)
	s_waitcnt lgkmcnt(0)
	s_barrier
; #define PG8_STAGE(bufoff, gbase, voff) do { _Pragma("unroll") for (int _i = 0; _i < 2; ++_i) \
;         __builtin_amdgcn_global_load_lds((const unsigned*)((const char*)(gbase) + (voff)[_i]), (PG8_LAS unsigned*)(lds + (bufoff) + ldsw + _i * 8192), 16, 0, 0); } while (0)
; #define PG8_LDA(dst, b, h) do { _Pragma("unroll") for (int m = 0; m < 4; ++m) _Pragma("unroll") for (int k = 0; k < 2; ++k) dst[m][k] = *(const PG8_LAS bf16x8*)(lds + PG8_SA(b, h) + aoff + m * 2048 + k * 1024); } while (0)
; #define PG8_LDB(dst, b, h) do { _Pragma("unroll") for (int n = 0; n < 2; ++n) _Pragma("unroll") for (int k = 0; k < 2; ++k) dst[n][k] = *(const PG8_LAS bf16x8*)(lds + PG8_SB(b, h) + boff + n * 2048 + k * 1024); } while (0)
; #define PG8_MMA(ai, bj, At, Bt) do { __builtin_amdgcn_s_setprio(1); _Pragma("unroll") for (int m = 0; m < 4; ++m) _Pragma("unroll") for (int n = 0; n < 2; ++n) _Pragma("unroll") for (int k = 0; k < 2; ++k) \
;         acc[ai][bj][m][n] = __builtin_amdgcn_mfma_f32_16x16x32_bf16(Bt[n][k], At[m][k], acc[ai][bj][m][n], 0, 0, 0); __builtin_amdgcn_s_setprio(0); } while (0)
; #define PG8_WAIT_V(n) asm volatile("s_waitcnt vmcnt(" #n ")" ::: "memory")
; #define PG8_WAIT_L(n) asm volatile("s_waitcnt lgkmcnt(" #n ")" ::: "memory")
; #define PG8_BAR __builtin_amdgcn_s_barrier()
; #define PG8_SCHED __builtin_amdgcn_sched_barrier(0)
; template <class Epi, class Sched, bool ALIGN_EPI = false, bool SP2 = false>
; __device__ __forceinline__ void gemm_phase(PG8_LAS unsigned char* lds, const Gemm g, const Sched& S, const Epi& E) {
;     ...
;             PG8_WAIT_V(8); PG8_WAIT_L(0); PG8_BAR; PG8_MMA(1, 0, At, B0); PG8_MMA(1, 1, At, B1); PG8_BAR; PG8_SCHED;
;             PG8_LDB(B0, 1, 0); PG8_LDB(B1, 1, 1); PG8_SCHED; PG8_LDA(At, 1, 0); PG8_STAGE(PG8_SA(0, 1), a2 + hA, voffA);
;             PG8_WAIT_V(8); PG8_WAIT_L(0); PG8_BAR; PG8_MMA(0, 0, At, B0); PG8_MMA(0, 1, At, B1); PG8_BAR; PG8_SCHED;
;             PG8_LDA(At, 1, 1); PG8_STAGE(PG8_SB(1, 0), b3, voffB); PG8_STAGE(PG8_SB(1, 1), b3 + hB, voffB); PG8_STAGE(PG8_SA(1, 0), a3, voffA);
;             PG8_WAIT_V(8); PG8_WAIT_L(0); PG8_BAR; PG8_MMA(1, 0, At, B0); PG8_MMA(1, 1, At, B1); PG8_BAR; PG8_SCHED;
	s_setprio 0
	v_mfma_f32_16x16x32_bf16 v[126:129], v[148:151], v[196:199], v[126:129]
	v_mfma_f32_16x16x32_bf16 v[122:125], v[156:159], v[196:199], v[122:125]
	v_mfma_f32_16x16x32_bf16 v[110:113], v[148:151], v[204:207], v[110:113]
	v_mfma_f32_16x16x32_bf16 v[106:109], v[156:159], v[204:207], v[106:109]
	v_mfma_f32_16x16x32_bf16 v[94:97], v[148:151], v[212:215], v[94:97]
	v_mfma_f32_16x16x32_bf16 v[90:93], v[156:159], v[212:215], v[90:93]
	v_mfma_f32_16x16x32_bf16 v[78:81], v[148:151], v[224:227], v[78:81]
	v_mfma_f32_16x16x32_bf16 v[74:77], v[156:159], v[224:227], v[74:77]
	v_mfma_f32_16x16x32_bf16 v[126:129], v[152:155], v[200:203], v[126:129]
	v_mfma_f32_16x16x32_bf16 v[122:125], v[160:163], v[200:203], v[122:125]
	v_mfma_f32_16x16x32_bf16 v[110:113], v[152:155], v[208:211], v[110:113]
	v_mfma_f32_16x16x32_bf16 v[106:109], v[160:163], v[208:211], v[106:109]
	v_mfma_f32_16x16x32_bf16 v[94:97], v[152:155], v[216:219], v[94:97]
	v_mfma_f32_16x16x32_bf16 v[90:93], v[160:163], v[216:219], v[90:93]
	v_mfma_f32_16x16x32_bf16 v[78:81], v[152:155], v[228:231], v[78:81]
	v_mfma_f32_16x16x32_bf16 v[74:77], v[160:163], v[228:231], v[74:77]
	v_mfma_f32_16x16x32_bf16 v[118:121], v[180:183], v[196:199], v[118:121]
	v_mfma_f32_16x16x32_bf16 v[114:117], v[188:191], v[196:199], v[114:117]
	v_mfma_f32_16x16x32_bf16 v[102:105], v[180:183], v[204:207], v[102:105]
	v_mfma_f32_16x16x32_bf16 v[98:101], v[188:191], v[204:207], v[98:101]
	v_mfma_f32_16x16x32_bf16 v[86:89], v[180:183], v[212:215], v[86:89]
	v_mfma_f32_16x16x32_bf16 v[82:85], v[188:191], v[212:215], v[82:85]
	v_mfma_f32_16x16x32_bf16 v[70:73], v[180:183], v[224:227], v[70:73]
	v_mfma_f32_16x16x32_bf16 v[66:69], v[188:191], v[224:227], v[66:69]
	v_mfma_f32_16x16x32_bf16 v[118:121], v[184:187], v[200:203], v[118:121]
	v_mfma_f32_16x16x32_bf16 v[114:117], v[192:195], v[200:203], v[114:117]
	v_mfma_f32_16x16x32_bf16 v[102:105], v[184:187], v[208:211], v[102:105]
	v_mfma_f32_16x16x32_bf16 v[98:101], v[192:195], v[208:211], v[98:101]
	v_mfma_f32_16x16x32_bf16 v[86:89], v[184:187], v[216:219], v[86:89]
	v_mfma_f32_16x16x32_bf16 v[82:85], v[192:195], v[216:219], v[82:85]
	v_mfma_f32_16x16x32_bf16 v[70:73], v[184:187], v[228:231], v[70:73]
	v_mfma_f32_16x16x32_bf16 v[66:69], v[192:195], v[228:231], v[66:69]
	s_barrier
	s_setprio 1
	s_add_i32 s18, s18, s49
	s_mov_b32 m0, s18
	ds_read_b128 v[196:199], v173 offset:49152
	ds_read_b128 v[200:203], v173 offset:50176
	ds_read_b128 v[204:207], v173 offset:51200
	ds_read_b128 v[208:211], v173 offset:52224
	ds_read_b128 v[212:215], v173 offset:53248
	ds_read_b128 v[216:219], v173 offset:54272
	ds_read_b128 v[224:227], v173 offset:55296
	ds_read_b128 v[228:231], v173 offset:56320
	global_load_lds_dwordx4 v134, s[76:77]
	s_add_i32 m0, s18, 0x2000
	s_add_u32 s42, s42, 0x80080
	s_addc_u32 s43, s43, 0
	s_add_i32 s18, s19, s49
	global_load_lds_dwordx4 v130, s[76:77]
	s_mov_b32 m0, s18
	s_nop 0
	global_load_lds_dwordx4 v134, s[42:43]
	s_add_i32 m0, s18, 0x2000
	s_nop 0
	global_load_lds_dwordx4 v130, s[42:43]
	s_mov_b32 m0, s60
	s_nop 0
	global_load_lds_dwordx4 v136, s[78:79]
	s_mov_b32 m0, s61
	s_nop 0
	global_load_lds_dwordx4 v132, s[78:79]
	s_waitcnt vmcnt(8)
	s_waitcnt lgkmcnt(0)
	s_barrier
	s_setprio 0
	v_mfma_f32_16x16x32_bf16 v[62:65], v[148:151], v[196:199], v[62:65]
	v_mfma_f32_16x16x32_bf16 v[58:61], v[156:159], v[196:199], v[58:61]
	v_mfma_f32_16x16x32_bf16 v[46:49], v[148:151], v[204:207], v[46:49]
	v_mfma_f32_16x16x32_bf16 v[42:45], v[156:159], v[204:207], v[42:45]
	v_mfma_f32_16x16x32_bf16 v[30:33], v[148:151], v[212:215], v[30:33]
	v_mfma_f32_16x16x32_bf16 v[26:29], v[156:159], v[212:215], v[26:29]
	v_mfma_f32_16x16x32_bf16 v[14:17], v[148:151], v[224:227], v[14:17]
	v_mfma_f32_16x16x32_bf16 v[10:13], v[156:159], v[224:227], v[10:13]
	v_mfma_f32_16x16x32_bf16 v[62:65], v[152:155], v[200:203], v[62:65]
	v_mfma_f32_16x16x32_bf16 v[58:61], v[160:163], v[200:203], v[58:61]
	v_mfma_f32_16x16x32_bf16 v[46:49], v[152:155], v[208:211], v[46:49]
	v_mfma_f32_16x16x32_bf16 v[42:45], v[160:163], v[208:211], v[42:45]
	v_mfma_f32_16x16x32_bf16 v[30:33], v[152:155], v[216:219], v[30:33]
	v_mfma_f32_16x16x32_bf16 v[26:29], v[160:163], v[216:219], v[26:29]
	v_mfma_f32_16x16x32_bf16 v[14:17], v[152:155], v[228:231], v[14:17]
	v_mfma_f32_16x16x32_bf16 v[10:13], v[160:163], v[228:231], v[10:13]
	v_mfma_f32_16x16x32_bf16 v[54:57], v[180:183], v[196:199], v[54:57]
	v_mfma_f32_16x16x32_bf16 v[50:53], v[188:191], v[196:199], v[50:53]
	v_mfma_f32_16x16x32_bf16 v[38:41], v[180:183], v[204:207], v[38:41]
	v_mfma_f32_16x16x32_bf16 v[34:37], v[188:191], v[204:207], v[34:37]
	v_mfma_f32_16x16x32_bf16 v[22:25], v[180:183], v[212:215], v[22:25]
	v_mfma_f32_16x16x32_bf16 v[18:21], v[188:191], v[212:215], v[18:21]
	v_mfma_f32_16x16x32_bf16 v[6:9], v[180:183], v[224:227], v[6:9]
	v_mfma_f32_16x16x32_bf16 v[2:5], v[188:191], v[224:227], v[2:5]
	v_mfma_f32_16x16x32_bf16 v[54:57], v[184:187], v[200:203], v[54:57]
	v_mfma_f32_16x16x32_bf16 v[50:53], v[192:195], v[200:203], v[50:53]
	v_mfma_f32_16x16x32_bf16 v[38:41], v[184:187], v[208:211], v[38:41]
	v_mfma_f32_16x16x32_bf16 v[34:37], v[192:195], v[208:211], v[34:37]
	v_mfma_f32_16x16x32_bf16 v[22:25], v[184:187], v[216:219], v[22:25]
	v_mfma_f32_16x16x32_bf16 v[18:21], v[192:195], v[216:219], v[18:21]
	v_mfma_f32_16x16x32_bf16 v[6:9], v[184:187], v[228:231], v[6:9]
	v_mfma_f32_16x16x32_bf16 v[2:5], v[192:195], v[228:231], v[2:5]
	s_barrier
	s_add_i32 s72, s72, 2
	s_add_u32 s8, s8, 0x100
	s_addc_u32 s9, s9, 0
	s_add_u32 s70, s70, 0x100
	s_addc_u32 s71, s71, 0
	s_cmp_gt_u32 s72, 29
	s_cbranch_scc0 .LBB0_1048
	s_and_b64 vcc, exec, s[22:23]
	s_cbranch_vccz .LBB0_1051
	s_barrier

; #define PG8_STAGE(bufoff, gbase, voff) do { _Pragma("unroll") for (int _i = 0; _i < 2; ++_i) \
;         __builtin_amdgcn_global_load_lds((const unsigned*)((const char*)(gbase) + (voff)[_i]), (PG8_LAS unsigned*)(lds + (bufoff) + ldsw + _i * 8192), 16, 0, 0); } while (0)
; #define PG8_LDA(dst, b, h) do { _Pragma("unroll") for (int m = 0; m < 4; ++m) _Pragma("unroll") for (int k = 0; k < 2; ++k) dst[m][k] = *(const PG8_LAS bf16x8*)(lds + PG8_SA(b, h) + aoff + m * 2048 + k * 1024); } while (0)
; #define PG8_LDB(dst, b, h) do { _Pragma("unroll") for (int n = 0; n < 2; ++n) _Pragma("unroll") for (int k = 0; k < 2; ++k) dst[n][k] = *(const PG8_LAS bf16x8*)(lds + PG8_SB(b, h) + boff + n * 2048 + k * 1024); } while (0)
; #define PG8_WAIT_V(n) asm volatile("s_waitcnt vmcnt(" #n ")" ::: "memory")
; #define PG8_WAIT_L(n) asm volatile("s_waitcnt lgkmcnt(" #n ")" ::: "memory")
; #define PG8_BAR __builtin_amdgcn_s_barrier()
; #define PG8_SCHED __builtin_amdgcn_sched_barrier(0)
; template <class Epi, class Sched, bool ALIGN_EPI = false, bool SP2 = false>
; __device__ __forceinline__ void gemm_phase(PG8_LAS unsigned char* lds, const Gemm g, const Sched& S, const Epi& E) {
;     ...
;         const char* nA = has_next ? (const char*)g.A + (size_t)nxt.pm * tA + (size_t)nxt.pn * pnA : cA; const char* nB = has_next ? (const char*)g.Bt + (size_t)nxt.pn * tB : cB;
; #pragma nounroll
;         for (int t = 0; t < nt; t += 2) {
;             const bool last = (t == nt - 2);
;             const char* a1 = cA + (size_t)(t + 1) * kstep;
;             const char* a2 = last ? nA : cA + (size_t)(t + 2) * kstep; const char* b2 = last ? nB : cB + (size_t)(t + 2) * kstep;
;             const char* a3 = a2 + kstep; const char* b3 = b2 + kstep;
;             if (last && has_next) S.a_ready(nxt);
;             if constexpr (SP2) {
;             PG8_LDB(B0, 0, 0); PG8_LDB(B1, 0, 1); PG8_SCHED; PG8_LDA(At, 0, 0); PG8_STAGE(PG8_SA(1, 1), a1 + hA, voffA);
;             PG8_WAIT_V(8); PG8_WAIT_L(0); PG8_BAR; PG8_MMA(0, 0, At, B0); PG8_MMA(0, 1, At, B1); PG8_BAR; PG8_SCHED;
;             PG8_LDA(At, 0, 1); PG8_STAGE(PG8_SB(0, 0), b2, voffB); PG8_STAGE(PG8_SB(0, 1), b2 + hB, voffB); PG8_STAGE(PG8_SA(0, 0), a2, voffA);
;             PG8_WAIT_V(8); PG8_WAIT_L(0); PG8_BAR; PG8_MMA(1, 0, At, B0); PG8_MMA(1, 1, At, B1); PG8_BAR; PG8_SCHED;
.LBB0_1126:
	s_add_u32 s61, s36, 0x100
	v_mov_b32_e32 v2, 0
	s_addc_u32 s62, s37, 0
	s_mov_b32 s63, -2
	s_waitcnt lgkmcnt(0)
	v_mov_b32_e32 v3, v2
	s_setprio 1
	ds_read_b128 v[130:133], v190
	ds_read_b128 v[134:137], v190 offset:1024
	ds_read_b128 v[138:141], v190 offset:2048
	ds_read_b128 v[142:145], v190 offset:3072
	ds_read_b128 v[146:149], v191
	ds_read_b128 v[150:153], v191 offset:1024
	ds_read_b128 v[170:173], v191 offset:2048
	ds_read_b128 v[174:177], v191 offset:3072
	s_add_u32 s36, s24, 0x100
	s_addc_u32 s37, s25, 0
	s_cmpk_eq_i32 s63, 0x54
	s_cselect_b32 s41, s9, s37
	s_cselect_b32 s40, s8, s36
	s_cselect_b32 s39, s23, s62
	s_cselect_b32 s38, s22, s61
	s_add_i32 m0, s46, 0xc000
	ds_read_b128 v[178:181], v192
	ds_read_b128 v[182:185], v192 offset:1024
	ds_read_b128 v[194:197], v192 offset:2048
	ds_read_b128 v[198:201], v192 offset:3072
	ds_read_b128 v[202:205], v192 offset:4096
	ds_read_b128 v[206:209], v192 offset:5120
	ds_read_b128 v[210:213], v192 offset:6144
	ds_read_b128 v[214:217], v192 offset:7168
	global_load_lds_dwordx4 v162, s[24:25]
	s_add_i32 m0, s46, 0xe000
	s_nop 0
	global_load_lds_dwordx4 v164, s[24:25]
	s_waitcnt vmcnt(8)
	s_waitcnt lgkmcnt(0)
	s_barrier
	s_setprio 0
	v_mfma_f32_16x16x32_bf16 v[126:129], v[130:133], v[178:181], 0
	v_mfma_f32_16x16x32_bf16 v[122:125], v[138:141], v[178:181], 0
	v_mfma_f32_16x16x32_bf16 v[110:113], v[130:133], v[194:197], 0
	v_mfma_f32_16x16x32_bf16 v[106:109], v[138:141], v[194:197], 0
	v_mfma_f32_16x16x32_bf16 v[94:97], v[130:133], v[202:205], 0
	v_mfma_f32_16x16x32_bf16 v[90:93], v[138:141], v[202:205], 0
	v_mfma_f32_16x16x32_bf16 v[78:81], v[130:133], v[210:213], 0
	v_mfma_f32_16x16x32_bf16 v[74:77], v[138:141], v[210:213], 0
	v_mfma_f32_16x16x32_bf16 v[126:129], v[134:137], v[182:185], v[126:129]
	v_mfma_f32_16x16x32_bf16 v[122:125], v[142:145], v[182:185], v[122:125]
	v_mfma_f32_16x16x32_bf16 v[110:113], v[134:137], v[198:201], v[110:113]
	v_mfma_f32_16x16x32_bf16 v[106:109], v[142:145], v[198:201], v[106:109]
	v_mfma_f32_16x16x32_bf16 v[94:97], v[134:137], v[206:209], v[94:97]
	v_mfma_f32_16x16x32_bf16 v[90:93], v[142:145], v[206:209], v[90:93]
	v_mfma_f32_16x16x32_bf16 v[78:81], v[134:137], v[214:217], v[78:81]
	v_mfma_f32_16x16x32_bf16 v[74:77], v[142:145], v[214:217], v[74:77]
	v_mfma_f32_16x16x32_bf16 v[118:121], v[146:149], v[178:181], 0
	v_mfma_f32_16x16x32_bf16 v[114:117], v[170:173], v[178:181], 0
	v_mfma_f32_16x16x32_bf16 v[102:105], v[146:149], v[194:197], 0
	v_mfma_f32_16x16x32_bf16 v[98:101], v[170:173], v[194:197], 0
	v_mfma_f32_16x16x32_bf16 v[86:89], v[146:149], v[202:205], 0
	v_mfma_f32_16x16x32_bf16 v[82:85], v[170:173], v[202:205], 0
	v_mfma_f32_16x16x32_bf16 v[70:73], v[146:149], v[210:213], 0
	v_mfma_f32_16x16x32_bf16 v[66:69], v[170:173], v[210:213], 0
	v_mfma_f32_16x16x32_bf16 v[118:121], v[150:153], v[182:185], v[118:121]
	v_mfma_f32_16x16x32_bf16 v[114:117], v[174:177], v[182:185], v[114:117]
	v_mfma_f32_16x16x32_bf16 v[102:105], v[150:153], v[198:201], v[102:105]
	v_mfma_f32_16x16x32_bf16 v[98:101], v[174:177], v[198:201], v[98:101]
	v_mfma_f32_16x16x32_bf16 v[86:89], v[150:153], v[206:209], v[86:89]
	v_mfma_f32_16x16x32_bf16 v[82:85], v[174:177], v[206:209], v[82:85]
	v_mfma_f32_16x16x32_bf16 v[70:73], v[150:153], v[214:217], v[70:73]
	v_mfma_f32_16x16x32_bf16 v[66:69], v[174:177], v[214:217], v[66:69]
	s_barrier
	s_setprio 1
	s_add_i32 s18, s55, s45
	s_add_u32 s76, s38, s16
	s_addc_u32 s77, s39, s17
	s_mov_b32 m0, s18
	ds_read_b128 v[178:181], v192 offset:16384
	ds_read_b128 v[182:185], v192 offset:17408
	ds_read_b128 v[194:197], v192 offset:18432
	ds_read_b128 v[198:201], v192 offset:19456
	ds_read_b128 v[202:205], v192 offset:20480
	ds_read_b128 v[206:209], v192 offset:21504
	ds_read_b128 v[210:213], v192 offset:22528
	ds_read_b128 v[214:217], v192 offset:23552
	global_load_lds_dwordx4 v156, s[38:39]
	s_add_i32 m0, s18, 0x2000
	s_add_u32 s24, s38, 0x160000
	s_addc_u32 s25, s39, 0
	s_add_i32 s18, s56, s45
	global_load_lds_dwordx4 v160, s[38:39]
	s_mov_b32 m0, s18
	s_nop 0
	global_load_lds_dwordx4 v156, s[24:25]
	s_add_i32 m0, s18, 0x2000
	s_nop 0
	global_load_lds_dwordx4 v160, s[24:25]
	s_add_u32 s78, s40, s16
	s_addc_u32 s79, s41, s17
	s_mov_b32 m0, s46
	s_nop 0
	global_load_lds_dwordx4 v154, s[40:41]
	s_mov_b32 m0, s47
	s_nop 0
	global_load_lds_dwordx4 v158, s[40:41]
	s_waitcnt vmcnt(8)
	s_waitcnt lgkmcnt(0)
	s_barrier
	s_setprio 0
	v_mfma_f32_16x16x32_bf16 v[62:65], v[130:133], v[178:181], 0
	v_mfma_f32_16x16x32_bf16 v[58:61], v[138:141], v[178:181], 0
	v_mfma_f32_16x16x32_bf16 v[46:49], v[130:133], v[194:197], 0
	v_mfma_f32_16x16x32_bf16 v[42:45], v[138:141], v[194:197], 0
	v_mfma_f32_16x16x32_bf16 v[30:33], v[130:133], v[202:205], 0
	v_mfma_f32_16x16x32_bf16 v[26:29], v[138:141], v[202:205], 0
	v_mfma_f32_16x16x32_bf16 v[14:17], v[130:133], v[210:213], 0
	v_mfma_f32_16x16x32_bf16 v[10:13], v[138:141], v[210:213], 0
	v_mfma_f32_16x16x32_bf16 v[62:65], v[134:137], v[182:185], v[62:65]
	v_mfma_f32_16x16x32_bf16 v[58:61], v[142:145], v[182:185], v[58:61]
	v_mfma_f32_16x16x32_bf16 v[46:49], v[134:137], v[198:201], v[46:49]
	v_mfma_f32_16x16x32_bf16 v[42:45], v[142:145], v[198:201], v[42:45]
	v_mfma_f32_16x16x32_bf16 v[30:33], v[134:137], v[206:209], v[30:33]
	v_mfma_f32_16x16x32_bf16 v[26:29], v[142:145], v[206:209], v[26:29]
	v_mfma_f32_16x16x32_bf16 v[14:17], v[134:137], v[214:217], v[14:17]
	v_mfma_f32_16x16x32_bf16 v[10:13], v[142:145], v[214:217], v[10:13]
	v_mfma_f32_16x16x32_bf16 v[54:57], v[146:149], v[178:181], 0
	v_mfma_f32_16x16x32_bf16 v[50:53], v[170:173], v[178:181], 0
	v_mfma_f32_16x16x32_bf16 v[38:41], v[146:149], v[194:197], 0
	v_mfma_f32_16x16x32_bf16 v[34:37], v[170:173], v[194:197], 0
	v_mfma_f32_16x16x32_bf16 v[22:25], v[146:149], v[202:205], 0
	v_mfma_f32_16x16x32_bf16 v[18:21], v[170:173], v[202:205], 0
	v_mfma_f32_16x16x32_bf16 v[6:9], v[146:149], v[210:213], 0
	v_mfma_f32_16x16x32_bf16 v[2:5], v[170:173], v[210:213], 0
	v_mfma_f32_16x16x32_bf16 v[54:57], v[150:153], v[182:185], v[54:57]
	v_mfma_f32_16x16x32_bf16 v[50:53], v[174:177], v[182:185], v[50:53]
	v_mfma_f32_16x16x32_bf16 v[38:41], v[150:153], v[198:201], v[38:41]
	v_mfma_f32_16x16x32_bf16 v[34:37], v[174:177], v[198:201], v[34:37]
	v_mfma_f32_16x16x32_bf16 v[22:25], v[150:153], v[206:209], v[22:25]
	v_mfma_f32_16x16x32_bf16 v[18:21], v[174:177], v[206:209], v[18:21]
	v_mfma_f32_16x16x32_bf16 v[6:9], v[150:153], v[214:217], v[6:9]
	v_mfma_f32_16x16x32_bf16 v[2:5], v[174:177], v[214:217], v[2:5]
	s_barrier
; #define PG8_STAGE(bufoff, gbase, voff) do { _Pragma("unroll") for (int _i = 0; _i < 2; ++_i) \
;         __builtin_amdgcn_global_load_lds((const unsigned*)((const char*)(gbase) + (voff)[_i]), (PG8_LAS unsigned*)(lds + (bufoff) + ldsw + _i * 8192), 16, 0, 0); } while (0)
; #define PG8_LDA(dst, b, h) do { _Pragma("unroll") for (int m = 0; m < 4; ++m) _Pragma("unroll") for (int k = 0; k < 2; ++k) dst[m][k] = *(const PG8_LAS bf16x8*)(lds + PG8_SA(b, h) + aoff + m * 2048 + k * 1024); } while (0)
; #define PG8_LDB(dst, b, h) do { _Pragma("unroll") for (int n = 0; n < 2; ++n) _Pragma("unroll") for (int k = 0; k < 2; ++k) dst[n][k] = *(const PG8_LAS bf16x8*)(lds + PG8_SB(b, h) + boff + n * 2048 + k * 1024); } while (0)
; #define PG8_MMA(ai, bj, At, Bt) do { __builtin_amdgcn_s_setprio(1); _Pragma("unroll") for (int m = 0; m < 4; ++m) _Pragma("unroll") for (int n = 0; n < 2; ++n) _Pragma("unroll") for (int k = 0; k < 2; ++k) \
;         acc[ai][bj][m][n] = __builtin_amdgcn_mfma_f32_16x16x32_bf16(Bt[n][k], At[m][k], acc[ai][bj][m][n], 0, 0, 0); __builtin_amdgcn_s_setprio(0); } while (0)
; #define PG8_WAIT_V(n) asm volatile("s_waitcnt vmcnt(" #n ")" ::: "memory")
; #define PG8_WAIT_L(n) asm volatile("s_waitcnt lgkmcnt(" #n ")" ::: "memory")
; #define PG8_BAR __builtin_amdgcn_s_barrier()
; #define PG8_SCHED __builtin_amdgcn_sched_barrier(0)
; template <class Epi, class Sched, bool ALIGN_EPI = false, bool SP2 = false>
; __device__ __forceinline__ void gemm_phase(PG8_LAS unsigned char* lds, const Gemm g, const Sched& S, const Epi& E) {
;     ...
;             PG8_LDB(B0, 1, 0); PG8_LDB(B1, 1, 1); PG8_SCHED; PG8_LDA(At, 1, 0); PG8_STAGE(PG8_SA(0, 1), a2 + hA, voffA);
;             PG8_WAIT_V(8); PG8_WAIT_L(0); PG8_BAR; PG8_MMA(0, 0, At, B0); PG8_MMA(0, 1, At, B1); PG8_BAR; PG8_SCHED;
;             PG8_LDA(At, 1, 1); PG8_STAGE(PG8_SB(1, 0), b3, voffB); PG8_STAGE(PG8_SB(1, 1), b3 + hB, voffB); PG8_STAGE(PG8_SA(1, 0), a3, voffA);
;             PG8_WAIT_V(8); PG8_WAIT_L(0); PG8_BAR; PG8_MMA(1, 0, At, B0); PG8_MMA(1, 1, At, B1); PG8_BAR; PG8_SCHED;
	s_setprio 1
	s_add_i32 s18, 0, 0x18000
	s_add_i32 s19, 0, 0x1c000
	v_add_u32_e32 v142, s18, v188
	v_add_u32_e32 v174, s19, v188
	ds_read_b128 v[130:133], v142
	ds_read_b128 v[134:137], v142 offset:1024
	ds_read_b128 v[138:141], v142 offset:2048
	ds_read_b128 v[142:145], v142 offset:3072
	ds_read_b128 v[146:149], v174
	ds_read_b128 v[150:153], v174 offset:1024
	ds_read_b128 v[170:173], v174 offset:2048
	ds_read_b128 v[174:177], v174 offset:3072
	s_add_u32 s24, s40, 0x160000
	s_addc_u32 s25, s41, 0
	s_mov_b32 m0, s48
	ds_read_b128 v[178:181], v192 offset:32768
	ds_read_b128 v[182:185], v192 offset:33792
	ds_read_b128 v[194:197], v192 offset:34816
	ds_read_b128 v[198:201], v192 offset:35840
	ds_read_b128 v[202:205], v192 offset:36864
	ds_read_b128 v[206:209], v192 offset:37888
	ds_read_b128 v[210:213], v192 offset:38912
	ds_read_b128 v[214:217], v192 offset:39936
	global_load_lds_dwordx4 v154, s[24:25]
	s_mov_b32 m0, s49
	s_nop 0
	global_load_lds_dwordx4 v158, s[24:25]
	s_waitcnt vmcnt(8)
	s_waitcnt lgkmcnt(0)
	s_barrier
	s_setprio 0
	v_mfma_f32_16x16x32_bf16 v[126:129], v[130:133], v[178:181], v[126:129]
	v_mfma_f32_16x16x32_bf16 v[122:125], v[138:141], v[178:181], v[122:125]
	v_mfma_f32_16x16x32_bf16 v[110:113], v[130:133], v[194:197], v[110:113]
	v_mfma_f32_16x16x32_bf16 v[106:109], v[138:141], v[194:197], v[106:109]
	v_mfma_f32_16x16x32_bf16 v[94:97], v[130:133], v[202:205], v[94:97]
	v_mfma_f32_16x16x32_bf16 v[90:93], v[138:141], v[202:205], v[90:93]
	v_mfma_f32_16x16x32_bf16 v[78:81], v[130:133], v[210:213], v[78:81]
	v_mfma_f32_16x16x32_bf16 v[74:77], v[138:141], v[210:213], v[74:77]
	v_mfma_f32_16x16x32_bf16 v[126:129], v[134:137], v[182:185], v[126:129]
	v_mfma_f32_16x16x32_bf16 v[122:125], v[142:145], v[182:185], v[122:125]
	v_mfma_f32_16x16x32_bf16 v[110:113], v[134:137], v[198:201], v[110:113]
	v_mfma_f32_16x16x32_bf16 v[106:109], v[142:145], v[198:201], v[106:109]
	v_mfma_f32_16x16x32_bf16 v[94:97], v[134:137], v[206:209], v[94:97]
	v_mfma_f32_16x16x32_bf16 v[90:93], v[142:145], v[206:209], v[90:93]
	v_mfma_f32_16x16x32_bf16 v[78:81], v[134:137], v[214:217], v[78:81]
	v_mfma_f32_16x16x32_bf16 v[74:77], v[142:145], v[214:217], v[74:77]
	v_mfma_f32_16x16x32_bf16 v[118:121], v[146:149], v[178:181], v[118:121]
	v_mfma_f32_16x16x32_bf16 v[114:117], v[170:173], v[178:181], v[114:117]
	v_mfma_f32_16x16x32_bf16 v[102:105], v[146:149], v[194:197], v[102:105]
	v_mfma_f32_16x16x32_bf16 v[98:101], v[170:173], v[194:197], v[98:101]
	v_mfma_f32_16x16x32_bf16 v[86:89], v[146:149], v[202:205], v[86:89]
	v_mfma_f32_16x16x32_bf16 v[82:85], v[170:173], v[202:205], v[82:85]
	v_mfma_f32_16x16x32_bf16 v[70:73], v[146:149], v[210:213], v[70:73]
	v_mfma_f32_16x16x32_bf16 v[66:69], v[170:173], v[210:213], v[66:69]
	v_mfma_f32_16x16x32_bf16 v[118:121], v[150:153], v[182:185], v[118:121]
	v_mfma_f32_16x16x32_bf16 v[114:117], v[174:177], v[182:185], v[114:117]
	v_mfma_f32_16x16x32_bf16 v[102:105], v[150:153], v[198:201], v[102:105]
	v_mfma_f32_16x16x32_bf16 v[98:101], v[174:177], v[198:201], v[98:101]
	v_mfma_f32_16x16x32_bf16 v[86:89], v[150:153], v[206:209], v[86:89]
	v_mfma_f32_16x16x32_bf16 v[82:85], v[174:177], v[206:209], v[82:85]
	v_mfma_f32_16x16x32_bf16 v[70:73], v[150:153], v[214:217], v[70:73]
	v_mfma_f32_16x16x32_bf16 v[66:69], v[174:177], v[214:217], v[66:69]
	s_barrier
	s_setprio 1
	s_add_i32 s18, s18, s45
	s_mov_b32 m0, s18
	ds_read_b128 v[178:181], v192 offset:49152
	ds_read_b128 v[182:185], v192 offset:50176
	ds_read_b128 v[194:197], v192 offset:51200
	ds_read_b128 v[198:201], v192 offset:52224
	ds_read_b128 v[202:205], v192 offset:53248
	ds_read_b128 v[206:209], v192 offset:54272
	ds_read_b128 v[210:213], v192 offset:55296
	ds_read_b128 v[214:217], v192 offset:56320
	global_load_lds_dwordx4 v156, s[76:77]
	s_add_i32 m0, s18, 0x2000
	s_add_u32 s24, s38, 0x160080
	s_addc_u32 s25, s39, 0
	s_add_i32 s18, s19, s45
	global_load_lds_dwordx4 v160, s[76:77]
	s_mov_b32 m0, s18
	s_nop 0
	global_load_lds_dwordx4 v156, s[24:25]
	s_add_i32 m0, s18, 0x2000
	s_nop 0
	global_load_lds_dwordx4 v160, s[24:25]
	s_mov_b32 m0, s52
	s_nop 0
	global_load_lds_dwordx4 v154, s[78:79]
	s_mov_b32 m0, s53
	s_nop 0
	global_load_lds_dwordx4 v158, s[78:79]
	s_waitcnt vmcnt(8)
	s_waitcnt lgkmcnt(0)
	s_barrier
	s_setprio 0
	v_mfma_f32_16x16x32_bf16 v[62:65], v[130:133], v[178:181], v[62:65]
	v_mfma_f32_16x16x32_bf16 v[58:61], v[138:141], v[178:181], v[58:61]
	v_mfma_f32_16x16x32_bf16 v[46:49], v[130:133], v[194:197], v[46:49]
	v_mfma_f32_16x16x32_bf16 v[42:45], v[138:141], v[194:197], v[42:45]
	v_mfma_f32_16x16x32_bf16 v[30:33], v[130:133], v[202:205], v[30:33]
	v_mfma_f32_16x16x32_bf16 v[26:29], v[138:141], v[202:205], v[26:29]
	v_mfma_f32_16x16x32_bf16 v[14:17], v[130:133], v[210:213], v[14:17]
	v_mfma_f32_16x16x32_bf16 v[10:13], v[138:141], v[210:213], v[10:13]
	v_mfma_f32_16x16x32_bf16 v[62:65], v[134:137], v[182:185], v[62:65]
	v_mfma_f32_16x16x32_bf16 v[58:61], v[142:145], v[182:185], v[58:61]
	v_mfma_f32_16x16x32_bf16 v[46:49], v[134:137], v[198:201], v[46:49]
	v_mfma_f32_16x16x32_bf16 v[42:45], v[142:145], v[198:201], v[42:45]
	v_mfma_f32_16x16x32_bf16 v[30:33], v[134:137], v[206:209], v[30:33]
	v_mfma_f32_16x16x32_bf16 v[26:29], v[142:145], v[206:209], v[26:29]
	v_mfma_f32_16x16x32_bf16 v[14:17], v[134:137], v[214:217], v[14:17]
	v_mfma_f32_16x16x32_bf16 v[10:13], v[142:145], v[214:217], v[10:13]
	v_mfma_f32_16x16x32_bf16 v[54:57], v[146:149], v[178:181], v[54:57]
	v_mfma_f32_16x16x32_bf16 v[50:53], v[170:173], v[178:181], v[50:53]
	v_mfma_f32_16x16x32_bf16 v[38:41], v[146:149], v[194:197], v[38:41]
	v_mfma_f32_16x16x32_bf16 v[34:37], v[170:173], v[194:197], v[34:37]
	v_mfma_f32_16x16x32_bf16 v[22:25], v[146:149], v[202:205], v[22:25]
	v_mfma_f32_16x16x32_bf16 v[18:21], v[170:173], v[202:205], v[18:21]
	v_mfma_f32_16x16x32_bf16 v[6:9], v[146:149], v[210:213], v[6:9]
	v_mfma_f32_16x16x32_bf16 v[2:5], v[170:173], v[210:213], v[2:5]
	v_mfma_f32_16x16x32_bf16 v[54:57], v[150:153], v[182:185], v[54:57]
	v_mfma_f32_16x16x32_bf16 v[50:53], v[174:177], v[182:185], v[50:53]
	v_mfma_f32_16x16x32_bf16 v[38:41], v[150:153], v[198:201], v[38:41]
	v_mfma_f32_16x16x32_bf16 v[34:37], v[174:177], v[198:201], v[34:37]
	v_mfma_f32_16x16x32_bf16 v[22:25], v[150:153], v[206:209], v[22:25]
	v_mfma_f32_16x16x32_bf16 v[18:21], v[174:177], v[206:209], v[18:21]
	v_mfma_f32_16x16x32_bf16 v[6:9], v[150:153], v[214:217], v[6:9]
	v_mfma_f32_16x16x32_bf16 v[2:5], v[174:177], v[214:217], v[2:5]
	s_barrier
	s_add_i32 s63, s63, 2
	s_add_u32 s61, s61, 0x100
	s_addc_u32 s62, s62, 0
	s_cmpk_gt_u32 s63, 0x55
	s_mov_b64 s[24:25], s[36:37]
; #define PG8_STAGE(bufoff, gbase, voff) do { _Pragma("unroll") for (int _i = 0; _i < 2; ++_i) \
;         __builtin_amdgcn_global_load_lds((const unsigned*)((const char*)(gbase) + (voff)[_i]), (PG8_LAS unsigned*)(lds + (bufoff) + ldsw + _i * 8192), 16, 0, 0); } while (0)
; #define PG8_LDA(dst, b, h) do { _Pragma("unroll") for (int m = 0; m < 4; ++m) _Pragma("unroll") for (int k = 0; k < 2; ++k) dst[m][k] = *(const PG8_LAS bf16x8*)(lds + PG8_SA(b, h) + aoff + m * 2048 + k * 1024); } while (0)
; #define PG8_LDB(dst, b, h) do { _Pragma("unroll") for (int n = 0; n < 2; ++n) _Pragma("unroll") for (int k = 0; k < 2; ++k) dst[n][k] = *(const PG8_LAS bf16x8*)(lds + PG8_SB(b, h) + boff + n * 2048 + k * 1024); } while (0)
; #define PG8_MMA(ai, bj, At, Bt) do { __builtin_amdgcn_s_setprio(1); _Pragma("unroll") for (int m = 0; m < 4; ++m) _Pragma("unroll") for (int n = 0; n < 2; ++n) _Pragma("unroll") for (int k = 0; k < 2; ++k) \
;         acc[ai][bj][m][n] = __builtin_amdgcn_mfma_f32_16x16x32_bf16(Bt[n][k], At[m][k], acc[ai][bj][m][n], 0, 0, 0); __builtin_amdgcn_s_setprio(0); } while (0)
; #define PG8_WAIT_V(n) asm volatile("s_waitcnt vmcnt(" #n ")" ::: "memory")
; #define PG8_WAIT_L(n) asm volatile("s_waitcnt lgkmcnt(" #n ")" ::: "memory")
; #define PG8_BAR __builtin_amdgcn_s_barrier()
; #define PG8_SCHED __builtin_amdgcn_sched_barrier(0)
; template <class Epi, class Sched, bool ALIGN_EPI = false, bool SP2 = false>
; __device__ __forceinline__ void gemm_phase(PG8_LAS unsigned char* lds, const Gemm g, const Sched& S, const Epi& E) {
;     ...
;             PG8_LDB(B0, 0, 0); PG8_LDB(B1, 0, 1); PG8_SCHED; PG8_LDA(At, 0, 0); PG8_STAGE(PG8_SA(1, 1), a1 + hA, voffA);
;             PG8_WAIT_V(8); PG8_WAIT_L(0); PG8_BAR; PG8_MMA(0, 0, At, B0); PG8_MMA(0, 1, At, B1); PG8_BAR; PG8_SCHED;
;             PG8_LDA(At, 0, 1); PG8_STAGE(PG8_SB(0, 0), b2, voffB); PG8_STAGE(PG8_SB(0, 1), b2 + hB, voffB); PG8_STAGE(PG8_SA(0, 0), a2, voffA);
;             PG8_WAIT_V(8); PG8_WAIT_L(0); PG8_BAR; PG8_MMA(1, 0, At, B0); PG8_MMA(1, 1, At, B1); PG8_BAR; PG8_SCHED;
.LBB0_1127:
	s_setprio 1
	ds_read_b128 v[130:133], v190
	ds_read_b128 v[134:137], v190 offset:1024
	ds_read_b128 v[138:141], v190 offset:2048
	ds_read_b128 v[142:145], v190 offset:3072
	ds_read_b128 v[146:149], v191
	ds_read_b128 v[150:153], v191 offset:1024
	ds_read_b128 v[170:173], v191 offset:2048
	ds_read_b128 v[174:177], v191 offset:3072
	s_add_u32 s36, s24, 0x100
	s_addc_u32 s37, s25, 0
	s_cmpk_eq_i32 s63, 0x54
	s_cselect_b32 s41, s9, s37
	s_cselect_b32 s40, s8, s36
	s_cselect_b32 s39, s23, s62
	s_cselect_b32 s38, s22, s61
	s_add_i32 m0, s46, 0xc000
	ds_read_b128 v[178:181], v192
	ds_read_b128 v[182:185], v192 offset:1024
	ds_read_b128 v[194:197], v192 offset:2048
	ds_read_b128 v[198:201], v192 offset:3072
	ds_read_b128 v[202:205], v192 offset:4096
	ds_read_b128 v[206:209], v192 offset:5120
	ds_read_b128 v[210:213], v192 offset:6144
	ds_read_b128 v[214:217], v192 offset:7168
	global_load_lds_dwordx4 v162, s[24:25]
	s_add_i32 m0, s46, 0xe000
	s_nop 0
	global_load_lds_dwordx4 v164, s[24:25]
	s_waitcnt vmcnt(8)
	s_waitcnt lgkmcnt(0)
	s_barrier
	s_setprio 0
	v_mfma_f32_16x16x32_bf16 v[126:129], v[130:133], v[178:181], v[126:129]
	v_mfma_f32_16x16x32_bf16 v[122:125], v[138:141], v[178:181], v[122:125]
	v_mfma_f32_16x16x32_bf16 v[110:113], v[130:133], v[194:197], v[110:113]
	v_mfma_f32_16x16x32_bf16 v[106:109], v[138:141], v[194:197], v[106:109]
	v_mfma_f32_16x16x32_bf16 v[94:97], v[130:133], v[202:205], v[94:97]
	v_mfma_f32_16x16x32_bf16 v[90:93], v[138:141], v[202:205], v[90:93]
	v_mfma_f32_16x16x32_bf16 v[78:81], v[130:133], v[210:213], v[78:81]
	v_mfma_f32_16x16x32_bf16 v[74:77], v[138:141], v[210:213], v[74:77]
	v_mfma_f32_16x16x32_bf16 v[126:129], v[134:137], v[182:185], v[126:129]
	v_mfma_f32_16x16x32_bf16 v[122:125], v[142:145], v[182:185], v[122:125]
	v_mfma_f32_16x16x32_bf16 v[110:113], v[134:137], v[198:201], v[110:113]
	v_mfma_f32_16x16x32_bf16 v[106:109], v[142:145], v[198:201], v[106:109]
	v_mfma_f32_16x16x32_bf16 v[94:97], v[134:137], v[206:209], v[94:97]
	v_mfma_f32_16x16x32_bf16 v[90:93], v[142:145], v[206:209], v[90:93]
	v_mfma_f32_16x16x32_bf16 v[78:81], v[134:137], v[214:217], v[78:81]
	v_mfma_f32_16x16x32_bf16 v[74:77], v[142:145], v[214:217], v[74:77]
	v_mfma_f32_16x16x32_bf16 v[118:121], v[146:149], v[178:181], v[118:121]
	v_mfma_f32_16x16x32_bf16 v[114:117], v[170:173], v[178:181], v[114:117]
	v_mfma_f32_16x16x32_bf16 v[102:105], v[146:149], v[194:197], v[102:105]
	v_mfma_f32_16x16x32_bf16 v[98:101], v[170:173], v[194:197], v[98:101]
	v_mfma_f32_16x16x32_bf16 v[86:89], v[146:149], v[202:205], v[86:89]
	v_mfma_f32_16x16x32_bf16 v[82:85], v[170:173], v[202:205], v[82:85]
	v_mfma_f32_16x16x32_bf16 v[70:73], v[146:149], v[210:213], v[70:73]
	v_mfma_f32_16x16x32_bf16 v[66:69], v[170:173], v[210:213], v[66:69]
	v_mfma_f32_16x16x32_bf16 v[118:121], v[150:153], v[182:185], v[118:121]
	v_mfma_f32_16x16x32_bf16 v[114:117], v[174:177], v[182:185], v[114:117]
	v_mfma_f32_16x16x32_bf16 v[102:105], v[150:153], v[198:201], v[102:105]
	v_mfma_f32_16x16x32_bf16 v[98:101], v[174:177], v[198:201], v[98:101]
	v_mfma_f32_16x16x32_bf16 v[86:89], v[150:153], v[206:209], v[86:89]
	v_mfma_f32_16x16x32_bf16 v[82:85], v[174:177], v[206:209], v[82:85]
	v_mfma_f32_16x16x32_bf16 v[70:73], v[150:153], v[214:217], v[70:73]
	v_mfma_f32_16x16x32_bf16 v[66:69], v[174:177], v[214:217], v[66:69]
	s_barrier
	s_setprio 1
	s_add_i32 s18, s55, s45
	s_add_u32 s76, s38, s16
	s_addc_u32 s77, s39, s17
	s_mov_b32 m0, s18
	ds_read_b128 v[178:181], v192 offset:16384
	ds_read_b128 v[182:185], v192 offset:17408
	ds_read_b128 v[194:197], v192 offset:18432
	ds_read_b128 v[198:201], v192 offset:19456
	ds_read_b128 v[202:205], v192 offset:20480
	ds_read_b128 v[206:209], v192 offset:21504
	ds_read_b128 v[210:213], v192 offset:22528
	ds_read_b128 v[214:217], v192 offset:23552
	global_load_lds_dwordx4 v156, s[38:39]
	s_add_i32 m0, s18, 0x2000
	s_add_u32 s24, s38, 0x160000
	s_addc_u32 s25, s39, 0
	s_add_i32 s18, s56, s45
	global_load_lds_dwordx4 v160, s[38:39]
	s_mov_b32 m0, s18
	s_nop 0
	global_load_lds_dwordx4 v156, s[24:25]
	s_add_i32 m0, s18, 0x2000
	s_nop 0
	global_load_lds_dwordx4 v160, s[24:25]
	s_add_u32 s78, s40, s16
	s_addc_u32 s79, s41, s17
	s_mov_b32 m0, s46
	s_nop 0
	global_load_lds_dwordx4 v154, s[40:41]
	s_mov_b32 m0, s47
	s_nop 0
	global_load_lds_dwordx4 v158, s[40:41]
	s_waitcnt vmcnt(8)
	s_waitcnt lgkmcnt(0)
	s_barrier
	s_setprio 0
	v_mfma_f32_16x16x32_bf16 v[62:65], v[130:133], v[178:181], v[62:65]
	v_mfma_f32_16x16x32_bf16 v[58:61], v[138:141], v[178:181], v[58:61]
	v_mfma_f32_16x16x32_bf16 v[46:49], v[130:133], v[194:197], v[46:49]
	v_mfma_f32_16x16x32_bf16 v[42:45], v[138:141], v[194:197], v[42:45]
	v_mfma_f32_16x16x32_bf16 v[30:33], v[130:133], v[202:205], v[30:33]
	v_mfma_f32_16x16x32_bf16 v[26:29], v[138:141], v[202:205], v[26:29]
	v_mfma_f32_16x16x32_bf16 v[14:17], v[130:133], v[210:213], v[14:17]
	v_mfma_f32_16x16x32_bf16 v[10:13], v[138:141], v[210:213], v[10:13]
	v_mfma_f32_16x16x32_bf16 v[62:65], v[134:137], v[182:185], v[62:65]
	v_mfma_f32_16x16x32_bf16 v[58:61], v[142:145], v[182:185], v[58:61]
	v_mfma_f32_16x16x32_bf16 v[46:49], v[134:137], v[198:201], v[46:49]
	v_mfma_f32_16x16x32_bf16 v[42:45], v[142:145], v[198:201], v[42:45]
	v_mfma_f32_16x16x32_bf16 v[30:33], v[134:137], v[206:209], v[30:33]
	v_mfma_f32_16x16x32_bf16 v[26:29], v[142:145], v[206:209], v[26:29]
	v_mfma_f32_16x16x32_bf16 v[14:17], v[134:137], v[214:217], v[14:17]
	v_mfma_f32_16x16x32_bf16 v[10:13], v[142:145], v[214:217], v[10:13]
	v_mfma_f32_16x16x32_bf16 v[54:57], v[146:149], v[178:181], v[54:57]
	v_mfma_f32_16x16x32_bf16 v[50:53], v[170:173], v[178:181], v[50:53]
	v_mfma_f32_16x16x32_bf16 v[38:41], v[146:149], v[194:197], v[38:41]
	v_mfma_f32_16x16x32_bf16 v[34:37], v[170:173], v[194:197], v[34:37]
	v_mfma_f32_16x16x32_bf16 v[22:25], v[146:149], v[202:205], v[22:25]
	v_mfma_f32_16x16x32_bf16 v[18:21], v[170:173], v[202:205], v[18:21]
	v_mfma_f32_16x16x32_bf16 v[6:9], v[146:149], v[210:213], v[6:9]
	v_mfma_f32_16x16x32_bf16 v[2:5], v[170:173], v[210:213], v[2:5]
	v_mfma_f32_16x16x32_bf16 v[54:57], v[150:153], v[182:185], v[54:57]
	v_mfma_f32_16x16x32_bf16 v[50:53], v[174:177], v[182:185], v[50:53]
	v_mfma_f32_16x16x32_bf16 v[38:41], v[150:153], v[198:201], v[38:41]
	v_mfma_f32_16x16x32_bf16 v[34:37], v[174:177], v[198:201], v[34:37]
	v_mfma_f32_16x16x32_bf16 v[22:25], v[150:153], v[206:209], v[22:25]
	v_mfma_f32_16x16x32_bf16 v[18:21], v[174:177], v[206:209], v[18:21]
	v_mfma_f32_16x16x32_bf16 v[6:9], v[150:153], v[214:217], v[6:9]
	v_mfma_f32_16x16x32_bf16 v[2:5], v[174:177], v[214:217], v[2:5]
	s_barrier
; #define PG8_STAGE(bufoff, gbase, voff) do { _Pragma("unroll") for (int _i = 0; _i < 2; ++_i) \
;         __builtin_amdgcn_global_load_lds((const unsigned*)((const char*)(gbase) + (voff)[_i]), (PG8_LAS unsigned*)(lds + (bufoff) + ldsw + _i * 8192), 16, 0, 0); } while (0)
; #define PG8_LDA(dst, b, h) do { _Pragma("unroll") for (int m = 0; m < 4; ++m) _Pragma("unroll") for (int k = 0; k < 2; ++k) dst[m][k] = *(const PG8_LAS bf16x8*)(lds + PG8_SA(b, h) + aoff + m * 2048 + k * 1024); } while (0)
; #define PG8_LDB(dst, b, h) do { _Pragma("unroll") for (int n = 0; n < 2; ++n) _Pragma("unroll") for (int k = 0; k < 2; ++k) dst[n][k] = *(const PG8_LAS bf16x8*)(lds + PG8_SB(b, h) + boff + n * 2048 + k * 1024); } while (0)
; #define PG8_MMA(ai, bj, At, Bt) do { __builtin_amdgcn_s_setprio(1); _Pragma("unroll") for (int m = 0; m < 4; ++m) _Pragma("unroll") for (int n = 0; n < 2; ++n) _Pragma("unroll") for (int k = 0; k < 2; ++k) \
;         acc[ai][bj][m][n] = __builtin_amdgcn_mfma_f32_16x16x32_bf16(Bt[n][k], At[m][k], acc[ai][bj][m][n], 0, 0, 0); __builtin_amdgcn_s_setprio(0); } while (0)
; #define PG8_WAIT_V(n) asm volatile("s_waitcnt vmcnt(" #n ")" ::: "memory")
; #define PG8_WAIT_L(n) asm volatile("s_waitcnt lgkmcnt(" #n ")" ::: "memory")
; #define PG8_BAR __builtin_amdgcn_s_barrier()
; #define PG8_SCHED __builtin_amdgcn_sched_barrier(0)
; template <class Epi, class Sched, bool ALIGN_EPI = false, bool SP2 = false>
; __device__ __forceinline__ void gemm_phase(PG8_LAS unsigned char* lds, const Gemm g, const Sched& S, const Epi& E) {
;     ...
;         for (int t = 0; t < nt; t += 2) {
;     ...
;             PG8_LDB(B0, 1, 0); PG8_LDB(B1, 1, 1); PG8_SCHED; PG8_LDA(At, 1, 0); PG8_STAGE(PG8_SA(0, 1), a2 + hA, voffA);
;             PG8_WAIT_V(8); PG8_WAIT_L(0); PG8_BAR; PG8_MMA(0, 0, At, B0); PG8_MMA(0, 1, At, B1); PG8_BAR; PG8_SCHED;
;             PG8_LDA(At, 1, 1); PG8_STAGE(PG8_SB(1, 0), b3, voffB); PG8_STAGE(PG8_SB(1, 1), b3 + hB, voffB); PG8_STAGE(PG8_SA(1, 0), a3, voffA);
;             PG8_WAIT_V(8); PG8_WAIT_L(0); PG8_BAR; PG8_MMA(1, 0, At, B0); PG8_MMA(1, 1, At, B1); PG8_BAR; PG8_SCHED;
	s_setprio 1
	s_add_i32 s18, 0, 0x18000
	s_add_i32 s19, 0, 0x1c000
	v_add_u32_e32 v142, s18, v188
	v_add_u32_e32 v174, s19, v188
	ds_read_b128 v[130:133], v142
	ds_read_b128 v[134:137], v142 offset:1024
	ds_read_b128 v[138:141], v142 offset:2048
	ds_read_b128 v[142:145], v142 offset:3072
	ds_read_b128 v[146:149], v174
	ds_read_b128 v[150:153], v174 offset:1024
	ds_read_b128 v[170:173], v174 offset:2048
	ds_read_b128 v[174:177], v174 offset:3072
	s_add_u32 s24, s40, 0x160000
	s_addc_u32 s25, s41, 0
	s_mov_b32 m0, s48
	ds_read_b128 v[178:181], v192 offset:32768
	ds_read_b128 v[182:185], v192 offset:33792
	ds_read_b128 v[194:197], v192 offset:34816
	ds_read_b128 v[198:201], v192 offset:35840
	ds_read_b128 v[202:205], v192 offset:36864
	ds_read_b128 v[206:209], v192 offset:37888
	ds_read_b128 v[210:213], v192 offset:38912
	ds_read_b128 v[214:217], v192 offset:39936
	global_load_lds_dwordx4 v154, s[24:25]
	s_mov_b32 m0, s49
	s_nop 0
	global_load_lds_dwordx4 v158, s[24:25]
	s_waitcnt vmcnt(8)
	s_waitcnt lgkmcnt(0)
	s_barrier
	s_setprio 0
	v_mfma_f32_16x16x32_bf16 v[126:129], v[130:133], v[178:181], v[126:129]
	v_mfma_f32_16x16x32_bf16 v[122:125], v[138:141], v[178:181], v[122:125]
	v_mfma_f32_16x16x32_bf16 v[110:113], v[130:133], v[194:197], v[110:113]
	v_mfma_f32_16x16x32_bf16 v[106:109], v[138:141], v[194:197], v[106:109]
	v_mfma_f32_16x16x32_bf16 v[94:97], v[130:133], v[202:205], v[94:97]
	v_mfma_f32_16x16x32_bf16 v[90:93], v[138:141], v[202:205], v[90:93]
	v_mfma_f32_16x16x32_bf16 v[78:81], v[130:133], v[210:213], v[78:81]
	v_mfma_f32_16x16x32_bf16 v[74:77], v[138:141], v[210:213], v[74:77]
	v_mfma_f32_16x16x32_bf16 v[126:129], v[134:137], v[182:185], v[126:129]
	v_mfma_f32_16x16x32_bf16 v[122:125], v[142:145], v[182:185], v[122:125]
	v_mfma_f32_16x16x32_bf16 v[110:113], v[134:137], v[198:201], v[110:113]
	v_mfma_f32_16x16x32_bf16 v[106:109], v[142:145], v[198:201], v[106:109]
	v_mfma_f32_16x16x32_bf16 v[94:97], v[134:137], v[206:209], v[94:97]
	v_mfma_f32_16x16x32_bf16 v[90:93], v[142:145], v[206:209], v[90:93]
	v_mfma_f32_16x16x32_bf16 v[78:81], v[134:137], v[214:217], v[78:81]
	v_mfma_f32_16x16x32_bf16 v[74:77], v[142:145], v[214:217], v[74:77]
	v_mfma_f32_16x16x32_bf16 v[118:121], v[146:149], v[178:181], v[118:121]
	v_mfma_f32_16x16x32_bf16 v[114:117], v[170:173], v[178:181], v[114:117]
	v_mfma_f32_16x16x32_bf16 v[102:105], v[146:149], v[194:197], v[102:105]
	v_mfma_f32_16x16x32_bf16 v[98:101], v[170:173], v[194:197], v[98:101]
	v_mfma_f32_16x16x32_bf16 v[86:89], v[146:149], v[202:205], v[86:89]
	v_mfma_f32_16x16x32_bf16 v[82:85], v[170:173], v[202:205], v[82:85]
	v_mfma_f32_16x16x32_bf16 v[70:73], v[146:149], v[210:213], v[70:73]
	v_mfma_f32_16x16x32_bf16 v[66:69], v[170:173], v[210:213], v[66:69]
	v_mfma_f32_16x16x32_bf16 v[118:121], v[150:153], v[182:185], v[118:121]
	v_mfma_f32_16x16x32_bf16 v[114:117], v[174:177], v[182:185], v[114:117]
	v_mfma_f32_16x16x32_bf16 v[102:105], v[150:153], v[198:201], v[102:105]
	v_mfma_f32_16x16x32_bf16 v[98:101], v[174:177], v[198:201], v[98:101]
	v_mfma_f32_16x16x32_bf16 v[86:89], v[150:153], v[206:209], v[86:89]
	v_mfma_f32_16x16x32_bf16 v[82:85], v[174:177], v[206:209], v[82:85]
	v_mfma_f32_16x16x32_bf16 v[70:73], v[150:153], v[214:217], v[70:73]
	v_mfma_f32_16x16x32_bf16 v[66:69], v[174:177], v[214:217], v[66:69]
	s_barrier
	s_setprio 1
	s_add_i32 s18, s18, s45
	s_mov_b32 m0, s18
	ds_read_b128 v[178:181], v192 offset:49152
	ds_read_b128 v[182:185], v192 offset:50176
	ds_read_b128 v[194:197], v192 offset:51200
	ds_read_b128 v[198:201], v192 offset:52224
	ds_read_b128 v[202:205], v192 offset:53248
	ds_read_b128 v[206:209], v192 offset:54272
	ds_read_b128 v[210:213], v192 offset:55296
	ds_read_b128 v[214:217], v192 offset:56320
	global_load_lds_dwordx4 v156, s[76:77]
	s_add_i32 m0, s18, 0x2000
	s_add_u32 s24, s38, 0x160080
	s_addc_u32 s25, s39, 0
	s_add_i32 s18, s19, s45
	global_load_lds_dwordx4 v160, s[76:77]
	s_mov_b32 m0, s18
	s_nop 0
	global_load_lds_dwordx4 v156, s[24:25]
	s_add_i32 m0, s18, 0x2000
	s_nop 0
	global_load_lds_dwordx4 v160, s[24:25]
	s_mov_b32 m0, s52
	s_nop 0
	global_load_lds_dwordx4 v154, s[78:79]
	s_mov_b32 m0, s53
	s_nop 0
	global_load_lds_dwordx4 v158, s[78:79]
	s_waitcnt vmcnt(8)
	s_waitcnt lgkmcnt(0)
	s_barrier
	s_setprio 0
	v_mfma_f32_16x16x32_bf16 v[62:65], v[130:133], v[178:181], v[62:65]
	v_mfma_f32_16x16x32_bf16 v[58:61], v[138:141], v[178:181], v[58:61]
	v_mfma_f32_16x16x32_bf16 v[46:49], v[130:133], v[194:197], v[46:49]
	v_mfma_f32_16x16x32_bf16 v[42:45], v[138:141], v[194:197], v[42:45]
	v_mfma_f32_16x16x32_bf16 v[30:33], v[130:133], v[202:205], v[30:33]
	v_mfma_f32_16x16x32_bf16 v[26:29], v[138:141], v[202:205], v[26:29]
	v_mfma_f32_16x16x32_bf16 v[14:17], v[130:133], v[210:213], v[14:17]
	v_mfma_f32_16x16x32_bf16 v[10:13], v[138:141], v[210:213], v[10:13]
	v_mfma_f32_16x16x32_bf16 v[62:65], v[134:137], v[182:185], v[62:65]
	v_mfma_f32_16x16x32_bf16 v[58:61], v[142:145], v[182:185], v[58:61]
	v_mfma_f32_16x16x32_bf16 v[46:49], v[134:137], v[198:201], v[46:49]
	v_mfma_f32_16x16x32_bf16 v[42:45], v[142:145], v[198:201], v[42:45]
	v_mfma_f32_16x16x32_bf16 v[30:33], v[134:137], v[206:209], v[30:33]
	v_mfma_f32_16x16x32_bf16 v[26:29], v[142:145], v[206:209], v[26:29]
	v_mfma_f32_16x16x32_bf16 v[14:17], v[134:137], v[214:217], v[14:17]
	v_mfma_f32_16x16x32_bf16 v[10:13], v[142:145], v[214:217], v[10:13]
	v_mfma_f32_16x16x32_bf16 v[54:57], v[146:149], v[178:181], v[54:57]
	v_mfma_f32_16x16x32_bf16 v[50:53], v[170:173], v[178:181], v[50:53]
	v_mfma_f32_16x16x32_bf16 v[38:41], v[146:149], v[194:197], v[38:41]
	v_mfma_f32_16x16x32_bf16 v[34:37], v[170:173], v[194:197], v[34:37]
	v_mfma_f32_16x16x32_bf16 v[22:25], v[146:149], v[202:205], v[22:25]
	v_mfma_f32_16x16x32_bf16 v[18:21], v[170:173], v[202:205], v[18:21]
	v_mfma_f32_16x16x32_bf16 v[6:9], v[146:149], v[210:213], v[6:9]
	v_mfma_f32_16x16x32_bf16 v[2:5], v[170:173], v[210:213], v[2:5]
	v_mfma_f32_16x16x32_bf16 v[54:57], v[150:153], v[182:185], v[54:57]
	v_mfma_f32_16x16x32_bf16 v[50:53], v[174:177], v[182:185], v[50:53]
	v_mfma_f32_16x16x32_bf16 v[38:41], v[150:153], v[198:201], v[38:41]
	v_mfma_f32_16x16x32_bf16 v[34:37], v[174:177], v[198:201], v[34:37]
	v_mfma_f32_16x16x32_bf16 v[22:25], v[150:153], v[206:209], v[22:25]
	v_mfma_f32_16x16x32_bf16 v[18:21], v[174:177], v[206:209], v[18:21]
	v_mfma_f32_16x16x32_bf16 v[6:9], v[150:153], v[214:217], v[6:9]
	v_mfma_f32_16x16x32_bf16 v[2:5], v[174:177], v[214:217], v[2:5]
	s_barrier
	s_add_i32 s63, s63, 2
	s_add_u32 s61, s61, 0x100
	s_addc_u32 s62, s62, 0
	s_cmpk_gt_u32 s63, 0x55
	s_mov_b64 s[24:25], s[36:37]
	s_cbranch_scc0 .LBB0_1127
	s_and_b64 vcc, exec, s[20:21]
	s_cbranch_vccz .LBB0_1130
	s_barrier
